# the vmcnt and lgkmcnt waits that close each GEMM load segment merged into one s_waitcnt
# baseline (speedup 1.0000x reference)
; #define PG8_STAGE(bufoff, gbase, voff) do { _Pragma("unroll") for (int _i = 0; _i < 2; ++_i) \
;         __builtin_amdgcn_global_load_lds((const unsigned*)((const char*)(gbase) + (voff)[_i]), (PG8_LAS unsigned*)(lds + (bufoff) + ldsw + _i * 8192), 16, 0, 0); } while (0)
; #define PG8_LDA(dst, b, h) do { _Pragma("unroll") for (int m = 0; m < 4; ++m) _Pragma("unroll") for (int k = 0; k < 2; ++k) dst[m][k] = *(const PG8_LAS bf16x8*)(lds + PG8_SA(b, h) + aoff + m * 2048 + k * 1024); } while (0)
; #define PG8_LDB(dst, b, h) do { _Pragma("unroll") for (int n = 0; n < 2; ++n) _Pragma("unroll") for (int k = 0; k < 2; ++k) dst[n][k] = *(const PG8_LAS bf16x8*)(lds + PG8_SB(b, h) + boff + n * 2048 + k * 1024); } while (0)
; #define PG8_MMA(ai, bj, At, Bt) do { __builtin_amdgcn_s_setprio(1); _Pragma("unroll") for (int m = 0; m < 4; ++m) _Pragma("unroll") for (int n = 0; n < 2; ++n) _Pragma("unroll") for (int k = 0; k < 2; ++k) \
;         acc[ai][bj][m][n] = __builtin_amdgcn_mfma_f32_16x16x32_bf16(Bt[n][k], At[m][k], acc[ai][bj][m][n], 0, 0, 0); __builtin_amdgcn_s_setprio(0); } while (0)
; #define PG8_BAR __builtin_amdgcn_s_barrier()
; template <class Epi, class Sched, bool ALIGN_EPI = false, bool SP2 = false>
; __device__ __forceinline__ void gemm_phase(PG8_LAS unsigned char* lds, const Gemm g, const Sched& S, const Epi& E) {
;     ...
;         for (int t = 0; t < nt; t += 2) {
;             const bool last = (t == nt - 2);
;             if constexpr (Epi::HAS_MID) { if (t == E.mid_t) E.mid(acc, cur, wr, wc, fr, fq); }
;             const char* a1 = cA + (size_t)(t + 1) * kstep;
;             const char* a2 = last ? nA : cA + (size_t)(t + 2) * kstep; const char* b2 = last ? nB : cB + (size_t)(t + 2) * kstep;
;             const char* a3 = a2 + kstep; const char* b3 = b2 + kstep;
;             if (last && has_next) S.a_ready(nxt);
;             if constexpr (SP2) {
;             PG8_LDB(B0, 0, 0); PG8_LDB(B1, 0, 1); PG8_SCHED; PG8_LDA(At, 0, 0); PG8_STAGE(PG8_SA(1, 1), a1 + hstepA, voffA);
;             PG8_WAIT_V(8); PG8_WAIT_L(0); PG8_BAR; PG8_MMA(0, 0, At, B0); PG8_MMA(0, 1, At, B1); PG8_BAR; PG8_SCHED;
;             PG8_LDA(At, 0, 1); PG8_STAGE(PG8_SB(0, 0), b2, voffB); PG8_STAGE(PG8_SB(0, 1), b2 + hstepB, voffB); PG8_STAGE(PG8_SA(0, 0), a2, voffA);
;             PG8_WAIT_V(8); PG8_WAIT_L(0); PG8_BAR; PG8_MMA(1, 0, At, B0); PG8_MMA(1, 1, At, B1); PG8_BAR; PG8_SCHED;
.LBB0_187:
	ds_read_b128 v[128:131], v173
	ds_read_b128 v[132:135], v173 offset:1024
	ds_read_b128 v[152:155], v173 offset:2048
	ds_read_b128 v[156:159], v173 offset:3072
	ds_read_b128 v[160:163], v174
	ds_read_b128 v[164:167], v174 offset:1024
	ds_read_b128 v[180:183], v174 offset:2048
	ds_read_b128 v[184:187], v174 offset:3072
	s_add_u32 s16, s12, 0xfff80080
	s_addc_u32 s17, s13, -1
	s_cmp_eq_u32 s61, 28
	s_cselect_b32 s19, s1, s17
	s_cselect_b32 s18, s26, s16
	s_cselect_b32 s17, s15, s60
	s_cselect_b32 s16, s36, s37
	ds_read_b128 v[188:191], v175
	ds_read_b128 v[192:195], v175 offset:1024
	ds_read_b128 v[196:199], v175 offset:2048
	ds_read_b128 v[200:203], v175 offset:3072
	ds_read_b128 v[204:207], v175 offset:4096
	ds_read_b128 v[208:211], v175 offset:5120
	ds_read_b128 v[212:215], v175 offset:6144
	ds_read_b128 v[216:219], v175 offset:7168
	s_add_u32 s98, s12, 0xfff80000
	s_addc_u32 s99, s13, -1
	s_mov_b32 m0, s7
	s_nop 0
	global_load_lds_dwordx4 v136, s[98:99]
	s_mov_b32 m0, s46
	s_nop 0
	global_load_lds_dwordx4 v140, s[98:99]
	s_add_i32 m0, s77, 0xc000
	s_nop 0
	global_load_lds_dwordx4 v144, s[12:13]
	s_add_i32 m0, s77, 0xe000
	s_nop 0
	global_load_lds_dwordx4 v146, s[12:13]
	s_waitcnt vmcnt(8) lgkmcnt(0)
	s_barrier
	s_setprio 1
	v_mfma_f32_16x16x32_bf16 v[124:127], v[128:131], v[188:191], v[124:127]
	v_mfma_f32_16x16x32_bf16 v[120:123], v[152:155], v[188:191], v[120:123]
	v_mfma_f32_16x16x32_bf16 v[108:111], v[128:131], v[196:199], v[108:111]
	v_mfma_f32_16x16x32_bf16 v[104:107], v[152:155], v[196:199], v[104:107]
	v_mfma_f32_16x16x32_bf16 v[92:95], v[128:131], v[204:207], v[92:95]
	v_mfma_f32_16x16x32_bf16 v[88:91], v[152:155], v[204:207], v[88:91]
	v_mfma_f32_16x16x32_bf16 v[76:79], v[128:131], v[212:215], v[76:79]
	v_mfma_f32_16x16x32_bf16 v[72:75], v[152:155], v[212:215], v[72:75]
	v_mfma_f32_16x16x32_bf16 v[124:127], v[132:135], v[192:195], v[124:127]
	v_mfma_f32_16x16x32_bf16 v[120:123], v[156:159], v[192:195], v[120:123]
	v_mfma_f32_16x16x32_bf16 v[108:111], v[132:135], v[200:203], v[108:111]
	v_mfma_f32_16x16x32_bf16 v[104:107], v[156:159], v[200:203], v[104:107]
	v_mfma_f32_16x16x32_bf16 v[92:95], v[132:135], v[208:211], v[92:95]
	v_mfma_f32_16x16x32_bf16 v[88:91], v[156:159], v[208:211], v[88:91]
	v_mfma_f32_16x16x32_bf16 v[76:79], v[132:135], v[216:219], v[76:79]
	v_mfma_f32_16x16x32_bf16 v[72:75], v[156:159], v[216:219], v[72:75]
	s_setprio 0
	s_setprio 1
	v_mfma_f32_16x16x32_bf16 v[116:119], v[160:163], v[188:191], v[116:119]
	v_mfma_f32_16x16x32_bf16 v[112:115], v[180:183], v[188:191], v[112:115]
	v_mfma_f32_16x16x32_bf16 v[100:103], v[160:163], v[196:199], v[100:103]
	v_mfma_f32_16x16x32_bf16 v[96:99], v[180:183], v[196:199], v[96:99]
	v_mfma_f32_16x16x32_bf16 v[84:87], v[160:163], v[204:207], v[84:87]
	v_mfma_f32_16x16x32_bf16 v[80:83], v[180:183], v[204:207], v[80:83]
	v_mfma_f32_16x16x32_bf16 v[68:71], v[160:163], v[212:215], v[68:71]
	v_mfma_f32_16x16x32_bf16 v[64:67], v[180:183], v[212:215], v[64:67]
	v_mfma_f32_16x16x32_bf16 v[116:119], v[164:167], v[192:195], v[116:119]
	v_mfma_f32_16x16x32_bf16 v[112:115], v[184:187], v[192:195], v[112:115]
	v_mfma_f32_16x16x32_bf16 v[100:103], v[164:167], v[200:203], v[100:103]
	v_mfma_f32_16x16x32_bf16 v[96:99], v[184:187], v[200:203], v[96:99]
	v_mfma_f32_16x16x32_bf16 v[84:87], v[164:167], v[208:211], v[84:87]
	v_mfma_f32_16x16x32_bf16 v[80:83], v[184:187], v[208:211], v[80:83]
	v_mfma_f32_16x16x32_bf16 v[68:71], v[164:167], v[216:219], v[68:71]
	v_mfma_f32_16x16x32_bf16 v[64:67], v[184:187], v[216:219], v[64:67]
	s_setprio 0
	s_barrier
	s_add_i32 s69, s47, s33
	s_mov_b32 m0, s69
	ds_read_b128 v[188:191], v175 offset:16384
	ds_read_b128 v[192:195], v175 offset:17408
	ds_read_b128 v[196:199], v175 offset:18432
	ds_read_b128 v[200:203], v175 offset:19456
	ds_read_b128 v[204:207], v175 offset:20480
	ds_read_b128 v[208:211], v175 offset:21504
	ds_read_b128 v[212:215], v175 offset:22528
	ds_read_b128 v[216:219], v175 offset:23552
	global_load_lds_dwordx4 v138, s[16:17]
	s_add_i32 m0, s69, 0x2000
	s_add_u32 s70, s16, 0x80000
	s_addc_u32 s71, s17, 0
	s_add_i32 s69, s56, s33
	global_load_lds_dwordx4 v142, s[16:17]
	s_mov_b32 m0, s69
	s_nop 0
	global_load_lds_dwordx4 v138, s[70:71]
	s_add_i32 m0, s69, 0x2000
	s_nop 0
	global_load_lds_dwordx4 v142, s[70:71]
	s_waitcnt vmcnt(6) lgkmcnt(0)
	s_barrier
	s_setprio 1
	v_mfma_f32_16x16x32_bf16 v[60:63], v[128:131], v[188:191], v[60:63]
	v_mfma_f32_16x16x32_bf16 v[56:59], v[152:155], v[188:191], v[56:59]
	v_mfma_f32_16x16x32_bf16 v[44:47], v[128:131], v[196:199], v[44:47]
	v_mfma_f32_16x16x32_bf16 v[40:43], v[152:155], v[196:199], v[40:43]
	v_mfma_f32_16x16x32_bf16 v[28:31], v[128:131], v[204:207], v[28:31]
	v_mfma_f32_16x16x32_bf16 v[24:27], v[152:155], v[204:207], v[24:27]
	v_mfma_f32_16x16x32_bf16 v[12:15], v[128:131], v[212:215], v[12:15]
	v_mfma_f32_16x16x32_bf16 v[8:11], v[152:155], v[212:215], v[8:11]
	v_mfma_f32_16x16x32_bf16 v[60:63], v[132:135], v[192:195], v[60:63]
	v_mfma_f32_16x16x32_bf16 v[56:59], v[156:159], v[192:195], v[56:59]
	v_mfma_f32_16x16x32_bf16 v[44:47], v[132:135], v[200:203], v[44:47]
	v_mfma_f32_16x16x32_bf16 v[40:43], v[156:159], v[200:203], v[40:43]
	v_mfma_f32_16x16x32_bf16 v[28:31], v[132:135], v[208:211], v[28:31]
	v_mfma_f32_16x16x32_bf16 v[24:27], v[156:159], v[208:211], v[24:27]
	v_mfma_f32_16x16x32_bf16 v[12:15], v[132:135], v[216:219], v[12:15]
	v_mfma_f32_16x16x32_bf16 v[8:11], v[156:159], v[216:219], v[8:11]
	s_setprio 0
	s_setprio 1
	v_mfma_f32_16x16x32_bf16 v[52:55], v[160:163], v[188:191], v[52:55]
	v_mfma_f32_16x16x32_bf16 v[48:51], v[180:183], v[188:191], v[48:51]
	v_mfma_f32_16x16x32_bf16 v[36:39], v[160:163], v[196:199], v[36:39]
	v_mfma_f32_16x16x32_bf16 v[32:35], v[180:183], v[196:199], v[32:35]
	v_mfma_f32_16x16x32_bf16 v[20:23], v[160:163], v[204:207], v[20:23]
	v_mfma_f32_16x16x32_bf16 v[16:19], v[180:183], v[204:207], v[16:19]
	v_mfma_f32_16x16x32_bf16 v[4:7], v[160:163], v[212:215], v[4:7]
	v_mfma_f32_16x16x32_bf16 v[0:3], v[180:183], v[212:215], v[0:3]
	v_mfma_f32_16x16x32_bf16 v[52:55], v[164:167], v[192:195], v[52:55]
	v_mfma_f32_16x16x32_bf16 v[48:51], v[184:187], v[192:195], v[48:51]
	v_mfma_f32_16x16x32_bf16 v[36:39], v[164:167], v[200:203], v[36:39]
	v_mfma_f32_16x16x32_bf16 v[32:35], v[184:187], v[200:203], v[32:35]
	v_mfma_f32_16x16x32_bf16 v[20:23], v[164:167], v[208:211], v[20:23]
	v_mfma_f32_16x16x32_bf16 v[16:19], v[184:187], v[208:211], v[16:19]
	v_mfma_f32_16x16x32_bf16 v[4:7], v[164:167], v[216:219], v[4:7]
	v_mfma_f32_16x16x32_bf16 v[0:3], v[184:187], v[216:219], v[0:3]
	s_setprio 0
	s_barrier
; #define PG8_STAGE(bufoff, gbase, voff) do { _Pragma("unroll") for (int _i = 0; _i < 2; ++_i) \
;         __builtin_amdgcn_global_load_lds((const unsigned*)((const char*)(gbase) + (voff)[_i]), (PG8_LAS unsigned*)(lds + (bufoff) + ldsw + _i * 8192), 16, 0, 0); } while (0)
; #define PG8_LDA(dst, b, h) do { _Pragma("unroll") for (int m = 0; m < 4; ++m) _Pragma("unroll") for (int k = 0; k < 2; ++k) dst[m][k] = *(const PG8_LAS bf16x8*)(lds + PG8_SA(b, h) + aoff + m * 2048 + k * 1024); } while (0)
; #define PG8_LDB(dst, b, h) do { _Pragma("unroll") for (int n = 0; n < 2; ++n) _Pragma("unroll") for (int k = 0; k < 2; ++k) dst[n][k] = *(const PG8_LAS bf16x8*)(lds + PG8_SB(b, h) + boff + n * 2048 + k * 1024); } while (0)
; #define PG8_MMA(ai, bj, At, Bt) do { __builtin_amdgcn_s_setprio(1); _Pragma("unroll") for (int m = 0; m < 4; ++m) _Pragma("unroll") for (int n = 0; n < 2; ++n) _Pragma("unroll") for (int k = 0; k < 2; ++k) \
;         acc[ai][bj][m][n] = __builtin_amdgcn_mfma_f32_16x16x32_bf16(Bt[n][k], At[m][k], acc[ai][bj][m][n], 0, 0, 0); __builtin_amdgcn_s_setprio(0); } while (0)
; #define PG8_WAIT_V(n) asm volatile("s_waitcnt vmcnt(" #n ")" ::: "memory")
; #define PG8_WAIT_L(n) asm volatile("s_waitcnt lgkmcnt(" #n ")" ::: "memory")
; #define PG8_BAR __builtin_amdgcn_s_barrier()
; #define PG8_SCHED __builtin_amdgcn_sched_barrier(0)
; template <class Epi, class Sched, bool ALIGN_EPI = false, bool SP2 = false>
; __device__ __forceinline__ void gemm_phase(PG8_LAS unsigned char* lds, const Gemm g, const Sched& S, const Epi& E) {
;     ...
;             PG8_LDB(B0, 1, 0); PG8_LDB(B1, 1, 1); PG8_SCHED; PG8_LDA(At, 1, 0); PG8_STAGE(PG8_SA(0, 1), a2 + hstepA, voffA);
;             PG8_WAIT_V(8); PG8_WAIT_L(0); PG8_BAR; PG8_MMA(0, 0, At, B0); PG8_MMA(0, 1, At, B1); PG8_BAR; PG8_SCHED;
;             PG8_LDA(At, 1, 1); PG8_STAGE(PG8_SB(1, 0), b3, voffB); PG8_STAGE(PG8_SB(1, 1), b3 + hstepB, voffB); PG8_STAGE(PG8_SA(1, 0), a3, voffA);
;             PG8_WAIT_V(8); PG8_WAIT_L(0); PG8_BAR; PG8_MMA(1, 0, At, B0); PG8_MMA(1, 1, At, B1); PG8_BAR; PG8_SCHED;
;     ...
;         if constexpr (ALIGN_EPI) { if (wr == 0) PG8_BAR; }
	s_add_i32 s69, 0, 0x18000
	s_add_i32 s70, 0, 0x1c000
	v_add_u32_e32 v156, s69, v172
	v_add_u32_e32 v179, s70, v172
	ds_read_b128 v[128:131], v156
	ds_read_b128 v[132:135], v156 offset:1024
	ds_read_b128 v[152:155], v156 offset:2048
	ds_read_b128 v[156:159], v156 offset:3072
	ds_read_b128 v[160:163], v179
	ds_read_b128 v[164:167], v179 offset:1024
	ds_read_b128 v[180:183], v179 offset:2048
	ds_read_b128 v[184:187], v179 offset:3072
	s_mov_b64 s[100:101], s[18:19]
	s_add_u32 s18, s18, 0x80000
	s_addc_u32 s19, s19, 0
	ds_read_b128 v[188:191], v175 offset:32768
	ds_read_b128 v[192:195], v175 offset:33792
	ds_read_b128 v[196:199], v175 offset:34816
	ds_read_b128 v[200:203], v175 offset:35840
	ds_read_b128 v[204:207], v175 offset:36864
	ds_read_b128 v[208:211], v175 offset:37888
	ds_read_b128 v[212:215], v175 offset:38912
	ds_read_b128 v[216:219], v175 offset:39936
	s_mov_b32 m0, s77
	s_nop 0
	global_load_lds_dwordx4 v136, s[100:101]
	s_mov_b32 m0, s22
	s_nop 0
	global_load_lds_dwordx4 v140, s[100:101]
	s_mov_b32 m0, s23
	s_nop 0
	global_load_lds_dwordx4 v136, s[18:19]
	s_mov_b32 m0, s4
	s_nop 0
	global_load_lds_dwordx4 v140, s[18:19]
	s_waitcnt vmcnt(8) lgkmcnt(0)
	s_barrier
	s_setprio 1
	v_mfma_f32_16x16x32_bf16 v[124:127], v[128:131], v[188:191], v[124:127]
	v_mfma_f32_16x16x32_bf16 v[120:123], v[152:155], v[188:191], v[120:123]
	v_mfma_f32_16x16x32_bf16 v[108:111], v[128:131], v[196:199], v[108:111]
	v_mfma_f32_16x16x32_bf16 v[104:107], v[152:155], v[196:199], v[104:107]
	v_mfma_f32_16x16x32_bf16 v[92:95], v[128:131], v[204:207], v[92:95]
	v_mfma_f32_16x16x32_bf16 v[88:91], v[152:155], v[204:207], v[88:91]
	v_mfma_f32_16x16x32_bf16 v[76:79], v[128:131], v[212:215], v[76:79]
	v_mfma_f32_16x16x32_bf16 v[72:75], v[152:155], v[212:215], v[72:75]
	v_mfma_f32_16x16x32_bf16 v[124:127], v[132:135], v[192:195], v[124:127]
	v_mfma_f32_16x16x32_bf16 v[120:123], v[156:159], v[192:195], v[120:123]
	v_mfma_f32_16x16x32_bf16 v[108:111], v[132:135], v[200:203], v[108:111]
	v_mfma_f32_16x16x32_bf16 v[104:107], v[156:159], v[200:203], v[104:107]
	v_mfma_f32_16x16x32_bf16 v[92:95], v[132:135], v[208:211], v[92:95]
	v_mfma_f32_16x16x32_bf16 v[88:91], v[156:159], v[208:211], v[88:91]
	v_mfma_f32_16x16x32_bf16 v[76:79], v[132:135], v[216:219], v[76:79]
	v_mfma_f32_16x16x32_bf16 v[72:75], v[156:159], v[216:219], v[72:75]
	s_setprio 0
	s_setprio 1
	v_mfma_f32_16x16x32_bf16 v[116:119], v[160:163], v[188:191], v[116:119]
	v_mfma_f32_16x16x32_bf16 v[112:115], v[180:183], v[188:191], v[112:115]
	v_mfma_f32_16x16x32_bf16 v[100:103], v[160:163], v[196:199], v[100:103]
	v_mfma_f32_16x16x32_bf16 v[96:99], v[180:183], v[196:199], v[96:99]
	v_mfma_f32_16x16x32_bf16 v[84:87], v[160:163], v[204:207], v[84:87]
	v_mfma_f32_16x16x32_bf16 v[80:83], v[180:183], v[204:207], v[80:83]
	v_mfma_f32_16x16x32_bf16 v[68:71], v[160:163], v[212:215], v[68:71]
	v_mfma_f32_16x16x32_bf16 v[64:67], v[180:183], v[212:215], v[64:67]
	v_mfma_f32_16x16x32_bf16 v[116:119], v[164:167], v[192:195], v[116:119]
	v_mfma_f32_16x16x32_bf16 v[112:115], v[184:187], v[192:195], v[112:115]
	v_mfma_f32_16x16x32_bf16 v[100:103], v[164:167], v[200:203], v[100:103]
	v_mfma_f32_16x16x32_bf16 v[96:99], v[184:187], v[200:203], v[96:99]
	v_mfma_f32_16x16x32_bf16 v[84:87], v[164:167], v[208:211], v[84:87]
	v_mfma_f32_16x16x32_bf16 v[80:83], v[184:187], v[208:211], v[80:83]
	v_mfma_f32_16x16x32_bf16 v[68:71], v[164:167], v[216:219], v[68:71]
	v_mfma_f32_16x16x32_bf16 v[64:67], v[184:187], v[216:219], v[64:67]
	s_setprio 0
	s_barrier
	s_add_i32 s18, s69, s33
	s_add_u32 s98, s16, 0x80
	s_addc_u32 s99, s17, 0
	s_mov_b32 m0, s18
	ds_read_b128 v[188:191], v175 offset:49152
	ds_read_b128 v[192:195], v175 offset:50176
	ds_read_b128 v[196:199], v175 offset:51200
	ds_read_b128 v[200:203], v175 offset:52224
	ds_read_b128 v[204:207], v175 offset:53248
	ds_read_b128 v[208:211], v175 offset:54272
	ds_read_b128 v[212:215], v175 offset:55296
	ds_read_b128 v[216:219], v175 offset:56320
	global_load_lds_dwordx4 v138, s[98:99]
	s_add_i32 m0, s18, 0x2000
	s_add_u32 s16, s16, 0x80080
	s_addc_u32 s17, s17, 0
	s_add_i32 s18, s70, s33
	global_load_lds_dwordx4 v142, s[98:99]
	s_mov_b32 m0, s18
	s_nop 0
	global_load_lds_dwordx4 v138, s[16:17]
	s_add_i32 m0, s18, 0x2000
	s_nop 0
	global_load_lds_dwordx4 v142, s[16:17]
	s_waitcnt vmcnt(6) lgkmcnt(0)
	s_barrier
	s_setprio 1
	v_mfma_f32_16x16x32_bf16 v[60:63], v[128:131], v[188:191], v[60:63]
	v_mfma_f32_16x16x32_bf16 v[56:59], v[152:155], v[188:191], v[56:59]
	v_mfma_f32_16x16x32_bf16 v[44:47], v[128:131], v[196:199], v[44:47]
	v_mfma_f32_16x16x32_bf16 v[40:43], v[152:155], v[196:199], v[40:43]
	v_mfma_f32_16x16x32_bf16 v[28:31], v[128:131], v[204:207], v[28:31]
	v_mfma_f32_16x16x32_bf16 v[24:27], v[152:155], v[204:207], v[24:27]
	v_mfma_f32_16x16x32_bf16 v[12:15], v[128:131], v[212:215], v[12:15]
	v_mfma_f32_16x16x32_bf16 v[8:11], v[152:155], v[212:215], v[8:11]
	v_mfma_f32_16x16x32_bf16 v[60:63], v[132:135], v[192:195], v[60:63]
	v_mfma_f32_16x16x32_bf16 v[56:59], v[156:159], v[192:195], v[56:59]
	v_mfma_f32_16x16x32_bf16 v[44:47], v[132:135], v[200:203], v[44:47]
	v_mfma_f32_16x16x32_bf16 v[40:43], v[156:159], v[200:203], v[40:43]
	v_mfma_f32_16x16x32_bf16 v[28:31], v[132:135], v[208:211], v[28:31]
	v_mfma_f32_16x16x32_bf16 v[24:27], v[156:159], v[208:211], v[24:27]
	v_mfma_f32_16x16x32_bf16 v[12:15], v[132:135], v[216:219], v[12:15]
	v_mfma_f32_16x16x32_bf16 v[8:11], v[156:159], v[216:219], v[8:11]
	s_setprio 0
	s_setprio 1
	v_mfma_f32_16x16x32_bf16 v[52:55], v[160:163], v[188:191], v[52:55]
	v_mfma_f32_16x16x32_bf16 v[48:51], v[180:183], v[188:191], v[48:51]
	v_mfma_f32_16x16x32_bf16 v[36:39], v[160:163], v[196:199], v[36:39]
	v_mfma_f32_16x16x32_bf16 v[32:35], v[180:183], v[196:199], v[32:35]
	v_mfma_f32_16x16x32_bf16 v[20:23], v[160:163], v[204:207], v[20:23]
	v_mfma_f32_16x16x32_bf16 v[16:19], v[180:183], v[204:207], v[16:19]
	v_mfma_f32_16x16x32_bf16 v[4:7], v[160:163], v[212:215], v[4:7]
	v_mfma_f32_16x16x32_bf16 v[0:3], v[180:183], v[212:215], v[0:3]
	v_mfma_f32_16x16x32_bf16 v[52:55], v[164:167], v[192:195], v[52:55]
	v_mfma_f32_16x16x32_bf16 v[48:51], v[184:187], v[192:195], v[48:51]
	v_mfma_f32_16x16x32_bf16 v[36:39], v[164:167], v[200:203], v[36:39]
	v_mfma_f32_16x16x32_bf16 v[32:35], v[184:187], v[200:203], v[32:35]
	v_mfma_f32_16x16x32_bf16 v[20:23], v[164:167], v[208:211], v[20:23]
	v_mfma_f32_16x16x32_bf16 v[16:19], v[184:187], v[208:211], v[16:19]
	v_mfma_f32_16x16x32_bf16 v[4:7], v[164:167], v[216:219], v[4:7]
	v_mfma_f32_16x16x32_bf16 v[0:3], v[184:187], v[216:219], v[0:3]
	s_setprio 0
	s_barrier
	s_add_i32 s61, s61, 2
	s_add_u32 s12, s12, 0x100
	s_addc_u32 s13, s13, 0
	s_add_u32 s37, s37, 0x100
	s_addc_u32 s60, s60, 0
	s_cmp_gt_u32 s61, 29
	s_cbranch_scc0 .LBB0_187
	s_and_b64 vcc, exec, s[96:97]
	s_cbranch_vccz .LBB0_190
	s_barrier

; #define PG8_STAGE(bufoff, gbase, voff) do { _Pragma("unroll") for (int _i = 0; _i < 2; ++_i) \
;         __builtin_amdgcn_global_load_lds((const unsigned*)((const char*)(gbase) + (voff)[_i]), (PG8_LAS unsigned*)(lds + (bufoff) + ldsw + _i * 8192), 16, 0, 0); } while (0)
; #define PG8_LDA(dst, b, h) do { _Pragma("unroll") for (int m = 0; m < 4; ++m) _Pragma("unroll") for (int k = 0; k < 2; ++k) dst[m][k] = *(const PG8_LAS bf16x8*)(lds + PG8_SA(b, h) + aoff + m * 2048 + k * 1024); } while (0)
; #define PG8_LDB(dst, b, h) do { _Pragma("unroll") for (int n = 0; n < 2; ++n) _Pragma("unroll") for (int k = 0; k < 2; ++k) dst[n][k] = *(const PG8_LAS bf16x8*)(lds + PG8_SB(b, h) + boff + n * 2048 + k * 1024); } while (0)
; #define PG8_MMA(ai, bj, At, Bt) do { __builtin_amdgcn_s_setprio(1); _Pragma("unroll") for (int m = 0; m < 4; ++m) _Pragma("unroll") for (int n = 0; n < 2; ++n) _Pragma("unroll") for (int k = 0; k < 2; ++k) \
;         acc[ai][bj][m][n] = __builtin_amdgcn_mfma_f32_16x16x32_bf16(Bt[n][k], At[m][k], acc[ai][bj][m][n], 0, 0, 0); __builtin_amdgcn_s_setprio(0); } while (0)
; #define PG8_WAIT_V(n) asm volatile("s_waitcnt vmcnt(" #n ")" ::: "memory")
; template <class Epi, class Sched, bool ALIGN_EPI = false, bool SP2 = false>
; __device__ __forceinline__ void gemm_phase(PG8_LAS unsigned char* lds, const Gemm g, const Sched& S, const Epi& E) {
;     ...
;             const bool last = (t == nt - 2);
;             if constexpr (Epi::HAS_MID) { if (t == E.mid_t) E.mid(acc, cur, wr, wc, fr, fq); }
;             const char* a1 = cA + (size_t)(t + 1) * kstep;
;             const char* a2 = last ? nA : cA + (size_t)(t + 2) * kstep; const char* b2 = last ? nB : cB + (size_t)(t + 2) * kstep;
;             const char* a3 = a2 + kstep; const char* b3 = b2 + kstep;
;             if (last && has_next) S.a_ready(nxt);
;             if constexpr (SP2) {
;             PG8_LDB(B0, 0, 0); PG8_LDB(B1, 0, 1); PG8_SCHED; PG8_LDA(At, 0, 0); PG8_STAGE(PG8_SA(1, 1), a1 + hstepA, voffA);
;             PG8_WAIT_V(8); PG8_WAIT_L(0); PG8_BAR; PG8_MMA(0, 0, At, B0); PG8_MMA(0, 1, At, B1); PG8_BAR; PG8_SCHED;
;             PG8_LDA(At, 0, 1); PG8_STAGE(PG8_SB(0, 0), b2, voffB); PG8_STAGE(PG8_SB(0, 1), b2 + hstepB, voffB); PG8_STAGE(PG8_SA(0, 0), a2, voffA);
;             PG8_WAIT_V(8); PG8_WAIT_L(0); PG8_BAR; PG8_MMA(1, 0, At, B0); PG8_MMA(1, 1, At, B1); PG8_BAR; PG8_SCHED;
.LBB0_519:
	ds_read_b128 v[128:131], v169
	ds_read_b128 v[132:135], v169 offset:1024
	ds_read_b128 v[148:151], v169 offset:2048
	ds_read_b128 v[152:155], v169 offset:3072
	ds_read_b128 v[156:159], v170
	ds_read_b128 v[160:163], v170 offset:1024
	ds_read_b128 v[174:177], v170 offset:2048
	ds_read_b128 v[178:181], v170 offset:3072
	s_add_u32 s18, s16, 0xfff80080
	s_addc_u32 s19, s17, -1
	s_cmp_eq_u32 s69, 28
	s_cselect_b32 s43, s13, s19
	s_cselect_b32 s42, s39, s18
	s_cselect_b32 s19, s37, s68
	s_cselect_b32 s18, s66, s67
	v_lshl_add_u64 v[164:165], s[16:17], 0, v[144:145]
	s_add_i32 m0, s6, 0xc000
	ds_read_b128 v[182:185], v171
	ds_read_b128 v[186:189], v171 offset:1024
	ds_read_b128 v[190:193], v171 offset:2048
	ds_read_b128 v[194:197], v171 offset:3072
	ds_read_b128 v[198:201], v171 offset:4096
	ds_read_b128 v[202:205], v171 offset:5120
	ds_read_b128 v[206:209], v171 offset:6144
	ds_read_b128 v[210:213], v171 offset:7168
	global_load_lds_dwordx4 v[164:165], off
	v_lshl_add_u64 v[164:165], s[16:17], 0, v[146:147]
	s_add_i32 m0, s6, 0xe000
	s_nop 0
	global_load_lds_dwordx4 v[164:165], off
	s_waitcnt vmcnt(8) lgkmcnt(0)
	s_barrier
	s_setprio 1
	s_waitcnt lgkmcnt(0)
	v_mfma_f32_16x16x32_bf16 v[124:127], v[128:131], v[182:185], v[124:127]
	v_mfma_f32_16x16x32_bf16 v[120:123], v[148:151], v[182:185], v[120:123]
	v_mfma_f32_16x16x32_bf16 v[108:111], v[128:131], v[190:193], v[108:111]
	v_mfma_f32_16x16x32_bf16 v[104:107], v[148:151], v[190:193], v[104:107]
	v_mfma_f32_16x16x32_bf16 v[92:95], v[128:131], v[198:201], v[92:95]
	v_mfma_f32_16x16x32_bf16 v[88:91], v[148:151], v[198:201], v[88:91]
	v_mfma_f32_16x16x32_bf16 v[76:79], v[128:131], v[206:209], v[76:79]
	v_mfma_f32_16x16x32_bf16 v[72:75], v[148:151], v[206:209], v[72:75]
	v_mfma_f32_16x16x32_bf16 v[124:127], v[132:135], v[186:189], v[124:127]
	v_mfma_f32_16x16x32_bf16 v[120:123], v[152:155], v[186:189], v[120:123]
	v_mfma_f32_16x16x32_bf16 v[108:111], v[132:135], v[194:197], v[108:111]
	v_mfma_f32_16x16x32_bf16 v[104:107], v[152:155], v[194:197], v[104:107]
	v_mfma_f32_16x16x32_bf16 v[92:95], v[132:135], v[202:205], v[92:95]
	v_mfma_f32_16x16x32_bf16 v[88:91], v[152:155], v[202:205], v[88:91]
	v_mfma_f32_16x16x32_bf16 v[76:79], v[132:135], v[210:213], v[76:79]
	v_mfma_f32_16x16x32_bf16 v[72:75], v[152:155], v[210:213], v[72:75]
	s_setprio 0
	s_setprio 1
	v_mfma_f32_16x16x32_bf16 v[116:119], v[156:159], v[182:185], v[116:119]
	v_mfma_f32_16x16x32_bf16 v[112:115], v[174:177], v[182:185], v[112:115]
	v_mfma_f32_16x16x32_bf16 v[100:103], v[156:159], v[190:193], v[100:103]
	v_mfma_f32_16x16x32_bf16 v[96:99], v[174:177], v[190:193], v[96:99]
	v_mfma_f32_16x16x32_bf16 v[84:87], v[156:159], v[198:201], v[84:87]
	v_mfma_f32_16x16x32_bf16 v[80:83], v[174:177], v[198:201], v[80:83]
	v_mfma_f32_16x16x32_bf16 v[68:71], v[156:159], v[206:209], v[68:71]
	v_mfma_f32_16x16x32_bf16 v[64:67], v[174:177], v[206:209], v[64:67]
	v_mfma_f32_16x16x32_bf16 v[116:119], v[160:163], v[186:189], v[116:119]
	v_mfma_f32_16x16x32_bf16 v[112:115], v[178:181], v[186:189], v[112:115]
	v_mfma_f32_16x16x32_bf16 v[100:103], v[160:163], v[194:197], v[100:103]
	v_mfma_f32_16x16x32_bf16 v[96:99], v[178:181], v[194:197], v[96:99]
	v_mfma_f32_16x16x32_bf16 v[84:87], v[160:163], v[202:205], v[84:87]
	v_mfma_f32_16x16x32_bf16 v[80:83], v[178:181], v[202:205], v[80:83]
	v_mfma_f32_16x16x32_bf16 v[68:71], v[160:163], v[210:213], v[68:71]
	v_mfma_f32_16x16x32_bf16 v[64:67], v[178:181], v[210:213], v[64:67]
	s_setprio 0
	s_barrier
	s_add_i32 s70, s59, s5
	v_lshl_add_u64 v[164:165], s[18:19], 0, v[138:139]
	s_mov_b32 m0, s70
	ds_read_b128 v[182:185], v171 offset:16384
	ds_read_b128 v[186:189], v171 offset:17408
	ds_read_b128 v[190:193], v171 offset:18432
	ds_read_b128 v[194:197], v171 offset:19456
	ds_read_b128 v[198:201], v171 offset:20480
	ds_read_b128 v[202:205], v171 offset:21504
	ds_read_b128 v[206:209], v171 offset:22528
	ds_read_b128 v[210:213], v171 offset:23552
	global_load_lds_dwordx4 v[164:165], off
	s_add_i32 m0, s70, 0x2000
	s_add_u32 s70, s18, 0x80000
	v_lshl_add_u64 v[214:215], s[18:19], 0, v[142:143]
	s_addc_u32 s71, s19, 0
	s_add_i32 s74, s62, s5
	global_load_lds_dwordx4 v[214:215], off
	v_lshl_add_u64 v[216:217], s[70:71], 0, v[138:139]
	s_mov_b32 m0, s74
	v_lshl_add_u64 v[218:219], s[42:43], 0, v[140:141]
	global_load_lds_dwordx4 v[216:217], off
	v_lshl_add_u64 v[216:217], s[70:71], 0, v[142:143]
	s_add_i32 m0, s74, 0x2000
	s_nop 0
	global_load_lds_dwordx4 v[216:217], off
	v_lshl_add_u64 v[216:217], s[42:43], 0, v[136:137]
	s_mov_b32 m0, s6
	s_nop 0
	global_load_lds_dwordx4 v[216:217], off
	s_mov_b32 m0, s7
	s_nop 0
	global_load_lds_dwordx4 v[218:219], off
	s_waitcnt vmcnt(8) lgkmcnt(0)
	s_barrier
; #define PG8_STAGE(bufoff, gbase, voff) do { _Pragma("unroll") for (int _i = 0; _i < 2; ++_i) \
;         __builtin_amdgcn_global_load_lds((const unsigned*)((const char*)(gbase) + (voff)[_i]), (PG8_LAS unsigned*)(lds + (bufoff) + ldsw + _i * 8192), 16, 0, 0); } while (0)
; #define PG8_LDA(dst, b, h) do { _Pragma("unroll") for (int m = 0; m < 4; ++m) _Pragma("unroll") for (int k = 0; k < 2; ++k) dst[m][k] = *(const PG8_LAS bf16x8*)(lds + PG8_SA(b, h) + aoff + m * 2048 + k * 1024); } while (0)
; #define PG8_LDB(dst, b, h) do { _Pragma("unroll") for (int n = 0; n < 2; ++n) _Pragma("unroll") for (int k = 0; k < 2; ++k) dst[n][k] = *(const PG8_LAS bf16x8*)(lds + PG8_SB(b, h) + boff + n * 2048 + k * 1024); } while (0)
; #define PG8_MMA(ai, bj, At, Bt) do { __builtin_amdgcn_s_setprio(1); _Pragma("unroll") for (int m = 0; m < 4; ++m) _Pragma("unroll") for (int n = 0; n < 2; ++n) _Pragma("unroll") for (int k = 0; k < 2; ++k) \
;         acc[ai][bj][m][n] = __builtin_amdgcn_mfma_f32_16x16x32_bf16(Bt[n][k], At[m][k], acc[ai][bj][m][n], 0, 0, 0); __builtin_amdgcn_s_setprio(0); } while (0)
; #define PG8_WAIT_V(n) asm volatile("s_waitcnt vmcnt(" #n ")" ::: "memory")
; #define PG8_WAIT_L(n) asm volatile("s_waitcnt lgkmcnt(" #n ")" ::: "memory")
; #define PG8_BAR __builtin_amdgcn_s_barrier()
; #define PG8_SCHED __builtin_amdgcn_sched_barrier(0)
; template <class Epi, class Sched, bool ALIGN_EPI = false, bool SP2 = false>
; __device__ __forceinline__ void gemm_phase(PG8_LAS unsigned char* lds, const Gemm g, const Sched& S, const Epi& E) {
;     ...
;             PG8_WAIT_V(8); PG8_WAIT_L(0); PG8_BAR; PG8_MMA(1, 0, At, B0); PG8_MMA(1, 1, At, B1); PG8_BAR; PG8_SCHED;
;             PG8_LDB(B0, 1, 0); PG8_LDB(B1, 1, 1); PG8_SCHED; PG8_LDA(At, 1, 0); PG8_STAGE(PG8_SA(0, 1), a2 + hstepA, voffA);
;             PG8_WAIT_V(8); PG8_WAIT_L(0); PG8_BAR; PG8_MMA(0, 0, At, B0); PG8_MMA(0, 1, At, B1); PG8_BAR; PG8_SCHED;
	s_setprio 1
	s_waitcnt lgkmcnt(0)
	v_mfma_f32_16x16x32_bf16 v[60:63], v[128:131], v[182:185], v[60:63]
	v_mfma_f32_16x16x32_bf16 v[56:59], v[148:151], v[182:185], v[56:59]
	v_mfma_f32_16x16x32_bf16 v[44:47], v[128:131], v[190:193], v[44:47]
	v_mfma_f32_16x16x32_bf16 v[40:43], v[148:151], v[190:193], v[40:43]
	v_mfma_f32_16x16x32_bf16 v[28:31], v[128:131], v[198:201], v[28:31]
	v_mfma_f32_16x16x32_bf16 v[24:27], v[148:151], v[198:201], v[24:27]
	v_mfma_f32_16x16x32_bf16 v[12:15], v[128:131], v[206:209], v[12:15]
	v_mfma_f32_16x16x32_bf16 v[8:11], v[148:151], v[206:209], v[8:11]
	v_mfma_f32_16x16x32_bf16 v[60:63], v[132:135], v[186:189], v[60:63]
	v_mfma_f32_16x16x32_bf16 v[56:59], v[152:155], v[186:189], v[56:59]
	v_mfma_f32_16x16x32_bf16 v[44:47], v[132:135], v[194:197], v[44:47]
	v_mfma_f32_16x16x32_bf16 v[40:43], v[152:155], v[194:197], v[40:43]
	v_mfma_f32_16x16x32_bf16 v[28:31], v[132:135], v[202:205], v[28:31]
	v_mfma_f32_16x16x32_bf16 v[24:27], v[152:155], v[202:205], v[24:27]
	v_mfma_f32_16x16x32_bf16 v[12:15], v[132:135], v[210:213], v[12:15]
	v_mfma_f32_16x16x32_bf16 v[8:11], v[152:155], v[210:213], v[8:11]
	s_setprio 0
	s_setprio 1
	v_mfma_f32_16x16x32_bf16 v[52:55], v[156:159], v[182:185], v[52:55]
	v_mfma_f32_16x16x32_bf16 v[48:51], v[174:177], v[182:185], v[48:51]
	v_mfma_f32_16x16x32_bf16 v[36:39], v[156:159], v[190:193], v[36:39]
	v_mfma_f32_16x16x32_bf16 v[32:35], v[174:177], v[190:193], v[32:35]
	v_mfma_f32_16x16x32_bf16 v[20:23], v[156:159], v[198:201], v[20:23]
	v_mfma_f32_16x16x32_bf16 v[16:19], v[174:177], v[198:201], v[16:19]
	v_mfma_f32_16x16x32_bf16 v[4:7], v[156:159], v[206:209], v[4:7]
	v_mfma_f32_16x16x32_bf16 v[0:3], v[174:177], v[206:209], v[0:3]
	v_mfma_f32_16x16x32_bf16 v[52:55], v[160:163], v[186:189], v[52:55]
	v_mfma_f32_16x16x32_bf16 v[48:51], v[178:181], v[186:189], v[48:51]
	v_mfma_f32_16x16x32_bf16 v[36:39], v[160:163], v[194:197], v[36:39]
	v_mfma_f32_16x16x32_bf16 v[32:35], v[178:181], v[194:197], v[32:35]
	v_mfma_f32_16x16x32_bf16 v[20:23], v[160:163], v[202:205], v[20:23]
	v_mfma_f32_16x16x32_bf16 v[16:19], v[178:181], v[202:205], v[16:19]
	v_mfma_f32_16x16x32_bf16 v[4:7], v[160:163], v[210:213], v[4:7]
	v_mfma_f32_16x16x32_bf16 v[0:3], v[178:181], v[210:213], v[0:3]
	s_setprio 0
	s_barrier
	s_add_i32 s70, 0, 0x18000
	s_add_i32 s71, 0, 0x1c000
	v_add_u32_e32 v152, s70, v168
	v_add_u32_e32 v173, s71, v168
	ds_read_b128 v[128:131], v152
	ds_read_b128 v[132:135], v152 offset:1024
	ds_read_b128 v[148:151], v152 offset:2048
	ds_read_b128 v[152:155], v152 offset:3072
	ds_read_b128 v[156:159], v173
	ds_read_b128 v[160:163], v173 offset:1024
	ds_read_b128 v[174:177], v173 offset:2048
	ds_read_b128 v[178:181], v173 offset:3072
	s_add_u32 s42, s42, 0x80000
	s_addc_u32 s43, s43, 0
	s_mov_b32 m0, s22
	v_lshl_add_u64 v[220:221], s[42:43], 0, v[136:137]
	ds_read_b128 v[182:185], v171 offset:32768
	ds_read_b128 v[186:189], v171 offset:33792
	ds_read_b128 v[190:193], v171 offset:34816
	ds_read_b128 v[194:197], v171 offset:35840
	ds_read_b128 v[198:201], v171 offset:36864
	ds_read_b128 v[202:205], v171 offset:37888
	ds_read_b128 v[206:209], v171 offset:38912
	ds_read_b128 v[210:213], v171 offset:39936
	global_load_lds_dwordx4 v[220:221], off
	v_lshl_add_u64 v[220:221], s[42:43], 0, v[140:141]
	s_mov_b32 m0, s23
	s_nop 0
	global_load_lds_dwordx4 v[220:221], off
	s_waitcnt vmcnt(8) lgkmcnt(0)
	s_barrier
	s_setprio 1
	s_waitcnt lgkmcnt(0)
	v_mfma_f32_16x16x32_bf16 v[124:127], v[128:131], v[182:185], v[124:127]
	v_mfma_f32_16x16x32_bf16 v[120:123], v[148:151], v[182:185], v[120:123]
	v_mfma_f32_16x16x32_bf16 v[108:111], v[128:131], v[190:193], v[108:111]
	v_mfma_f32_16x16x32_bf16 v[104:107], v[148:151], v[190:193], v[104:107]
	v_mfma_f32_16x16x32_bf16 v[92:95], v[128:131], v[198:201], v[92:95]
	v_mfma_f32_16x16x32_bf16 v[88:91], v[148:151], v[198:201], v[88:91]
	v_mfma_f32_16x16x32_bf16 v[76:79], v[128:131], v[206:209], v[76:79]
	v_mfma_f32_16x16x32_bf16 v[72:75], v[148:151], v[206:209], v[72:75]
	v_mfma_f32_16x16x32_bf16 v[124:127], v[132:135], v[186:189], v[124:127]
	v_mfma_f32_16x16x32_bf16 v[120:123], v[152:155], v[186:189], v[120:123]
	v_mfma_f32_16x16x32_bf16 v[108:111], v[132:135], v[194:197], v[108:111]
	v_mfma_f32_16x16x32_bf16 v[104:107], v[152:155], v[194:197], v[104:107]
	v_mfma_f32_16x16x32_bf16 v[92:95], v[132:135], v[202:205], v[92:95]
	v_mfma_f32_16x16x32_bf16 v[88:91], v[152:155], v[202:205], v[88:91]
	v_mfma_f32_16x16x32_bf16 v[76:79], v[132:135], v[210:213], v[76:79]
	v_mfma_f32_16x16x32_bf16 v[72:75], v[152:155], v[210:213], v[72:75]
	s_setprio 0
	s_setprio 1
	v_mfma_f32_16x16x32_bf16 v[116:119], v[156:159], v[182:185], v[116:119]
	v_mfma_f32_16x16x32_bf16 v[112:115], v[174:177], v[182:185], v[112:115]
	v_mfma_f32_16x16x32_bf16 v[100:103], v[156:159], v[190:193], v[100:103]
	v_mfma_f32_16x16x32_bf16 v[96:99], v[174:177], v[190:193], v[96:99]
	v_mfma_f32_16x16x32_bf16 v[84:87], v[156:159], v[198:201], v[84:87]
	v_mfma_f32_16x16x32_bf16 v[80:83], v[174:177], v[198:201], v[80:83]
	v_mfma_f32_16x16x32_bf16 v[68:71], v[156:159], v[206:209], v[68:71]
	v_mfma_f32_16x16x32_bf16 v[64:67], v[174:177], v[206:209], v[64:67]
	v_mfma_f32_16x16x32_bf16 v[116:119], v[160:163], v[186:189], v[116:119]
	v_mfma_f32_16x16x32_bf16 v[112:115], v[178:181], v[186:189], v[112:115]
	v_mfma_f32_16x16x32_bf16 v[100:103], v[160:163], v[194:197], v[100:103]
	v_mfma_f32_16x16x32_bf16 v[96:99], v[178:181], v[194:197], v[96:99]
	v_mfma_f32_16x16x32_bf16 v[84:87], v[160:163], v[202:205], v[84:87]
	v_mfma_f32_16x16x32_bf16 v[80:83], v[178:181], v[202:205], v[80:83]
	v_mfma_f32_16x16x32_bf16 v[68:71], v[160:163], v[210:213], v[68:71]
	v_mfma_f32_16x16x32_bf16 v[64:67], v[178:181], v[210:213], v[64:67]
	s_setprio 0
	s_barrier
; #define PG8_STAGE(bufoff, gbase, voff) do { _Pragma("unroll") for (int _i = 0; _i < 2; ++_i) \
;         __builtin_amdgcn_global_load_lds((const unsigned*)((const char*)(gbase) + (voff)[_i]), (PG8_LAS unsigned*)(lds + (bufoff) + ldsw + _i * 8192), 16, 0, 0); } while (0)
; #define PG8_LDA(dst, b, h) do { _Pragma("unroll") for (int m = 0; m < 4; ++m) _Pragma("unroll") for (int k = 0; k < 2; ++k) dst[m][k] = *(const PG8_LAS bf16x8*)(lds + PG8_SA(b, h) + aoff + m * 2048 + k * 1024); } while (0)
; #define PG8_MMA(ai, bj, At, Bt) do { __builtin_amdgcn_s_setprio(1); _Pragma("unroll") for (int m = 0; m < 4; ++m) _Pragma("unroll") for (int n = 0; n < 2; ++n) _Pragma("unroll") for (int k = 0; k < 2; ++k) \
;         acc[ai][bj][m][n] = __builtin_amdgcn_mfma_f32_16x16x32_bf16(Bt[n][k], At[m][k], acc[ai][bj][m][n], 0, 0, 0); __builtin_amdgcn_s_setprio(0); } while (0)
; #define PG8_WAIT_V(n) asm volatile("s_waitcnt vmcnt(" #n ")" ::: "memory")
; #define PG8_WAIT_L(n) asm volatile("s_waitcnt lgkmcnt(" #n ")" ::: "memory")
; #define PG8_BAR __builtin_amdgcn_s_barrier()
; #define PG8_SCHED __builtin_amdgcn_sched_barrier(0)
; template <class Epi, class Sched, bool ALIGN_EPI = false, bool SP2 = false>
; __device__ __forceinline__ void gemm_phase(PG8_LAS unsigned char* lds, const Gemm g, const Sched& S, const Epi& E) {
;     ...
;             PG8_LDA(At, 1, 1); PG8_STAGE(PG8_SB(1, 0), b3, voffB); PG8_STAGE(PG8_SB(1, 1), b3 + hstepB, voffB); PG8_STAGE(PG8_SA(1, 0), a3, voffA);
;             PG8_WAIT_V(8); PG8_WAIT_L(0); PG8_BAR; PG8_MMA(1, 0, At, B0); PG8_MMA(1, 1, At, B1); PG8_BAR; PG8_SCHED;
;     ...
;         if constexpr (ALIGN_EPI) { if (wr == 0) PG8_BAR; }
	s_add_i32 s42, s70, s5
	v_lshl_add_u64 v[164:165], v[164:165], 0, s[26:27]
	s_mov_b32 m0, s42
	ds_read_b128 v[182:185], v171 offset:49152
	ds_read_b128 v[186:189], v171 offset:50176
	ds_read_b128 v[190:193], v171 offset:51200
	ds_read_b128 v[194:197], v171 offset:52224
	ds_read_b128 v[198:201], v171 offset:53248
	ds_read_b128 v[202:205], v171 offset:54272
	ds_read_b128 v[206:209], v171 offset:55296
	ds_read_b128 v[210:213], v171 offset:56320
	global_load_lds_dwordx4 v[164:165], off
	s_add_i32 m0, s42, 0x2000
	s_add_u32 s18, s18, 0x80080
	v_lshl_add_u64 v[164:165], v[214:215], 0, s[26:27]
	s_addc_u32 s19, s19, 0
	s_add_i32 s42, s71, s5
	global_load_lds_dwordx4 v[164:165], off
	v_lshl_add_u64 v[164:165], s[18:19], 0, v[138:139]
	s_mov_b32 m0, s42
	s_nop 0
	global_load_lds_dwordx4 v[164:165], off
	v_lshl_add_u64 v[164:165], s[18:19], 0, v[142:143]
	s_add_i32 m0, s42, 0x2000
	s_nop 0
	global_load_lds_dwordx4 v[164:165], off
	v_lshl_add_u64 v[164:165], v[216:217], 0, s[26:27]
	s_mov_b32 m0, s47
	s_nop 0
	global_load_lds_dwordx4 v[164:165], off
	v_lshl_add_u64 v[164:165], v[218:219], 0, s[26:27]
	s_mov_b32 m0, s56
	s_nop 0
	global_load_lds_dwordx4 v[164:165], off
	s_waitcnt vmcnt(8) lgkmcnt(0)
	s_barrier
	s_setprio 1
	s_waitcnt lgkmcnt(0)
	v_mfma_f32_16x16x32_bf16 v[60:63], v[128:131], v[182:185], v[60:63]
	v_mfma_f32_16x16x32_bf16 v[56:59], v[148:151], v[182:185], v[56:59]
	v_mfma_f32_16x16x32_bf16 v[44:47], v[128:131], v[190:193], v[44:47]
	v_mfma_f32_16x16x32_bf16 v[40:43], v[148:151], v[190:193], v[40:43]
	v_mfma_f32_16x16x32_bf16 v[28:31], v[128:131], v[198:201], v[28:31]
	v_mfma_f32_16x16x32_bf16 v[24:27], v[148:151], v[198:201], v[24:27]
	v_mfma_f32_16x16x32_bf16 v[12:15], v[128:131], v[206:209], v[12:15]
	v_mfma_f32_16x16x32_bf16 v[8:11], v[148:151], v[206:209], v[8:11]
	v_mfma_f32_16x16x32_bf16 v[60:63], v[132:135], v[186:189], v[60:63]
	v_mfma_f32_16x16x32_bf16 v[56:59], v[152:155], v[186:189], v[56:59]
	v_mfma_f32_16x16x32_bf16 v[44:47], v[132:135], v[194:197], v[44:47]
	v_mfma_f32_16x16x32_bf16 v[40:43], v[152:155], v[194:197], v[40:43]
	v_mfma_f32_16x16x32_bf16 v[28:31], v[132:135], v[202:205], v[28:31]
	v_mfma_f32_16x16x32_bf16 v[24:27], v[152:155], v[202:205], v[24:27]
	v_mfma_f32_16x16x32_bf16 v[12:15], v[132:135], v[210:213], v[12:15]
	v_mfma_f32_16x16x32_bf16 v[8:11], v[152:155], v[210:213], v[8:11]
	s_setprio 0
	s_setprio 1
	v_mfma_f32_16x16x32_bf16 v[52:55], v[156:159], v[182:185], v[52:55]
	v_mfma_f32_16x16x32_bf16 v[48:51], v[174:177], v[182:185], v[48:51]
	v_mfma_f32_16x16x32_bf16 v[36:39], v[156:159], v[190:193], v[36:39]
	v_mfma_f32_16x16x32_bf16 v[32:35], v[174:177], v[190:193], v[32:35]
	v_mfma_f32_16x16x32_bf16 v[20:23], v[156:159], v[198:201], v[20:23]
	v_mfma_f32_16x16x32_bf16 v[16:19], v[174:177], v[198:201], v[16:19]
	v_mfma_f32_16x16x32_bf16 v[4:7], v[156:159], v[206:209], v[4:7]
	v_mfma_f32_16x16x32_bf16 v[0:3], v[174:177], v[206:209], v[0:3]
	v_mfma_f32_16x16x32_bf16 v[52:55], v[160:163], v[186:189], v[52:55]
	v_mfma_f32_16x16x32_bf16 v[48:51], v[178:181], v[186:189], v[48:51]
	v_mfma_f32_16x16x32_bf16 v[36:39], v[160:163], v[194:197], v[36:39]
	v_mfma_f32_16x16x32_bf16 v[32:35], v[178:181], v[194:197], v[32:35]
	v_mfma_f32_16x16x32_bf16 v[20:23], v[160:163], v[202:205], v[20:23]
	v_mfma_f32_16x16x32_bf16 v[16:19], v[178:181], v[202:205], v[16:19]
	v_mfma_f32_16x16x32_bf16 v[4:7], v[160:163], v[210:213], v[4:7]
	v_mfma_f32_16x16x32_bf16 v[0:3], v[178:181], v[210:213], v[0:3]
	s_setprio 0
	s_barrier
	s_add_i32 s69, s69, 2
	s_add_u32 s16, s16, 0x100
	s_addc_u32 s17, s17, 0
	s_add_u32 s67, s67, 0x100
	s_addc_u32 s68, s68, 0
	s_cmp_gt_u32 s69, 29
	s_cbranch_scc0 .LBB0_519
	s_and_b64 vcc, exec, s[28:29]
	s_cbranch_vccz .LBB0_522
	s_barrier

; #define PG8_STAGE(bufoff, gbase, voff) do { _Pragma("unroll") for (int _i = 0; _i < 2; ++_i) \
;         __builtin_amdgcn_global_load_lds((const unsigned*)((const char*)(gbase) + (voff)[_i]), (PG8_LAS unsigned*)(lds + (bufoff) + ldsw + _i * 8192), 16, 0, 0); } while (0)
; #define PG8_LDA(dst, b, h) do { _Pragma("unroll") for (int m = 0; m < 4; ++m) _Pragma("unroll") for (int k = 0; k < 2; ++k) dst[m][k] = *(const PG8_LAS bf16x8*)(lds + PG8_SA(b, h) + aoff + m * 2048 + k * 1024); } while (0)
; #define PG8_LDB(dst, b, h) do { _Pragma("unroll") for (int n = 0; n < 2; ++n) _Pragma("unroll") for (int k = 0; k < 2; ++k) dst[n][k] = *(const PG8_LAS bf16x8*)(lds + PG8_SB(b, h) + boff + n * 2048 + k * 1024); } while (0)
; #define PG8_MMA(ai, bj, At, Bt) do { __builtin_amdgcn_s_setprio(1); _Pragma("unroll") for (int m = 0; m < 4; ++m) _Pragma("unroll") for (int n = 0; n < 2; ++n) _Pragma("unroll") for (int k = 0; k < 2; ++k) \
;         acc[ai][bj][m][n] = __builtin_amdgcn_mfma_f32_16x16x32_bf16(Bt[n][k], At[m][k], acc[ai][bj][m][n], 0, 0, 0); __builtin_amdgcn_s_setprio(0); } while (0)
; #define PG8_WAIT_V(n) asm volatile("s_waitcnt vmcnt(" #n ")" ::: "memory")
; #define PG8_WAIT_L(n) asm volatile("s_waitcnt lgkmcnt(" #n ")" ::: "memory")
; template <class Epi, class Sched, bool ALIGN_EPI = false, bool SP2 = false>
; __device__ __forceinline__ void gemm_phase(PG8_LAS unsigned char* lds, const Gemm g, const Sched& S, const Epi& E) {
;     ...
;         PG8_STAGE(PG8_SB(0, 0), cB, voffB); PG8_STAGE(PG8_SB(0, 1), cB + hstepB, voffB); PG8_STAGE(PG8_SA(0, 0), cA, voffA); PG8_STAGE(PG8_SA(0, 1), cA + hstepA, voffA);
;         if (wr == 1) PG8_BAR;
;         PG8_WAIT_V(2); PG8_BAR;
;         PG8_STAGE(PG8_SB(1, 0), cB + kstep, voffB); PG8_STAGE(PG8_SA(1, 0), cA + kstep, voffA); PG8_STAGE(PG8_SB(1, 1), cB + hstepB + kstep, voffB);
;         PG8_WAIT_V(6); PG8_BAR;
;     ...
;             PG8_LDB(B0, 0, 0); PG8_LDB(B1, 0, 1); PG8_SCHED; PG8_LDA(At, 0, 0); PG8_STAGE(PG8_SA(1, 1), a1 + hstepA, voffA);
;             PG8_WAIT_V(8); PG8_WAIT_L(0); PG8_BAR; PG8_MMA(0, 0, At, B0); PG8_MMA(0, 1, At, B1); PG8_BAR; PG8_SCHED;
;             PG8_LDA(At, 0, 1); PG8_STAGE(PG8_SB(0, 0), b2, voffB); PG8_STAGE(PG8_SB(0, 1), b2 + hstepB, voffB); PG8_STAGE(PG8_SA(0, 0), a2, voffA);
;             PG8_WAIT_V(8); PG8_WAIT_L(0); PG8_BAR; PG8_MMA(1, 0, At, B0); PG8_MMA(1, 1, At, B1); PG8_BAR; PG8_SCHED;
.LBB0_697:
	s_lshl_b32 s37, s37, 5
	s_add_i32 s66, s43, s35
	s_and_b32 s37, s37, 0x60
	v_lshl_add_u64 v[16:17], v[0:1], 0, s[30:31]
	s_mov_b32 m0, s66
	s_add_i32 s68, s66, 0x2000
	s_lshl_b32 s71, s36, 13
	s_lshl_b32 s76, s37, 7
	s_waitcnt vmcnt(2)
	s_barrier
	global_load_lds_dwordx4 v[16:17], off
	v_lshl_add_u64 v[242:243], v[4:5], 0, s[30:31]
	s_mov_b32 m0, s68
	s_add_i32 s67, s34, 0x8000
	s_add_i32 s69, s34, 0xa000
	global_load_lds_dwordx4 v[242:243], off
	v_lshl_add_u64 v[14:15], v[18:19], 0, s[30:31]
	s_mov_b32 m0, s67
	s_add_u32 s74, s16, 0x8080
	global_load_lds_dwordx4 v[14:15], off
	v_lshl_add_u64 v[244:245], v[20:21], 0, s[30:31]
	s_mov_b32 m0, s69
	s_addc_u32 s75, s17, 0
	s_add_i32 s16, s46, s35
	global_load_lds_dwordx4 v[244:245], off
	v_lshl_add_u64 v[246:247], s[74:75], 0, v[140:141]
	s_mov_b32 m0, s16
	s_add_i32 s17, s16, 0x2000
	global_load_lds_dwordx4 v[246:247], off
	v_lshl_add_u64 v[248:249], s[74:75], 0, v[24:25]
	s_mov_b32 m0, s17
	v_and_b32_e32 v140, 15, v156
	global_load_lds_dwordx4 v[248:249], off
	v_and_b32_e32 v24, 48, v156
	v_lshlrev_b32_e32 v25, 2, v156
	v_lshl_or_b32 v24, v140, 6, v24
	v_and_b32_e32 v25, 32, v25
	v_bitop3_b32 v26, v24, s71, v25 bitop3:0xde
	v_bitop3_b32 v56, s76, v24, v25 bitop3:0xf6
	s_add_i32 s71, 0, 0x10000
	s_add_i32 s74, 0, 0x14000
	v_add_u32_e32 v36, s71, v56
	v_add_u32_e32 v52, s74, v56
	s_waitcnt vmcnt(6)
	s_barrier
	v_add_u32_e32 v157, 0, v26
	ds_read_b128 v[24:27], v36
	ds_read_b128 v[28:31], v36 offset:1024
	ds_read_b128 v[32:35], v36 offset:2048
	ds_read_b128 v[36:39], v36 offset:3072
	ds_read_b128 v[40:43], v52
	ds_read_b128 v[44:47], v52 offset:1024
	ds_read_b128 v[48:51], v52 offset:2048
	ds_read_b128 v[52:55], v52 offset:3072
	s_add_u32 s12, s12, 0x40080
	v_add_u32_e32 v206, s43, v56
	v_add_u32_e32 v222, s46, v56
	s_addc_u32 s13, s13, 0
	v_lshl_add_u64 v[8:9], s[12:13], 0, v[8:9]
	s_add_i32 m0, s34, 0xc000
	ds_read_b128 v[56:59], v157
	ds_read_b128 v[60:63], v157 offset:1024
	ds_read_b128 v[64:67], v157 offset:2048
	ds_read_b128 v[68:71], v157 offset:3072
	ds_read_b128 v[72:75], v157 offset:4096
	ds_read_b128 v[76:79], v157 offset:5120
	ds_read_b128 v[80:83], v157 offset:6144
	ds_read_b128 v[84:87], v157 offset:7168
	global_load_lds_dwordx4 v[8:9], off
	v_lshl_add_u64 v[8:9], s[12:13], 0, v[22:23]
	s_add_i32 m0, s34, 0xe000
	s_nop 0
	global_load_lds_dwordx4 v[8:9], off
	s_waitcnt vmcnt(8) lgkmcnt(0)
	s_barrier
	s_setprio 1
	s_waitcnt lgkmcnt(0)
	v_mfma_f32_16x16x32_bf16 v[112:115], v[24:27], v[80:83], 0
	v_mfma_f32_16x16x32_bf16 v[88:91], v[24:27], v[56:59], 0
	v_mfma_f32_16x16x32_bf16 v[92:95], v[32:35], v[56:59], 0
	v_mfma_f32_16x16x32_bf16 v[96:99], v[24:27], v[64:67], 0
	v_mfma_f32_16x16x32_bf16 v[100:103], v[32:35], v[64:67], 0
	v_mfma_f32_16x16x32_bf16 v[116:119], v[28:31], v[84:87], v[112:115]
	v_mfma_f32_16x16x32_bf16 v[112:115], v[32:35], v[80:83], 0
	v_mfma_f32_16x16x32_bf16 v[88:91], v[28:31], v[60:63], v[88:91]
	v_mfma_f32_16x16x32_bf16 v[92:95], v[36:39], v[60:63], v[92:95]
	v_mfma_f32_16x16x32_bf16 v[96:99], v[28:31], v[68:71], v[96:99]
	v_mfma_f32_16x16x32_bf16 v[100:103], v[36:39], v[68:71], v[100:103]
	v_mfma_f32_16x16x32_bf16 v[104:107], v[24:27], v[72:75], 0
	v_mfma_f32_16x16x32_bf16 v[108:111], v[32:35], v[72:75], 0
	v_mfma_f32_16x16x32_bf16 v[124:127], v[36:39], v[84:87], v[112:115]
	v_mfma_f32_16x16x32_bf16 v[104:107], v[28:31], v[76:79], v[104:107]
	v_mfma_f32_16x16x32_bf16 v[108:111], v[36:39], v[76:79], v[108:111]
	s_setprio 0
	s_setprio 1
	v_mfma_f32_16x16x32_bf16 v[112:115], v[40:43], v[56:59], 0
	v_mfma_f32_16x16x32_bf16 v[56:59], v[48:51], v[56:59], 0
	v_mfma_f32_16x16x32_bf16 v[132:135], v[44:47], v[60:63], v[112:115]
	v_mfma_f32_16x16x32_bf16 v[56:59], v[52:55], v[60:63], v[56:59]
	v_mfma_f32_16x16x32_bf16 v[60:63], v[40:43], v[64:67], 0
	v_mfma_f32_16x16x32_bf16 v[64:67], v[48:51], v[64:67], 0
	v_mfma_f32_16x16x32_bf16 v[60:63], v[44:47], v[68:71], v[60:63]
	v_mfma_f32_16x16x32_bf16 v[68:71], v[52:55], v[68:71], v[64:67]
	v_mfma_f32_16x16x32_bf16 v[64:67], v[40:43], v[72:75], 0
	v_mfma_f32_16x16x32_bf16 v[136:139], v[44:47], v[76:79], v[64:67]
	v_mfma_f32_16x16x32_bf16 v[64:67], v[48:51], v[72:75], 0
	v_mfma_f32_16x16x32_bf16 v[76:79], v[52:55], v[76:79], v[64:67]
	v_mfma_f32_16x16x32_bf16 v[64:67], v[40:43], v[80:83], 0
	v_mfma_f32_16x16x32_bf16 v[142:145], v[44:47], v[84:87], v[64:67]
	v_mfma_f32_16x16x32_bf16 v[64:67], v[48:51], v[80:83], 0
	v_mfma_f32_16x16x32_bf16 v[146:149], v[52:55], v[84:87], v[64:67]
	s_setprio 0
	s_barrier
	s_add_i32 s12, s71, s35
	s_mov_b32 m0, s12
	s_nop 2
	ds_read_b128 v[64:67], v157 offset:16384
	ds_read_b128 v[72:75], v157 offset:17408
	ds_read_b128 v[80:83], v157 offset:18432
	ds_read_b128 v[84:87], v157 offset:19456
	ds_read_b128 v[112:115], v157 offset:20480
	ds_read_b128 v[120:123], v157 offset:21504
	ds_read_b128 v[128:131], v157 offset:22528
	ds_read_b128 v[158:161], v157 offset:23552
	global_load_lds_dwordx4 v[0:1], off
	s_add_i32 m0, s12, 0x2000
	s_add_i32 s12, s74, s35
	global_load_lds_dwordx4 v[4:5], off
	s_mov_b32 m0, s12
	s_nop 0
	global_load_lds_dwordx4 v[10:11], off
	s_add_i32 m0, s12, 0x2000
	s_nop 0
	global_load_lds_dwordx4 v[12:13], off
	s_mov_b32 m0, s34
	s_nop 0
	global_load_lds_dwordx4 v[18:19], off
	s_mov_b32 m0, s70
	s_nop 0
	global_load_lds_dwordx4 v[20:21], off
	s_waitcnt vmcnt(8) lgkmcnt(0)
	s_barrier
; #define PG8_STAGE(bufoff, gbase, voff) do { _Pragma("unroll") for (int _i = 0; _i < 2; ++_i) \
;         __builtin_amdgcn_global_load_lds((const unsigned*)((const char*)(gbase) + (voff)[_i]), (PG8_LAS unsigned*)(lds + (bufoff) + ldsw + _i * 8192), 16, 0, 0); } while (0)
; #define PG8_LDA(dst, b, h) do { _Pragma("unroll") for (int m = 0; m < 4; ++m) _Pragma("unroll") for (int k = 0; k < 2; ++k) dst[m][k] = *(const PG8_LAS bf16x8*)(lds + PG8_SA(b, h) + aoff + m * 2048 + k * 1024); } while (0)
; #define PG8_LDB(dst, b, h) do { _Pragma("unroll") for (int n = 0; n < 2; ++n) _Pragma("unroll") for (int k = 0; k < 2; ++k) dst[n][k] = *(const PG8_LAS bf16x8*)(lds + PG8_SB(b, h) + boff + n * 2048 + k * 1024); } while (0)
; #define PG8_MMA(ai, bj, At, Bt) do { __builtin_amdgcn_s_setprio(1); _Pragma("unroll") for (int m = 0; m < 4; ++m) _Pragma("unroll") for (int n = 0; n < 2; ++n) _Pragma("unroll") for (int k = 0; k < 2; ++k) \
;         acc[ai][bj][m][n] = __builtin_amdgcn_mfma_f32_16x16x32_bf16(Bt[n][k], At[m][k], acc[ai][bj][m][n], 0, 0, 0); __builtin_amdgcn_s_setprio(0); } while (0)
; #define PG8_WAIT_V(n) asm volatile("s_waitcnt vmcnt(" #n ")" ::: "memory")
; template <class Epi, class Sched, bool ALIGN_EPI = false, bool SP2 = false>
; __device__ __forceinline__ void gemm_phase(PG8_LAS unsigned char* lds, const Gemm g, const Sched& S, const Epi& E) {
;     ...
;             PG8_LDB(B0, 0, 0); PG8_LDB(B1, 0, 1); PG8_SCHED; PG8_LDA(At, 0, 0); PG8_STAGE(PG8_SA(1, 1), a1 + hstepA, voffA);
;             PG8_WAIT_V(8); PG8_WAIT_L(0); PG8_BAR; PG8_MMA(0, 0, At, B0); PG8_MMA(0, 1, At, B1); PG8_BAR; PG8_SCHED;
;             PG8_LDA(At, 0, 1); PG8_STAGE(PG8_SB(0, 0), b2, voffB); PG8_STAGE(PG8_SB(0, 1), b2 + hstepB, voffB); PG8_STAGE(PG8_SA(0, 0), a2, voffA);
;             PG8_WAIT_V(8); PG8_WAIT_L(0); PG8_BAR; PG8_MMA(1, 0, At, B0); PG8_MMA(1, 1, At, B1); PG8_BAR; PG8_SCHED;
;             PG8_LDB(B0, 1, 0); PG8_LDB(B1, 1, 1); PG8_SCHED; PG8_LDA(At, 1, 0); PG8_STAGE(PG8_SA(0, 1), a2 + hstepA, voffA);
;             PG8_WAIT_V(8); PG8_WAIT_L(0); PG8_BAR; PG8_MMA(0, 0, At, B0); PG8_MMA(0, 1, At, B1); PG8_BAR; PG8_SCHED;
;             PG8_LDA(At, 1, 1); PG8_STAGE(PG8_SB(1, 0), b3, voffB); PG8_STAGE(PG8_SB(1, 1), b3 + hstepB, voffB); PG8_STAGE(PG8_SA(1, 0), a3, voffA);
;             PG8_WAIT_V(8); PG8_WAIT_L(0); PG8_BAR; PG8_MMA(1, 0, At, B0); PG8_MMA(1, 1, At, B1); PG8_BAR; PG8_SCHED;
	s_setprio 1
	s_waitcnt lgkmcnt(0)
	v_mfma_f32_16x16x32_bf16 v[8:11], v[24:27], v[64:67], 0
	v_mfma_f32_16x16x32_bf16 v[162:165], v[24:27], v[80:83], 0
	v_mfma_f32_16x16x32_bf16 v[170:173], v[24:27], v[112:115], 0
	v_mfma_f32_16x16x32_bf16 v[22:25], v[24:27], v[128:131], 0
	v_mfma_f32_16x16x32_bf16 v[8:11], v[28:31], v[72:75], v[8:11]
	v_mfma_f32_16x16x32_bf16 v[18:21], v[32:35], v[64:67], 0
	v_mfma_f32_16x16x32_bf16 v[162:165], v[28:31], v[84:87], v[162:165]
	v_mfma_f32_16x16x32_bf16 v[166:169], v[32:35], v[80:83], 0
	v_mfma_f32_16x16x32_bf16 v[170:173], v[28:31], v[120:123], v[170:173]
	v_mfma_f32_16x16x32_bf16 v[174:177], v[32:35], v[112:115], 0
	v_mfma_f32_16x16x32_bf16 v[28:31], v[28:31], v[158:161], v[22:25]
	v_mfma_f32_16x16x32_bf16 v[22:25], v[32:35], v[128:131], 0
	v_mfma_f32_16x16x32_bf16 v[18:21], v[36:39], v[72:75], v[18:21]
	v_mfma_f32_16x16x32_bf16 v[166:169], v[36:39], v[84:87], v[166:169]
	v_mfma_f32_16x16x32_bf16 v[174:177], v[36:39], v[120:123], v[174:177]
	v_mfma_f32_16x16x32_bf16 v[36:39], v[36:39], v[158:161], v[22:25]
	s_setprio 0
	s_setprio 1
	v_mfma_f32_16x16x32_bf16 v[22:25], v[40:43], v[64:67], 0
	v_mfma_f32_16x16x32_bf16 v[178:181], v[44:47], v[72:75], v[22:25]
	v_mfma_f32_16x16x32_bf16 v[22:25], v[48:51], v[64:67], 0
	v_mfma_f32_16x16x32_bf16 v[182:185], v[52:55], v[72:75], v[22:25]
	v_mfma_f32_16x16x32_bf16 v[22:25], v[40:43], v[80:83], 0
	v_mfma_f32_16x16x32_bf16 v[186:189], v[44:47], v[84:87], v[22:25]
	v_mfma_f32_16x16x32_bf16 v[22:25], v[48:51], v[80:83], 0
	v_mfma_f32_16x16x32_bf16 v[190:193], v[52:55], v[84:87], v[22:25]
	v_mfma_f32_16x16x32_bf16 v[22:25], v[40:43], v[112:115], 0
	v_mfma_f32_16x16x32_bf16 v[194:197], v[44:47], v[120:123], v[22:25]
	v_mfma_f32_16x16x32_bf16 v[22:25], v[48:51], v[112:115], 0
	v_mfma_f32_16x16x32_bf16 v[198:201], v[52:55], v[120:123], v[22:25]
	v_mfma_f32_16x16x32_bf16 v[22:25], v[40:43], v[128:131], 0
	v_mfma_f32_16x16x32_bf16 v[202:205], v[44:47], v[158:161], v[22:25]
	v_mfma_f32_16x16x32_bf16 v[22:25], v[48:51], v[128:131], 0
	v_mfma_f32_16x16x32_bf16 v[158:161], v[52:55], v[158:161], v[22:25]
	s_setprio 0
	s_barrier
	ds_read_b128 v[32:35], v206
	ds_read_b128 v[44:47], v206 offset:1024
	ds_read_b128 v[52:55], v206 offset:2048
	ds_read_b128 v[206:209], v206 offset:3072
	ds_read_b128 v[210:213], v222
	ds_read_b128 v[214:217], v222 offset:1024
	ds_read_b128 v[218:221], v222 offset:2048
	ds_read_b128 v[222:225], v222 offset:3072
	s_mov_b32 m0, s39
	ds_read_b128 v[22:25], v157 offset:32768
	ds_read_b128 v[40:43], v157 offset:33792
	ds_read_b128 v[48:51], v157 offset:34816
	ds_read_b128 v[84:87], v157 offset:35840
	ds_read_b128 v[226:229], v157 offset:36864
	ds_read_b128 v[230:233], v157 offset:37888
	ds_read_b128 v[234:237], v157 offset:38912
	ds_read_b128 v[238:241], v157 offset:39936
	global_load_lds_dwordx4 v[2:3], off
	s_mov_b32 m0, s65
	s_nop 0
	global_load_lds_dwordx4 v[6:7], off
	s_waitcnt vmcnt(8) lgkmcnt(0)
	s_barrier
	s_setprio 1
	s_waitcnt lgkmcnt(0)
	v_mfma_f32_16x16x32_bf16 v[0:3], v[32:35], v[22:25], v[88:91]
	v_mfma_f32_16x16x32_bf16 v[128:131], v[44:47], v[40:43], v[0:3]
	v_mfma_f32_16x16x32_bf16 v[0:3], v[52:55], v[22:25], v[92:95]
	v_mfma_f32_16x16x32_bf16 v[88:91], v[206:209], v[40:43], v[0:3]
	v_mfma_f32_16x16x32_bf16 v[0:3], v[32:35], v[48:51], v[96:99]
	v_mfma_f32_16x16x32_bf16 v[120:123], v[44:47], v[84:87], v[0:3]
	v_mfma_f32_16x16x32_bf16 v[0:3], v[52:55], v[48:51], v[100:103]
	v_mfma_f32_16x16x32_bf16 v[80:83], v[206:209], v[84:87], v[0:3]
	v_mfma_f32_16x16x32_bf16 v[0:3], v[32:35], v[226:229], v[104:107]
	v_mfma_f32_16x16x32_bf16 v[112:115], v[44:47], v[230:233], v[0:3]
	v_mfma_f32_16x16x32_bf16 v[0:3], v[52:55], v[226:229], v[108:111]
	v_mfma_f32_16x16x32_bf16 v[72:75], v[206:209], v[230:233], v[0:3]
	v_mfma_f32_16x16x32_bf16 v[0:3], v[32:35], v[234:237], v[116:119]
	v_mfma_f32_16x16x32_bf16 v[96:99], v[44:47], v[238:241], v[0:3]
	v_mfma_f32_16x16x32_bf16 v[0:3], v[52:55], v[234:237], v[124:127]
	v_mfma_f32_16x16x32_bf16 v[64:67], v[206:209], v[238:241], v[0:3]
	s_setprio 0
	s_setprio 1
	v_mfma_f32_16x16x32_bf16 v[0:3], v[210:213], v[22:25], v[132:135]
	v_mfma_f32_16x16x32_bf16 v[132:135], v[214:217], v[40:43], v[0:3]
	v_mfma_f32_16x16x32_bf16 v[0:3], v[218:221], v[22:25], v[56:59]
	v_mfma_f32_16x16x32_bf16 v[92:95], v[222:225], v[40:43], v[0:3]
	v_mfma_f32_16x16x32_bf16 v[0:3], v[210:213], v[48:51], v[60:63]
	v_mfma_f32_16x16x32_bf16 v[124:127], v[214:217], v[84:87], v[0:3]
	v_mfma_f32_16x16x32_bf16 v[0:3], v[218:221], v[48:51], v[68:71]
	v_mfma_f32_16x16x32_bf16 v[84:87], v[222:225], v[84:87], v[0:3]
	v_mfma_f32_16x16x32_bf16 v[0:3], v[210:213], v[226:229], v[136:139]
	v_mfma_f32_16x16x32_bf16 v[116:119], v[214:217], v[230:233], v[0:3]
	v_mfma_f32_16x16x32_bf16 v[0:3], v[218:221], v[226:229], v[76:79]
	v_mfma_f32_16x16x32_bf16 v[76:79], v[222:225], v[230:233], v[0:3]
	v_mfma_f32_16x16x32_bf16 v[0:3], v[210:213], v[234:237], v[142:145]
	v_mfma_f32_16x16x32_bf16 v[100:103], v[214:217], v[238:241], v[0:3]
	v_mfma_f32_16x16x32_bf16 v[0:3], v[218:221], v[234:237], v[146:149]
	v_mfma_f32_16x16x32_bf16 v[68:71], v[222:225], v[238:241], v[0:3]
	s_setprio 0
	s_barrier
; #define PG8_STAGE(bufoff, gbase, voff) do { _Pragma("unroll") for (int _i = 0; _i < 2; ++_i) \
;         __builtin_amdgcn_global_load_lds((const unsigned*)((const char*)(gbase) + (voff)[_i]), (PG8_LAS unsigned*)(lds + (bufoff) + ldsw + _i * 8192), 16, 0, 0); } while (0)
; #define PG8_LDA(dst, b, h) do { _Pragma("unroll") for (int m = 0; m < 4; ++m) _Pragma("unroll") for (int k = 0; k < 2; ++k) dst[m][k] = *(const PG8_LAS bf16x8*)(lds + PG8_SA(b, h) + aoff + m * 2048 + k * 1024); } while (0)
; #define PG8_MMA(ai, bj, At, Bt) do { __builtin_amdgcn_s_setprio(1); _Pragma("unroll") for (int m = 0; m < 4; ++m) _Pragma("unroll") for (int n = 0; n < 2; ++n) _Pragma("unroll") for (int k = 0; k < 2; ++k) \
;         acc[ai][bj][m][n] = __builtin_amdgcn_mfma_f32_16x16x32_bf16(Bt[n][k], At[m][k], acc[ai][bj][m][n], 0, 0, 0); __builtin_amdgcn_s_setprio(0); } while (0)
; #define PG8_WAIT_V(n) asm volatile("s_waitcnt vmcnt(" #n ")" ::: "memory")
; #define PG8_WAIT_L(n) asm volatile("s_waitcnt lgkmcnt(" #n ")" ::: "memory")
; #define PG8_BAR __builtin_amdgcn_s_barrier()
; #define PG8_SCHED __builtin_amdgcn_sched_barrier(0)
; template <class Epi, class Sched, bool ALIGN_EPI = false, bool SP2 = false>
; __device__ __forceinline__ void gemm_phase(PG8_LAS unsigned char* lds, const Gemm g, const Sched& S, const Epi& E) {
;     ...
;             PG8_LDA(At, 1, 1); PG8_STAGE(PG8_SB(1, 0), b3, voffB); PG8_STAGE(PG8_SB(1, 1), b3 + hstepB, voffB); PG8_STAGE(PG8_SA(1, 0), a3, voffA);
;             PG8_WAIT_V(8); PG8_WAIT_L(0); PG8_BAR; PG8_MMA(1, 0, At, B0); PG8_MMA(1, 1, At, B1); PG8_BAR; PG8_SCHED;
;     ...
;     PG8_WAIT_V(0);
;     if constexpr (!ALIGN_EPI) { if (wr == 0) PG8_BAR; }
	s_mov_b32 m0, s66
	ds_read_b128 v[4:7], v157 offset:49152
	ds_read_b128 v[104:107], v157 offset:50176
	ds_read_b128 v[108:111], v157 offset:51200
	ds_read_b128 v[136:139], v157 offset:52224
	ds_read_b128 v[142:145], v157 offset:53248
	ds_read_b128 v[146:149], v157 offset:54272
	ds_read_b128 v[226:229], v157 offset:55296
	ds_read_b128 v[230:233], v157 offset:56320
	global_load_lds_dwordx4 v[16:17], off
	s_mov_b32 m0, s68
	s_nop 0
	global_load_lds_dwordx4 v[242:243], off
	s_mov_b32 m0, s16
	s_nop 0
	global_load_lds_dwordx4 v[246:247], off
	s_mov_b32 m0, s17
	s_nop 0
	global_load_lds_dwordx4 v[248:249], off
	s_mov_b32 m0, s67
	s_nop 0
	global_load_lds_dwordx4 v[14:15], off
	s_mov_b32 m0, s69
	s_nop 0
	global_load_lds_dwordx4 v[244:245], off
	s_waitcnt vmcnt(8) lgkmcnt(0)
	s_barrier
	s_setprio 1
	s_waitcnt lgkmcnt(0)
	v_mfma_f32_16x16x32_bf16 v[0:3], v[32:35], v[4:7], v[8:11]
	v_mfma_f32_16x16x32_bf16 v[56:59], v[44:47], v[104:107], v[0:3]
	v_mfma_f32_16x16x32_bf16 v[0:3], v[52:55], v[4:7], v[18:21]
	v_mfma_f32_16x16x32_bf16 v[24:27], v[206:209], v[104:107], v[0:3]
	v_mfma_f32_16x16x32_bf16 v[0:3], v[32:35], v[108:111], v[162:165]
	v_mfma_f32_16x16x32_bf16 v[48:51], v[44:47], v[136:139], v[0:3]
	v_mfma_f32_16x16x32_bf16 v[0:3], v[52:55], v[108:111], v[166:169]
	v_mfma_f32_16x16x32_bf16 v[16:19], v[206:209], v[136:139], v[0:3]
	v_mfma_f32_16x16x32_bf16 v[0:3], v[32:35], v[142:145], v[170:173]
	v_mfma_f32_16x16x32_bf16 v[40:43], v[44:47], v[146:149], v[0:3]
	v_mfma_f32_16x16x32_bf16 v[0:3], v[52:55], v[142:145], v[174:177]
	v_mfma_f32_16x16x32_bf16 v[8:11], v[206:209], v[146:149], v[0:3]
	v_mfma_f32_16x16x32_bf16 v[0:3], v[32:35], v[226:229], v[28:31]
	v_mfma_f32_16x16x32_bf16 v[32:35], v[44:47], v[230:233], v[0:3]
	v_mfma_f32_16x16x32_bf16 v[0:3], v[52:55], v[226:229], v[36:39]
	v_mfma_f32_16x16x32_bf16 v[0:3], v[206:209], v[230:233], v[0:3]
	s_setprio 0
	s_setprio 1
	v_mfma_f32_16x16x32_bf16 v[12:15], v[210:213], v[4:7], v[178:181]
	v_mfma_f32_16x16x32_bf16 v[4:7], v[218:221], v[4:7], v[182:185]
	v_mfma_f32_16x16x32_bf16 v[28:31], v[222:225], v[104:107], v[4:7]
	v_mfma_f32_16x16x32_bf16 v[4:7], v[210:213], v[108:111], v[186:189]
	v_mfma_f32_16x16x32_bf16 v[52:55], v[214:217], v[136:139], v[4:7]
	v_mfma_f32_16x16x32_bf16 v[4:7], v[218:221], v[108:111], v[190:193]
	v_mfma_f32_16x16x32_bf16 v[20:23], v[222:225], v[136:139], v[4:7]
	v_mfma_f32_16x16x32_bf16 v[4:7], v[210:213], v[142:145], v[194:197]
	v_mfma_f32_16x16x32_bf16 v[44:47], v[214:217], v[146:149], v[4:7]
	v_mfma_f32_16x16x32_bf16 v[4:7], v[218:221], v[142:145], v[198:201]
	v_mfma_f32_16x16x32_bf16 v[60:63], v[214:217], v[104:107], v[12:15]
	v_mfma_f32_16x16x32_bf16 v[12:15], v[222:225], v[146:149], v[4:7]
	v_mfma_f32_16x16x32_bf16 v[4:7], v[210:213], v[226:229], v[202:205]
	v_mfma_f32_16x16x32_bf16 v[36:39], v[214:217], v[230:233], v[4:7]
	v_mfma_f32_16x16x32_bf16 v[4:7], v[218:221], v[226:229], v[158:161]
	v_mfma_f32_16x16x32_bf16 v[4:7], v[222:225], v[230:233], v[4:7]
	s_setprio 0
	s_barrier
	s_waitcnt vmcnt(0)
	s_cmpk_gt_u32 s19, 0xff
	s_cbranch_scc1 .LBB0_699
	s_barrier

; #define PG8_STAGE(bufoff, gbase, voff) do { _Pragma("unroll") for (int _i = 0; _i < 2; ++_i) \
;         __builtin_amdgcn_global_load_lds((const unsigned*)((const char*)(gbase) + (voff)[_i]), (PG8_LAS unsigned*)(lds + (bufoff) + ldsw + _i * 8192), 16, 0, 0); } while (0)
; #define PG8_LDA(dst, b, h) do { _Pragma("unroll") for (int m = 0; m < 4; ++m) _Pragma("unroll") for (int k = 0; k < 2; ++k) dst[m][k] = *(const PG8_LAS bf16x8*)(lds + PG8_SA(b, h) + aoff + m * 2048 + k * 1024); } while (0)
; #define PG8_WAIT_V(n) asm volatile("s_waitcnt vmcnt(" #n ")" ::: "memory")
; #define PG8_BAR __builtin_amdgcn_s_barrier()
; template <class Epi, class Sched, bool ALIGN_EPI = false, bool SP2 = false>
; __device__ __forceinline__ void gemm_phase(PG8_LAS unsigned char* lds, const Gemm g, const Sched& S, const Epi& E) {
;     ...
;         for (int t = 0; t < nt; t += 2) {
;             const bool last = (t == nt - 2);
;             if constexpr (Epi::HAS_MID) { if (t == E.mid_t) E.mid(acc, cur, wr, wc, fr, fq); }
;             const char* a1 = cA + (size_t)(t + 1) * kstep;
;             const char* a2 = last ? nA : cA + (size_t)(t + 2) * kstep; const char* b2 = last ? nB : cB + (size_t)(t + 2) * kstep;
;             const char* a3 = a2 + kstep; const char* b3 = b2 + kstep;
;             if (last && has_next) S.a_ready(nxt);
;             if constexpr (SP2) {
;             PG8_LDB(B0, 0, 0); PG8_LDB(B1, 0, 1); PG8_SCHED; PG8_LDA(At, 0, 0); PG8_STAGE(PG8_SA(1, 1), a1 + hstepA, voffA);
;             PG8_WAIT_V(8); PG8_WAIT_L(0); PG8_BAR; PG8_MMA(0, 0, At, B0); PG8_MMA(0, 1, At, B1); PG8_BAR; PG8_SCHED;
;             PG8_LDA(At, 0, 1); PG8_STAGE(PG8_SB(0, 0), b2, voffB); PG8_STAGE(PG8_SB(0, 1), b2 + hstepB, voffB); PG8_STAGE(PG8_SA(0, 0), a2, voffA);
;             PG8_WAIT_V(8); PG8_WAIT_L(0); PG8_BAR; PG8_MMA(1, 0, At, B0); PG8_MMA(1, 1, At, B1); PG8_BAR; PG8_SCHED;
;             PG8_LDB(B0, 1, 0); PG8_LDB(B1, 1, 1); PG8_SCHED; PG8_LDA(At, 1, 0); PG8_STAGE(PG8_SA(0, 1), a2 + hstepA, voffA);
;             PG8_WAIT_V(8); PG8_WAIT_L(0); PG8_BAR; PG8_MMA(0, 0, At, B0); PG8_MMA(0, 1, At, B1); PG8_BAR; PG8_SCHED;
;             PG8_LDA(At, 1, 1); PG8_STAGE(PG8_SB(1, 0), b3, voffB); PG8_STAGE(PG8_SB(1, 1), b3 + hstepB, voffB); PG8_STAGE(PG8_SA(1, 0), a3, voffA);
;             PG8_WAIT_V(8); PG8_WAIT_L(0); PG8_BAR; PG8_MMA(1, 0, At, B0); PG8_MMA(1, 1, At, B1); PG8_BAR; PG8_SCHED;
.LBB0_1217:
	v_add_u32_e32 v1, s57, v154
	ds_read_b128 v[158:161], v1
	ds_read_b128 v[162:165], v1 offset:1024
	ds_read_b128 v[166:169], v1 offset:2048
	ds_read_b128 v[170:173], v1 offset:3072
	v_add_u32_e32 v1, s58, v154
	s_add_u32 s42, s78, s18
	ds_read_b128 v[174:177], v1
	ds_read_b128 v[178:181], v1 offset:1024
	ds_read_b128 v[182:185], v1 offset:2048
	ds_read_b128 v[186:189], v1 offset:3072
	s_addc_u32 s43, s79, s19
	s_add_u32 s42, s42, 0x100
	s_addc_u32 s43, s43, 0
	s_add_u32 s69, s66, s18
	s_addc_u32 s70, s67, s19
	s_cmpk_eq_i32 s18, 0xf00
	s_cselect_b32 s43, s62, s43
	s_cselect_b32 s42, s63, s42
	s_cselect_b32 vcc_hi, s51, s70
	s_cselect_b32 vcc_lo, s65, s69
	v_lshl_add_u64 v[2:3], v[148:149], 0, s[18:19]
	s_add_i32 m0, s5, 0xc000
	ds_read_b128 v[190:193], v156
	ds_read_b128 v[194:197], v156 offset:1024
	ds_read_b128 v[198:201], v156 offset:2048
	ds_read_b128 v[202:205], v156 offset:3072
	ds_read_b128 v[206:209], v156 offset:4096
	ds_read_b128 v[210:213], v156 offset:5120
	ds_read_b128 v[214:217], v156 offset:6144
	ds_read_b128 v[218:221], v156 offset:7168
	s_add_u32 s98, s78, s18
	s_addc_u32 s99, s79, s19
	s_add_u32 s98, s98, 0x80
	s_addc_u32 s99, s99, 0
	s_mov_b32 m0, s47
	s_nop 0
	global_load_lds_dwordx4 v132, s[98:99]
	s_mov_b32 m0, s56
	s_nop 0
	global_load_lds_dwordx4 v136, s[98:99]
	s_add_i32 m0, s5, 0xc000
	s_nop 0
	global_load_lds_dwordx4 v[2:3], off
	v_lshl_add_u64 v[2:3], v[150:151], 0, s[18:19]
	s_add_i32 m0, s5, 0xe000
	s_nop 0
	global_load_lds_dwordx4 v[2:3], off
	s_waitcnt vmcnt(8) lgkmcnt(0)
	s_barrier
	s_setprio 1
	v_mfma_f32_16x16x32_bf16 v[128:131], v[158:161], v[190:193], v[128:131]
	v_mfma_f32_16x16x32_bf16 v[124:127], v[166:169], v[190:193], v[124:127]
	v_mfma_f32_16x16x32_bf16 v[112:115], v[158:161], v[198:201], v[112:115]
	v_mfma_f32_16x16x32_bf16 v[108:111], v[166:169], v[198:201], v[108:111]
	v_mfma_f32_16x16x32_bf16 v[96:99], v[158:161], v[206:209], v[96:99]
	v_mfma_f32_16x16x32_bf16 v[92:95], v[166:169], v[206:209], v[92:95]
	v_mfma_f32_16x16x32_bf16 v[80:83], v[158:161], v[214:217], v[80:83]
	v_mfma_f32_16x16x32_bf16 v[76:79], v[166:169], v[214:217], v[76:79]
	v_mfma_f32_16x16x32_bf16 v[128:131], v[162:165], v[194:197], v[128:131]
	v_mfma_f32_16x16x32_bf16 v[124:127], v[170:173], v[194:197], v[124:127]
	v_mfma_f32_16x16x32_bf16 v[112:115], v[162:165], v[202:205], v[112:115]
	v_mfma_f32_16x16x32_bf16 v[108:111], v[170:173], v[202:205], v[108:111]
	v_mfma_f32_16x16x32_bf16 v[96:99], v[162:165], v[210:213], v[96:99]
	v_mfma_f32_16x16x32_bf16 v[92:95], v[170:173], v[210:213], v[92:95]
	v_mfma_f32_16x16x32_bf16 v[80:83], v[162:165], v[218:221], v[80:83]
	v_mfma_f32_16x16x32_bf16 v[76:79], v[170:173], v[218:221], v[76:79]
	s_setprio 0
	s_setprio 1
	v_mfma_f32_16x16x32_bf16 v[120:123], v[174:177], v[190:193], v[120:123]
	v_mfma_f32_16x16x32_bf16 v[116:119], v[182:185], v[190:193], v[116:119]
	v_mfma_f32_16x16x32_bf16 v[104:107], v[174:177], v[198:201], v[104:107]
	v_mfma_f32_16x16x32_bf16 v[100:103], v[182:185], v[198:201], v[100:103]
	v_mfma_f32_16x16x32_bf16 v[88:91], v[174:177], v[206:209], v[88:91]
	v_mfma_f32_16x16x32_bf16 v[84:87], v[182:185], v[206:209], v[84:87]
	v_mfma_f32_16x16x32_bf16 v[72:75], v[174:177], v[214:217], v[72:75]
	v_mfma_f32_16x16x32_bf16 v[68:71], v[182:185], v[214:217], v[68:71]
	v_mfma_f32_16x16x32_bf16 v[120:123], v[178:181], v[194:197], v[120:123]
	v_mfma_f32_16x16x32_bf16 v[116:119], v[186:189], v[194:197], v[116:119]
	v_mfma_f32_16x16x32_bf16 v[104:107], v[178:181], v[202:205], v[104:107]
	v_mfma_f32_16x16x32_bf16 v[100:103], v[186:189], v[202:205], v[100:103]
	v_mfma_f32_16x16x32_bf16 v[88:91], v[178:181], v[210:213], v[88:91]
	v_mfma_f32_16x16x32_bf16 v[84:87], v[186:189], v[210:213], v[84:87]
	v_mfma_f32_16x16x32_bf16 v[72:75], v[178:181], v[218:221], v[72:75]
	v_mfma_f32_16x16x32_bf16 v[68:71], v[186:189], v[218:221], v[68:71]
	s_setprio 0
	s_barrier
	s_add_i32 s69, s57, s4
	s_mov_b32 m0, s69
	ds_read_b128 v[190:193], v156 offset:16384
	ds_read_b128 v[194:197], v156 offset:17408
	ds_read_b128 v[198:201], v156 offset:18432
	ds_read_b128 v[202:205], v156 offset:19456
	ds_read_b128 v[206:209], v156 offset:20480
	ds_read_b128 v[210:213], v156 offset:21504
	ds_read_b128 v[214:217], v156 offset:22528
	ds_read_b128 v[218:221], v156 offset:23552
	global_load_lds_dwordx4 v134, vcc
	s_add_i32 m0, s69, 0x2000
	s_add_u32 s70, vcc_lo, 0x80000
	s_addc_u32 s71, vcc_hi, 0
	s_add_i32 s69, s58, s4
	global_load_lds_dwordx4 v138, vcc
	s_mov_b32 m0, s69
	s_nop 0
	global_load_lds_dwordx4 v134, s[70:71]
	s_add_i32 m0, s69, 0x2000
	s_nop 0
	global_load_lds_dwordx4 v138, s[70:71]
	s_waitcnt vmcnt(6) lgkmcnt(0)
	s_barrier
; #define PG8_STAGE(bufoff, gbase, voff) do { _Pragma("unroll") for (int _i = 0; _i < 2; ++_i) \
;         __builtin_amdgcn_global_load_lds((const unsigned*)((const char*)(gbase) + (voff)[_i]), (PG8_LAS unsigned*)(lds + (bufoff) + ldsw + _i * 8192), 16, 0, 0); } while (0)
; #define PG8_LDA(dst, b, h) do { _Pragma("unroll") for (int m = 0; m < 4; ++m) _Pragma("unroll") for (int k = 0; k < 2; ++k) dst[m][k] = *(const PG8_LAS bf16x8*)(lds + PG8_SA(b, h) + aoff + m * 2048 + k * 1024); } while (0)
; #define PG8_LDB(dst, b, h) do { _Pragma("unroll") for (int n = 0; n < 2; ++n) _Pragma("unroll") for (int k = 0; k < 2; ++k) dst[n][k] = *(const PG8_LAS bf16x8*)(lds + PG8_SB(b, h) + boff + n * 2048 + k * 1024); } while (0)
; #define PG8_MMA(ai, bj, At, Bt) do { __builtin_amdgcn_s_setprio(1); _Pragma("unroll") for (int m = 0; m < 4; ++m) _Pragma("unroll") for (int n = 0; n < 2; ++n) _Pragma("unroll") for (int k = 0; k < 2; ++k) \
;         acc[ai][bj][m][n] = __builtin_amdgcn_mfma_f32_16x16x32_bf16(Bt[n][k], At[m][k], acc[ai][bj][m][n], 0, 0, 0); __builtin_amdgcn_s_setprio(0); } while (0)
; #define PG8_WAIT_V(n) asm volatile("s_waitcnt vmcnt(" #n ")" ::: "memory")
; #define PG8_WAIT_L(n) asm volatile("s_waitcnt lgkmcnt(" #n ")" ::: "memory")
; #define PG8_BAR __builtin_amdgcn_s_barrier()
; #define PG8_SCHED __builtin_amdgcn_sched_barrier(0)
; template <class Epi, class Sched, bool ALIGN_EPI = false, bool SP2 = false>
; __device__ __forceinline__ void gemm_phase(PG8_LAS unsigned char* lds, const Gemm g, const Sched& S, const Epi& E) {
;     ...
;             PG8_LDB(B0, 1, 0); PG8_LDB(B1, 1, 1); PG8_SCHED; PG8_LDA(At, 1, 0); PG8_STAGE(PG8_SA(0, 1), a2 + hstepA, voffA);
;             PG8_WAIT_V(8); PG8_WAIT_L(0); PG8_BAR; PG8_MMA(0, 0, At, B0); PG8_MMA(0, 1, At, B1); PG8_BAR; PG8_SCHED;
;             PG8_LDA(At, 1, 1); PG8_STAGE(PG8_SB(1, 0), b3, voffB); PG8_STAGE(PG8_SB(1, 1), b3 + hstepB, voffB); PG8_STAGE(PG8_SA(1, 0), a3, voffA);
;             PG8_WAIT_V(8); PG8_WAIT_L(0); PG8_BAR; PG8_MMA(1, 0, At, B0); PG8_MMA(1, 1, At, B1); PG8_BAR; PG8_SCHED;
	s_setprio 1
	v_mfma_f32_16x16x32_bf16 v[64:67], v[158:161], v[190:193], v[64:67]
	v_mfma_f32_16x16x32_bf16 v[60:63], v[166:169], v[190:193], v[60:63]
	v_mfma_f32_16x16x32_bf16 v[48:51], v[158:161], v[198:201], v[48:51]
	v_mfma_f32_16x16x32_bf16 v[44:47], v[166:169], v[198:201], v[44:47]
	v_mfma_f32_16x16x32_bf16 v[32:35], v[158:161], v[206:209], v[32:35]
	v_mfma_f32_16x16x32_bf16 v[28:31], v[166:169], v[206:209], v[28:31]
	v_mfma_f32_16x16x32_bf16 v[16:19], v[158:161], v[214:217], v[16:19]
	v_mfma_f32_16x16x32_bf16 v[12:15], v[166:169], v[214:217], v[12:15]
	v_mfma_f32_16x16x32_bf16 v[64:67], v[162:165], v[194:197], v[64:67]
	v_mfma_f32_16x16x32_bf16 v[60:63], v[170:173], v[194:197], v[60:63]
	v_mfma_f32_16x16x32_bf16 v[48:51], v[162:165], v[202:205], v[48:51]
	v_mfma_f32_16x16x32_bf16 v[44:47], v[170:173], v[202:205], v[44:47]
	v_mfma_f32_16x16x32_bf16 v[32:35], v[162:165], v[210:213], v[32:35]
	v_mfma_f32_16x16x32_bf16 v[28:31], v[170:173], v[210:213], v[28:31]
	v_mfma_f32_16x16x32_bf16 v[16:19], v[162:165], v[218:221], v[16:19]
	v_mfma_f32_16x16x32_bf16 v[12:15], v[170:173], v[218:221], v[12:15]
	s_setprio 0
	s_setprio 1
	v_mfma_f32_16x16x32_bf16 v[56:59], v[174:177], v[190:193], v[56:59]
	v_mfma_f32_16x16x32_bf16 v[52:55], v[182:185], v[190:193], v[52:55]
	v_mfma_f32_16x16x32_bf16 v[40:43], v[174:177], v[198:201], v[40:43]
	v_mfma_f32_16x16x32_bf16 v[36:39], v[182:185], v[198:201], v[36:39]
	v_mfma_f32_16x16x32_bf16 v[24:27], v[174:177], v[206:209], v[24:27]
	v_mfma_f32_16x16x32_bf16 v[20:23], v[182:185], v[206:209], v[20:23]
	v_mfma_f32_16x16x32_bf16 v[8:11], v[174:177], v[214:217], v[8:11]
	v_mfma_f32_16x16x32_bf16 v[2:5], v[182:185], v[214:217], v[4:7]
	v_mfma_f32_16x16x32_bf16 v[56:59], v[178:181], v[194:197], v[56:59]
	v_mfma_f32_16x16x32_bf16 v[52:55], v[186:189], v[194:197], v[52:55]
	v_mfma_f32_16x16x32_bf16 v[40:43], v[178:181], v[202:205], v[40:43]
	v_mfma_f32_16x16x32_bf16 v[36:39], v[186:189], v[202:205], v[36:39]
	v_mfma_f32_16x16x32_bf16 v[24:27], v[178:181], v[210:213], v[24:27]
	v_mfma_f32_16x16x32_bf16 v[20:23], v[186:189], v[210:213], v[20:23]
	v_mfma_f32_16x16x32_bf16 v[8:11], v[178:181], v[218:221], v[8:11]
	v_mfma_f32_16x16x32_bf16 v[2:5], v[186:189], v[218:221], v[2:5]
	s_setprio 0
	s_barrier
	s_add_i32 s69, 0, 0x18000
	v_add_u32_e32 v1, s69, v154
	s_add_i32 s70, 0, 0x1c000
	ds_read_b128 v[158:161], v1
	ds_read_b128 v[162:165], v1 offset:1024
	ds_read_b128 v[166:169], v1 offset:2048
	ds_read_b128 v[170:173], v1 offset:3072
	v_add_u32_e32 v1, s70, v154
	ds_read_b128 v[174:177], v1
	ds_read_b128 v[178:181], v1 offset:1024
	ds_read_b128 v[182:185], v1 offset:2048
	ds_read_b128 v[186:189], v1 offset:3072
	s_mov_b64 s[100:101], s[42:43]
	s_add_u32 s42, s42, 0x80000
	s_addc_u32 s43, s43, 0
	s_mov_b32 m0, s7
	ds_read_b128 v[190:193], v156 offset:32768
	ds_read_b128 v[194:197], v156 offset:33792
	ds_read_b128 v[198:201], v156 offset:34816
	ds_read_b128 v[202:205], v156 offset:35840
	ds_read_b128 v[206:209], v156 offset:36864
	ds_read_b128 v[210:213], v156 offset:37888
	ds_read_b128 v[214:217], v156 offset:38912
	ds_read_b128 v[218:221], v156 offset:39936
	s_mov_b32 m0, s5
	s_nop 0
	global_load_lds_dwordx4 v132, s[100:101]
	s_mov_b32 m0, s6
	s_nop 0
	global_load_lds_dwordx4 v136, s[100:101]
	s_mov_b32 m0, s7
	s_nop 0
	global_load_lds_dwordx4 v132, s[42:43]
	s_mov_b32 m0, s33
	s_nop 0
	global_load_lds_dwordx4 v136, s[42:43]
	s_waitcnt vmcnt(8) lgkmcnt(0)
	s_barrier
; #define PG8_STAGE(bufoff, gbase, voff) do { _Pragma("unroll") for (int _i = 0; _i < 2; ++_i) \
;         __builtin_amdgcn_global_load_lds((const unsigned*)((const char*)(gbase) + (voff)[_i]), (PG8_LAS unsigned*)(lds + (bufoff) + ldsw + _i * 8192), 16, 0, 0); } while (0)
; #define PG8_LDA(dst, b, h) do { _Pragma("unroll") for (int m = 0; m < 4; ++m) _Pragma("unroll") for (int k = 0; k < 2; ++k) dst[m][k] = *(const PG8_LAS bf16x8*)(lds + PG8_SA(b, h) + aoff + m * 2048 + k * 1024); } while (0)
; #define PG8_LDB(dst, b, h) do { _Pragma("unroll") for (int n = 0; n < 2; ++n) _Pragma("unroll") for (int k = 0; k < 2; ++k) dst[n][k] = *(const PG8_LAS bf16x8*)(lds + PG8_SB(b, h) + boff + n * 2048 + k * 1024); } while (0)
; #define PG8_MMA(ai, bj, At, Bt) do { __builtin_amdgcn_s_setprio(1); _Pragma("unroll") for (int m = 0; m < 4; ++m) _Pragma("unroll") for (int n = 0; n < 2; ++n) _Pragma("unroll") for (int k = 0; k < 2; ++k) \
;         acc[ai][bj][m][n] = __builtin_amdgcn_mfma_f32_16x16x32_bf16(Bt[n][k], At[m][k], acc[ai][bj][m][n], 0, 0, 0); __builtin_amdgcn_s_setprio(0); } while (0)
; #define PG8_WAIT_V(n) asm volatile("s_waitcnt vmcnt(" #n ")" ::: "memory")
; #define PG8_WAIT_L(n) asm volatile("s_waitcnt lgkmcnt(" #n ")" ::: "memory")
; #define PG8_BAR __builtin_amdgcn_s_barrier()
; #define PG8_SCHED __builtin_amdgcn_sched_barrier(0)
; template <class Epi, class Sched, bool ALIGN_EPI = false, bool SP2 = false>
; __device__ __forceinline__ void gemm_phase(PG8_LAS unsigned char* lds, const Gemm g, const Sched& S, const Epi& E) {
;     ...
;         for (int t = 0; t < nt; t += 2) {
;     ...
;             PG8_LDB(B0, 1, 0); PG8_LDB(B1, 1, 1); PG8_SCHED; PG8_LDA(At, 1, 0); PG8_STAGE(PG8_SA(0, 1), a2 + hstepA, voffA);
;             PG8_WAIT_V(8); PG8_WAIT_L(0); PG8_BAR; PG8_MMA(0, 0, At, B0); PG8_MMA(0, 1, At, B1); PG8_BAR; PG8_SCHED;
;             PG8_LDA(At, 1, 1); PG8_STAGE(PG8_SB(1, 0), b3, voffB); PG8_STAGE(PG8_SB(1, 1), b3 + hstepB, voffB); PG8_STAGE(PG8_SA(1, 0), a3, voffA);
;             PG8_WAIT_V(8); PG8_WAIT_L(0); PG8_BAR; PG8_MMA(1, 0, At, B0); PG8_MMA(1, 1, At, B1); PG8_BAR; PG8_SCHED;
	s_setprio 1
	v_mfma_f32_16x16x32_bf16 v[128:131], v[158:161], v[190:193], v[128:131]
	v_mfma_f32_16x16x32_bf16 v[124:127], v[166:169], v[190:193], v[124:127]
	v_mfma_f32_16x16x32_bf16 v[112:115], v[158:161], v[198:201], v[112:115]
	v_mfma_f32_16x16x32_bf16 v[108:111], v[166:169], v[198:201], v[108:111]
	v_mfma_f32_16x16x32_bf16 v[96:99], v[158:161], v[206:209], v[96:99]
	v_mfma_f32_16x16x32_bf16 v[92:95], v[166:169], v[206:209], v[92:95]
	v_mfma_f32_16x16x32_bf16 v[80:83], v[158:161], v[214:217], v[80:83]
	v_mfma_f32_16x16x32_bf16 v[76:79], v[166:169], v[214:217], v[76:79]
	v_mfma_f32_16x16x32_bf16 v[128:131], v[162:165], v[194:197], v[128:131]
	v_mfma_f32_16x16x32_bf16 v[124:127], v[170:173], v[194:197], v[124:127]
	v_mfma_f32_16x16x32_bf16 v[112:115], v[162:165], v[202:205], v[112:115]
	v_mfma_f32_16x16x32_bf16 v[108:111], v[170:173], v[202:205], v[108:111]
	v_mfma_f32_16x16x32_bf16 v[96:99], v[162:165], v[210:213], v[96:99]
	v_mfma_f32_16x16x32_bf16 v[92:95], v[170:173], v[210:213], v[92:95]
	v_mfma_f32_16x16x32_bf16 v[80:83], v[162:165], v[218:221], v[80:83]
	v_mfma_f32_16x16x32_bf16 v[76:79], v[170:173], v[218:221], v[76:79]
	s_setprio 0
	s_setprio 1
	v_mfma_f32_16x16x32_bf16 v[120:123], v[174:177], v[190:193], v[120:123]
	v_mfma_f32_16x16x32_bf16 v[116:119], v[182:185], v[190:193], v[116:119]
	v_mfma_f32_16x16x32_bf16 v[104:107], v[174:177], v[198:201], v[104:107]
	v_mfma_f32_16x16x32_bf16 v[100:103], v[182:185], v[198:201], v[100:103]
	v_mfma_f32_16x16x32_bf16 v[88:91], v[174:177], v[206:209], v[88:91]
	v_mfma_f32_16x16x32_bf16 v[84:87], v[182:185], v[206:209], v[84:87]
	v_mfma_f32_16x16x32_bf16 v[72:75], v[174:177], v[214:217], v[72:75]
	v_mfma_f32_16x16x32_bf16 v[68:71], v[182:185], v[214:217], v[68:71]
	v_mfma_f32_16x16x32_bf16 v[120:123], v[178:181], v[194:197], v[120:123]
	v_mfma_f32_16x16x32_bf16 v[116:119], v[186:189], v[194:197], v[116:119]
	v_mfma_f32_16x16x32_bf16 v[104:107], v[178:181], v[202:205], v[104:107]
	v_mfma_f32_16x16x32_bf16 v[100:103], v[186:189], v[202:205], v[100:103]
	v_mfma_f32_16x16x32_bf16 v[88:91], v[178:181], v[210:213], v[88:91]
	v_mfma_f32_16x16x32_bf16 v[84:87], v[186:189], v[210:213], v[84:87]
	v_mfma_f32_16x16x32_bf16 v[72:75], v[178:181], v[218:221], v[72:75]
	v_mfma_f32_16x16x32_bf16 v[68:71], v[186:189], v[218:221], v[68:71]
	s_setprio 0
	s_barrier
	s_add_i32 s42, s69, s4
	s_add_u32 s98, vcc_lo, 0x80
	s_addc_u32 s99, vcc_hi, 0
	s_mov_b32 m0, s42
	ds_read_b128 v[190:193], v156 offset:49152
	ds_read_b128 v[194:197], v156 offset:50176
	ds_read_b128 v[198:201], v156 offset:51200
	ds_read_b128 v[202:205], v156 offset:52224
	ds_read_b128 v[206:209], v156 offset:53248
	ds_read_b128 v[210:213], v156 offset:54272
	ds_read_b128 v[214:217], v156 offset:55296
	ds_read_b128 v[218:221], v156 offset:56320
	global_load_lds_dwordx4 v134, s[98:99]
	s_add_i32 m0, s42, 0x2000
	s_add_u32 s42, vcc_lo, 0x80080
	s_addc_u32 s43, vcc_hi, 0
	s_add_i32 s69, s70, s4
	global_load_lds_dwordx4 v138, s[98:99]
	s_mov_b32 m0, s69
	s_nop 0
	global_load_lds_dwordx4 v134, s[42:43]
	s_add_i32 m0, s69, 0x2000
	s_nop 0
	global_load_lds_dwordx4 v138, s[42:43]
	s_waitcnt vmcnt(6) lgkmcnt(0)
	s_barrier
	s_setprio 1
	v_mfma_f32_16x16x32_bf16 v[64:67], v[158:161], v[190:193], v[64:67]
	v_mfma_f32_16x16x32_bf16 v[60:63], v[166:169], v[190:193], v[60:63]
	v_mfma_f32_16x16x32_bf16 v[48:51], v[158:161], v[198:201], v[48:51]
	v_mfma_f32_16x16x32_bf16 v[44:47], v[166:169], v[198:201], v[44:47]
	v_mfma_f32_16x16x32_bf16 v[32:35], v[158:161], v[206:209], v[32:35]
	v_mfma_f32_16x16x32_bf16 v[28:31], v[166:169], v[206:209], v[28:31]
	v_mfma_f32_16x16x32_bf16 v[16:19], v[158:161], v[214:217], v[16:19]
	v_mfma_f32_16x16x32_bf16 v[12:15], v[166:169], v[214:217], v[12:15]
	v_mfma_f32_16x16x32_bf16 v[64:67], v[162:165], v[194:197], v[64:67]
	v_mfma_f32_16x16x32_bf16 v[60:63], v[170:173], v[194:197], v[60:63]
	v_mfma_f32_16x16x32_bf16 v[48:51], v[162:165], v[202:205], v[48:51]
	v_mfma_f32_16x16x32_bf16 v[44:47], v[170:173], v[202:205], v[44:47]
	v_mfma_f32_16x16x32_bf16 v[32:35], v[162:165], v[210:213], v[32:35]
	v_mfma_f32_16x16x32_bf16 v[28:31], v[170:173], v[210:213], v[28:31]
	v_mfma_f32_16x16x32_bf16 v[16:19], v[162:165], v[218:221], v[16:19]
	v_mfma_f32_16x16x32_bf16 v[12:15], v[170:173], v[218:221], v[12:15]
	s_setprio 0
	s_setprio 1
	v_mfma_f32_16x16x32_bf16 v[56:59], v[174:177], v[190:193], v[56:59]
	v_mfma_f32_16x16x32_bf16 v[52:55], v[182:185], v[190:193], v[52:55]
	v_mfma_f32_16x16x32_bf16 v[40:43], v[174:177], v[198:201], v[40:43]
	v_mfma_f32_16x16x32_bf16 v[36:39], v[182:185], v[198:201], v[36:39]
	v_mfma_f32_16x16x32_bf16 v[24:27], v[174:177], v[206:209], v[24:27]
	v_mfma_f32_16x16x32_bf16 v[20:23], v[182:185], v[206:209], v[20:23]
	v_mfma_f32_16x16x32_bf16 v[6:9], v[174:177], v[214:217], v[8:11]
	v_mfma_f32_16x16x32_bf16 v[2:5], v[182:185], v[214:217], v[2:5]
	v_mfma_f32_16x16x32_bf16 v[56:59], v[178:181], v[194:197], v[56:59]
	v_mfma_f32_16x16x32_bf16 v[52:55], v[186:189], v[194:197], v[52:55]
	v_mfma_f32_16x16x32_bf16 v[40:43], v[178:181], v[202:205], v[40:43]
	v_mfma_f32_16x16x32_bf16 v[36:39], v[186:189], v[202:205], v[36:39]
	v_mfma_f32_16x16x32_bf16 v[24:27], v[178:181], v[210:213], v[24:27]
	v_mfma_f32_16x16x32_bf16 v[20:23], v[186:189], v[210:213], v[20:23]
	v_mfma_f32_16x16x32_bf16 v[8:11], v[178:181], v[218:221], v[6:9]
	v_mfma_f32_16x16x32_bf16 v[4:7], v[186:189], v[218:221], v[2:5]
	s_setprio 0
	s_barrier
	s_add_i32 s68, s68, 2
	s_add_u32 s18, s18, 0x100
	s_addc_u32 s19, s19, 0
	s_cmp_gt_u32 s68, 29
	s_cbranch_scc1 .LBB0_1220

; #define PG8_STAGE(bufoff, gbase, voff) do { _Pragma("unroll") for (int _i = 0; _i < 2; ++_i) \
;         __builtin_amdgcn_global_load_lds((const unsigned*)((const char*)(gbase) + (voff)[_i]), (PG8_LAS unsigned*)(lds + (bufoff) + ldsw + _i * 8192), 16, 0, 0); } while (0)
; #define PG8_LDA(dst, b, h) do { _Pragma("unroll") for (int m = 0; m < 4; ++m) _Pragma("unroll") for (int k = 0; k < 2; ++k) dst[m][k] = *(const PG8_LAS bf16x8*)(lds + PG8_SA(b, h) + aoff + m * 2048 + k * 1024); } while (0)
; #define PG8_LDB(dst, b, h) do { _Pragma("unroll") for (int n = 0; n < 2; ++n) _Pragma("unroll") for (int k = 0; k < 2; ++k) dst[n][k] = *(const PG8_LAS bf16x8*)(lds + PG8_SB(b, h) + boff + n * 2048 + k * 1024); } while (0)
; #define PG8_MMA(ai, bj, At, Bt) do { __builtin_amdgcn_s_setprio(1); _Pragma("unroll") for (int m = 0; m < 4; ++m) _Pragma("unroll") for (int n = 0; n < 2; ++n) _Pragma("unroll") for (int k = 0; k < 2; ++k) \
;         acc[ai][bj][m][n] = __builtin_amdgcn_mfma_f32_16x16x32_bf16(Bt[n][k], At[m][k], acc[ai][bj][m][n], 0, 0, 0); __builtin_amdgcn_s_setprio(0); } while (0)
; #define PG8_WAIT_V(n) asm volatile("s_waitcnt vmcnt(" #n ")" ::: "memory")
; #define PG8_WAIT_L(n) asm volatile("s_waitcnt lgkmcnt(" #n ")" ::: "memory")
; #define PG8_BAR __builtin_amdgcn_s_barrier()
; #define PG8_SCHED __builtin_amdgcn_sched_barrier(0)
; template <class Epi, class Sched, bool ALIGN_EPI = false, bool SP2 = false>
; __device__ __forceinline__ void gemm_phase(PG8_LAS unsigned char* lds, const Gemm g, const Sched& S, const Epi& E) {
;     ...
;             PG8_LDB(B0, 0, 0); PG8_LDB(B1, 0, 1); PG8_SCHED; PG8_LDA(At, 0, 0); PG8_STAGE(PG8_SA(1, 1), a1 + hstepA, voffA);
;             PG8_WAIT_V(8); PG8_WAIT_L(0); PG8_BAR; PG8_MMA(0, 0, At, B0); PG8_MMA(0, 1, At, B1); PG8_BAR; PG8_SCHED;
;             PG8_LDA(At, 0, 1); PG8_STAGE(PG8_SB(0, 0), b2, voffB); PG8_STAGE(PG8_SB(0, 1), b2 + hstepB, voffB); PG8_STAGE(PG8_SA(0, 0), a2, voffA);
;             PG8_WAIT_V(8); PG8_WAIT_L(0); PG8_BAR; PG8_MMA(1, 0, At, B0); PG8_MMA(1, 1, At, B1); PG8_BAR; PG8_SCHED;
;             PG8_LDB(B0, 1, 0); PG8_LDB(B1, 1, 1); PG8_SCHED; PG8_LDA(At, 1, 0); PG8_STAGE(PG8_SA(0, 1), a2 + hstepA, voffA);
;             PG8_WAIT_V(8); PG8_WAIT_L(0); PG8_BAR; PG8_MMA(0, 0, At, B0); PG8_MMA(0, 1, At, B1); PG8_BAR; PG8_SCHED;
.LBB0_1309:
	ds_read_b128 v[128:131], v161
	ds_read_b128 v[132:135], v161 offset:1024
	ds_read_b128 v[148:151], v161 offset:2048
	ds_read_b128 v[152:155], v161 offset:3072
	ds_read_b128 v[166:169], v162
	ds_read_b128 v[170:173], v162 offset:1024
	ds_read_b128 v[174:177], v162 offset:2048
	ds_read_b128 v[178:181], v162 offset:3072
	s_add_u32 s16, s12, 0xfff80080
	s_addc_u32 s17, s13, -1
	s_cmp_eq_u32 s65, 28
	s_cselect_b32 s19, s39, s17
	s_cselect_b32 s18, s59, s16
	s_cselect_b32 s17, s37, s63
	s_cselect_b32 s16, s61, s62
	s_add_i32 m0, s5, 0xc000
	ds_read_b128 v[182:185], v163
	ds_read_b128 v[186:189], v163 offset:1024
	ds_read_b128 v[190:193], v163 offset:2048
	ds_read_b128 v[194:197], v163 offset:3072
	ds_read_b128 v[198:201], v163 offset:4096
	ds_read_b128 v[202:205], v163 offset:5120
	ds_read_b128 v[206:209], v163 offset:6144
	ds_read_b128 v[210:213], v163 offset:7168
	s_add_u32 s98, s12, 0xfff80000
	s_addc_u32 s99, s13, -1
	s_mov_b32 m0, s33
	s_nop 0
	global_load_lds_dwordx4 v136, s[98:99]
	s_mov_b32 m0, s34
	s_nop 0
	global_load_lds_dwordx4 v140, s[98:99]
	s_add_i32 m0, s5, 0xc000
	s_nop 0
	global_load_lds_dwordx4 v144, s[12:13]
	s_add_i32 m0, s5, 0xe000
	s_nop 0
	global_load_lds_dwordx4 v146, s[12:13]
	s_waitcnt vmcnt(8) lgkmcnt(0)
	s_barrier
	s_setprio 1
	v_mfma_f32_16x16x32_bf16 v[124:127], v[128:131], v[182:185], v[124:127]
	v_mfma_f32_16x16x32_bf16 v[120:123], v[148:151], v[182:185], v[120:123]
	v_mfma_f32_16x16x32_bf16 v[108:111], v[128:131], v[190:193], v[108:111]
	v_mfma_f32_16x16x32_bf16 v[104:107], v[148:151], v[190:193], v[104:107]
	v_mfma_f32_16x16x32_bf16 v[92:95], v[128:131], v[198:201], v[92:95]
	v_mfma_f32_16x16x32_bf16 v[88:91], v[148:151], v[198:201], v[88:91]
	v_mfma_f32_16x16x32_bf16 v[76:79], v[128:131], v[206:209], v[76:79]
	v_mfma_f32_16x16x32_bf16 v[72:75], v[148:151], v[206:209], v[72:75]
	v_mfma_f32_16x16x32_bf16 v[124:127], v[132:135], v[186:189], v[124:127]
	v_mfma_f32_16x16x32_bf16 v[120:123], v[152:155], v[186:189], v[120:123]
	v_mfma_f32_16x16x32_bf16 v[108:111], v[132:135], v[194:197], v[108:111]
	v_mfma_f32_16x16x32_bf16 v[104:107], v[152:155], v[194:197], v[104:107]
	v_mfma_f32_16x16x32_bf16 v[92:95], v[132:135], v[202:205], v[92:95]
	v_mfma_f32_16x16x32_bf16 v[88:91], v[152:155], v[202:205], v[88:91]
	v_mfma_f32_16x16x32_bf16 v[76:79], v[132:135], v[210:213], v[76:79]
	v_mfma_f32_16x16x32_bf16 v[72:75], v[152:155], v[210:213], v[72:75]
	s_setprio 0
	s_setprio 1
	v_mfma_f32_16x16x32_bf16 v[116:119], v[166:169], v[182:185], v[116:119]
	v_mfma_f32_16x16x32_bf16 v[112:115], v[174:177], v[182:185], v[112:115]
	v_mfma_f32_16x16x32_bf16 v[100:103], v[166:169], v[190:193], v[100:103]
	v_mfma_f32_16x16x32_bf16 v[96:99], v[174:177], v[190:193], v[96:99]
	v_mfma_f32_16x16x32_bf16 v[84:87], v[166:169], v[198:201], v[84:87]
	v_mfma_f32_16x16x32_bf16 v[80:83], v[174:177], v[198:201], v[80:83]
	v_mfma_f32_16x16x32_bf16 v[68:71], v[166:169], v[206:209], v[68:71]
	v_mfma_f32_16x16x32_bf16 v[64:67], v[174:177], v[206:209], v[64:67]
	v_mfma_f32_16x16x32_bf16 v[116:119], v[170:173], v[186:189], v[116:119]
	v_mfma_f32_16x16x32_bf16 v[112:115], v[178:181], v[186:189], v[112:115]
	v_mfma_f32_16x16x32_bf16 v[100:103], v[170:173], v[194:197], v[100:103]
	v_mfma_f32_16x16x32_bf16 v[96:99], v[178:181], v[194:197], v[96:99]
	v_mfma_f32_16x16x32_bf16 v[84:87], v[170:173], v[202:205], v[84:87]
	v_mfma_f32_16x16x32_bf16 v[80:83], v[178:181], v[202:205], v[80:83]
	v_mfma_f32_16x16x32_bf16 v[68:71], v[170:173], v[210:213], v[68:71]
	v_mfma_f32_16x16x32_bf16 v[64:67], v[178:181], v[210:213], v[64:67]
	s_setprio 0
	s_barrier
	s_add_i32 s66, s56, s4
	s_mov_b32 m0, s66
	ds_read_b128 v[182:185], v163 offset:16384
	ds_read_b128 v[186:189], v163 offset:17408
	ds_read_b128 v[190:193], v163 offset:18432
	ds_read_b128 v[194:197], v163 offset:19456
	ds_read_b128 v[198:201], v163 offset:20480
	ds_read_b128 v[202:205], v163 offset:21504
	ds_read_b128 v[206:209], v163 offset:22528
	ds_read_b128 v[210:213], v163 offset:23552
	global_load_lds_dwordx4 v138, s[16:17]
	s_add_i32 m0, s66, 0x2000
	s_add_u32 s66, s16, 0x80000
	s_addc_u32 s67, s17, 0
	s_add_i32 s68, s57, s4
	global_load_lds_dwordx4 v142, s[16:17]
	s_mov_b32 m0, s68
	s_nop 0
	global_load_lds_dwordx4 v138, s[66:67]
	s_add_i32 m0, s68, 0x2000
	s_nop 0
	global_load_lds_dwordx4 v142, s[66:67]
	s_waitcnt vmcnt(6) lgkmcnt(0)
	s_barrier
	s_setprio 1
	v_mfma_f32_16x16x32_bf16 v[60:63], v[128:131], v[182:185], v[60:63]
	v_mfma_f32_16x16x32_bf16 v[56:59], v[148:151], v[182:185], v[56:59]
	v_mfma_f32_16x16x32_bf16 v[44:47], v[128:131], v[190:193], v[44:47]
	v_mfma_f32_16x16x32_bf16 v[40:43], v[148:151], v[190:193], v[40:43]
	v_mfma_f32_16x16x32_bf16 v[28:31], v[128:131], v[198:201], v[28:31]
	v_mfma_f32_16x16x32_bf16 v[24:27], v[148:151], v[198:201], v[24:27]
	v_mfma_f32_16x16x32_bf16 v[12:15], v[128:131], v[206:209], v[12:15]
	v_mfma_f32_16x16x32_bf16 v[8:11], v[148:151], v[206:209], v[8:11]
	v_mfma_f32_16x16x32_bf16 v[60:63], v[132:135], v[186:189], v[60:63]
	v_mfma_f32_16x16x32_bf16 v[56:59], v[152:155], v[186:189], v[56:59]
	v_mfma_f32_16x16x32_bf16 v[44:47], v[132:135], v[194:197], v[44:47]
	v_mfma_f32_16x16x32_bf16 v[40:43], v[152:155], v[194:197], v[40:43]
	v_mfma_f32_16x16x32_bf16 v[28:31], v[132:135], v[202:205], v[28:31]
	v_mfma_f32_16x16x32_bf16 v[24:27], v[152:155], v[202:205], v[24:27]
	v_mfma_f32_16x16x32_bf16 v[12:15], v[132:135], v[210:213], v[12:15]
	v_mfma_f32_16x16x32_bf16 v[8:11], v[152:155], v[210:213], v[8:11]
	s_setprio 0
	s_setprio 1
	v_mfma_f32_16x16x32_bf16 v[52:55], v[166:169], v[182:185], v[52:55]
	v_mfma_f32_16x16x32_bf16 v[48:51], v[174:177], v[182:185], v[48:51]
	v_mfma_f32_16x16x32_bf16 v[36:39], v[166:169], v[190:193], v[36:39]
	v_mfma_f32_16x16x32_bf16 v[32:35], v[174:177], v[190:193], v[32:35]
	v_mfma_f32_16x16x32_bf16 v[20:23], v[166:169], v[198:201], v[20:23]
	v_mfma_f32_16x16x32_bf16 v[16:19], v[174:177], v[198:201], v[16:19]
	v_mfma_f32_16x16x32_bf16 v[4:7], v[166:169], v[206:209], v[4:7]
	v_mfma_f32_16x16x32_bf16 v[0:3], v[174:177], v[206:209], v[0:3]
	v_mfma_f32_16x16x32_bf16 v[52:55], v[170:173], v[186:189], v[52:55]
	v_mfma_f32_16x16x32_bf16 v[48:51], v[178:181], v[186:189], v[48:51]
	v_mfma_f32_16x16x32_bf16 v[36:39], v[170:173], v[194:197], v[36:39]
	v_mfma_f32_16x16x32_bf16 v[32:35], v[178:181], v[194:197], v[32:35]
	v_mfma_f32_16x16x32_bf16 v[20:23], v[170:173], v[202:205], v[20:23]
	v_mfma_f32_16x16x32_bf16 v[16:19], v[178:181], v[202:205], v[16:19]
	v_mfma_f32_16x16x32_bf16 v[4:7], v[170:173], v[210:213], v[4:7]
	v_mfma_f32_16x16x32_bf16 v[0:3], v[178:181], v[210:213], v[0:3]
	s_setprio 0
	s_barrier
; #define PG8_STAGE(bufoff, gbase, voff) do { _Pragma("unroll") for (int _i = 0; _i < 2; ++_i) \
;         __builtin_amdgcn_global_load_lds((const unsigned*)((const char*)(gbase) + (voff)[_i]), (PG8_LAS unsigned*)(lds + (bufoff) + ldsw + _i * 8192), 16, 0, 0); } while (0)
; #define PG8_LDA(dst, b, h) do { _Pragma("unroll") for (int m = 0; m < 4; ++m) _Pragma("unroll") for (int k = 0; k < 2; ++k) dst[m][k] = *(const PG8_LAS bf16x8*)(lds + PG8_SA(b, h) + aoff + m * 2048 + k * 1024); } while (0)
; #define PG8_LDB(dst, b, h) do { _Pragma("unroll") for (int n = 0; n < 2; ++n) _Pragma("unroll") for (int k = 0; k < 2; ++k) dst[n][k] = *(const PG8_LAS bf16x8*)(lds + PG8_SB(b, h) + boff + n * 2048 + k * 1024); } while (0)
; #define PG8_MMA(ai, bj, At, Bt) do { __builtin_amdgcn_s_setprio(1); _Pragma("unroll") for (int m = 0; m < 4; ++m) _Pragma("unroll") for (int n = 0; n < 2; ++n) _Pragma("unroll") for (int k = 0; k < 2; ++k) \
;         acc[ai][bj][m][n] = __builtin_amdgcn_mfma_f32_16x16x32_bf16(Bt[n][k], At[m][k], acc[ai][bj][m][n], 0, 0, 0); __builtin_amdgcn_s_setprio(0); } while (0)
; #define PG8_WAIT_V(n) asm volatile("s_waitcnt vmcnt(" #n ")" ::: "memory")
; #define PG8_WAIT_L(n) asm volatile("s_waitcnt lgkmcnt(" #n ")" ::: "memory")
; #define PG8_BAR __builtin_amdgcn_s_barrier()
; #define PG8_SCHED __builtin_amdgcn_sched_barrier(0)
; template <class Epi, class Sched, bool ALIGN_EPI = false, bool SP2 = false>
; __device__ __forceinline__ void gemm_phase(PG8_LAS unsigned char* lds, const Gemm g, const Sched& S, const Epi& E) {
;     ...
;             PG8_LDB(B0, 1, 0); PG8_LDB(B1, 1, 1); PG8_SCHED; PG8_LDA(At, 1, 0); PG8_STAGE(PG8_SA(0, 1), a2 + hstepA, voffA);
;             PG8_WAIT_V(8); PG8_WAIT_L(0); PG8_BAR; PG8_MMA(0, 0, At, B0); PG8_MMA(0, 1, At, B1); PG8_BAR; PG8_SCHED;
;             PG8_LDA(At, 1, 1); PG8_STAGE(PG8_SB(1, 0), b3, voffB); PG8_STAGE(PG8_SB(1, 1), b3 + hstepB, voffB); PG8_STAGE(PG8_SA(1, 0), a3, voffA);
;             PG8_WAIT_V(8); PG8_WAIT_L(0); PG8_BAR; PG8_MMA(1, 0, At, B0); PG8_MMA(1, 1, At, B1); PG8_BAR; PG8_SCHED;
;     ...
;         if constexpr (ALIGN_EPI) { if (wr == 0) PG8_BAR; }
	s_add_i32 s66, 0, 0x18000
	s_add_i32 s67, 0, 0x1c000
	v_add_u32_e32 v152, s66, v160
	v_add_u32_e32 v165, s67, v160
	ds_read_b128 v[128:131], v152
	ds_read_b128 v[132:135], v152 offset:1024
	ds_read_b128 v[148:151], v152 offset:2048
	ds_read_b128 v[152:155], v152 offset:3072
	ds_read_b128 v[166:169], v165
	ds_read_b128 v[170:173], v165 offset:1024
	ds_read_b128 v[174:177], v165 offset:2048
	ds_read_b128 v[178:181], v165 offset:3072
	s_mov_b64 s[100:101], s[18:19]
	s_add_u32 s18, s18, 0x80000
	s_addc_u32 s19, s19, 0
	s_mov_b32 m0, s7
	ds_read_b128 v[182:185], v163 offset:32768
	ds_read_b128 v[186:189], v163 offset:33792
	ds_read_b128 v[190:193], v163 offset:34816
	ds_read_b128 v[194:197], v163 offset:35840
	ds_read_b128 v[198:201], v163 offset:36864
	ds_read_b128 v[202:205], v163 offset:37888
	ds_read_b128 v[206:209], v163 offset:38912
	ds_read_b128 v[210:213], v163 offset:39936
	s_mov_b32 m0, s5
	s_nop 0
	global_load_lds_dwordx4 v136, s[100:101]
	s_mov_b32 m0, s6
	s_nop 0
	global_load_lds_dwordx4 v140, s[100:101]
	s_mov_b32 m0, s7
	s_nop 0
	global_load_lds_dwordx4 v136, s[18:19]
	s_mov_b32 m0, s20
	s_nop 0
	global_load_lds_dwordx4 v140, s[18:19]
	s_waitcnt vmcnt(8) lgkmcnt(0)
	s_barrier
	s_setprio 1
	v_mfma_f32_16x16x32_bf16 v[124:127], v[128:131], v[182:185], v[124:127]
	v_mfma_f32_16x16x32_bf16 v[120:123], v[148:151], v[182:185], v[120:123]
	v_mfma_f32_16x16x32_bf16 v[108:111], v[128:131], v[190:193], v[108:111]
	v_mfma_f32_16x16x32_bf16 v[104:107], v[148:151], v[190:193], v[104:107]
	v_mfma_f32_16x16x32_bf16 v[92:95], v[128:131], v[198:201], v[92:95]
	v_mfma_f32_16x16x32_bf16 v[88:91], v[148:151], v[198:201], v[88:91]
	v_mfma_f32_16x16x32_bf16 v[76:79], v[128:131], v[206:209], v[76:79]
	v_mfma_f32_16x16x32_bf16 v[72:75], v[148:151], v[206:209], v[72:75]
	v_mfma_f32_16x16x32_bf16 v[124:127], v[132:135], v[186:189], v[124:127]
	v_mfma_f32_16x16x32_bf16 v[120:123], v[152:155], v[186:189], v[120:123]
	v_mfma_f32_16x16x32_bf16 v[108:111], v[132:135], v[194:197], v[108:111]
	v_mfma_f32_16x16x32_bf16 v[104:107], v[152:155], v[194:197], v[104:107]
	v_mfma_f32_16x16x32_bf16 v[92:95], v[132:135], v[202:205], v[92:95]
	v_mfma_f32_16x16x32_bf16 v[88:91], v[152:155], v[202:205], v[88:91]
	v_mfma_f32_16x16x32_bf16 v[76:79], v[132:135], v[210:213], v[76:79]
	v_mfma_f32_16x16x32_bf16 v[72:75], v[152:155], v[210:213], v[72:75]
	s_setprio 0
	s_setprio 1
	v_mfma_f32_16x16x32_bf16 v[116:119], v[166:169], v[182:185], v[116:119]
	v_mfma_f32_16x16x32_bf16 v[112:115], v[174:177], v[182:185], v[112:115]
	v_mfma_f32_16x16x32_bf16 v[100:103], v[166:169], v[190:193], v[100:103]
	v_mfma_f32_16x16x32_bf16 v[96:99], v[174:177], v[190:193], v[96:99]
	v_mfma_f32_16x16x32_bf16 v[84:87], v[166:169], v[198:201], v[84:87]
	v_mfma_f32_16x16x32_bf16 v[80:83], v[174:177], v[198:201], v[80:83]
	v_mfma_f32_16x16x32_bf16 v[68:71], v[166:169], v[206:209], v[68:71]
	v_mfma_f32_16x16x32_bf16 v[64:67], v[174:177], v[206:209], v[64:67]
	v_mfma_f32_16x16x32_bf16 v[116:119], v[170:173], v[186:189], v[116:119]
	v_mfma_f32_16x16x32_bf16 v[112:115], v[178:181], v[186:189], v[112:115]
	v_mfma_f32_16x16x32_bf16 v[100:103], v[170:173], v[194:197], v[100:103]
	v_mfma_f32_16x16x32_bf16 v[96:99], v[178:181], v[194:197], v[96:99]
	v_mfma_f32_16x16x32_bf16 v[84:87], v[170:173], v[202:205], v[84:87]
	v_mfma_f32_16x16x32_bf16 v[80:83], v[178:181], v[202:205], v[80:83]
	v_mfma_f32_16x16x32_bf16 v[68:71], v[170:173], v[210:213], v[68:71]
	v_mfma_f32_16x16x32_bf16 v[64:67], v[178:181], v[210:213], v[64:67]
	s_setprio 0
	s_barrier
	s_add_i32 s18, s66, s4
	s_add_u32 s98, s16, 0x80
	s_addc_u32 s99, s17, 0
	s_mov_b32 m0, s18
	ds_read_b128 v[182:185], v163 offset:49152
	ds_read_b128 v[186:189], v163 offset:50176
	ds_read_b128 v[190:193], v163 offset:51200
	ds_read_b128 v[194:197], v163 offset:52224
	ds_read_b128 v[198:201], v163 offset:53248
	ds_read_b128 v[202:205], v163 offset:54272
	ds_read_b128 v[206:209], v163 offset:55296
	ds_read_b128 v[210:213], v163 offset:56320
	global_load_lds_dwordx4 v138, s[98:99]
	s_add_i32 m0, s18, 0x2000
	s_add_u32 s16, s16, 0x80080
	s_addc_u32 s17, s17, 0
	s_add_i32 s18, s67, s4
	global_load_lds_dwordx4 v142, s[98:99]
	s_mov_b32 m0, s18
	s_nop 0
	global_load_lds_dwordx4 v138, s[16:17]
	s_add_i32 m0, s18, 0x2000
	s_nop 0
	global_load_lds_dwordx4 v142, s[16:17]
	s_waitcnt vmcnt(6) lgkmcnt(0)
	s_barrier
	s_setprio 1
	v_mfma_f32_16x16x32_bf16 v[60:63], v[128:131], v[182:185], v[60:63]
	v_mfma_f32_16x16x32_bf16 v[56:59], v[148:151], v[182:185], v[56:59]
	v_mfma_f32_16x16x32_bf16 v[44:47], v[128:131], v[190:193], v[44:47]
	v_mfma_f32_16x16x32_bf16 v[40:43], v[148:151], v[190:193], v[40:43]
	v_mfma_f32_16x16x32_bf16 v[28:31], v[128:131], v[198:201], v[28:31]
	v_mfma_f32_16x16x32_bf16 v[24:27], v[148:151], v[198:201], v[24:27]
	v_mfma_f32_16x16x32_bf16 v[12:15], v[128:131], v[206:209], v[12:15]
	v_mfma_f32_16x16x32_bf16 v[8:11], v[148:151], v[206:209], v[8:11]
	v_mfma_f32_16x16x32_bf16 v[60:63], v[132:135], v[186:189], v[60:63]
	v_mfma_f32_16x16x32_bf16 v[56:59], v[152:155], v[186:189], v[56:59]
	v_mfma_f32_16x16x32_bf16 v[44:47], v[132:135], v[194:197], v[44:47]
	v_mfma_f32_16x16x32_bf16 v[40:43], v[152:155], v[194:197], v[40:43]
	v_mfma_f32_16x16x32_bf16 v[28:31], v[132:135], v[202:205], v[28:31]
	v_mfma_f32_16x16x32_bf16 v[24:27], v[152:155], v[202:205], v[24:27]
	v_mfma_f32_16x16x32_bf16 v[12:15], v[132:135], v[210:213], v[12:15]
	v_mfma_f32_16x16x32_bf16 v[8:11], v[152:155], v[210:213], v[8:11]
	s_setprio 0
	s_setprio 1
	v_mfma_f32_16x16x32_bf16 v[52:55], v[166:169], v[182:185], v[52:55]
	v_mfma_f32_16x16x32_bf16 v[48:51], v[174:177], v[182:185], v[48:51]
	v_mfma_f32_16x16x32_bf16 v[36:39], v[166:169], v[190:193], v[36:39]
	v_mfma_f32_16x16x32_bf16 v[32:35], v[174:177], v[190:193], v[32:35]
	v_mfma_f32_16x16x32_bf16 v[20:23], v[166:169], v[198:201], v[20:23]
	v_mfma_f32_16x16x32_bf16 v[16:19], v[174:177], v[198:201], v[16:19]
	v_mfma_f32_16x16x32_bf16 v[4:7], v[166:169], v[206:209], v[4:7]
	v_mfma_f32_16x16x32_bf16 v[0:3], v[174:177], v[206:209], v[0:3]
	v_mfma_f32_16x16x32_bf16 v[52:55], v[170:173], v[186:189], v[52:55]
	v_mfma_f32_16x16x32_bf16 v[48:51], v[178:181], v[186:189], v[48:51]
	v_mfma_f32_16x16x32_bf16 v[36:39], v[170:173], v[194:197], v[36:39]
	v_mfma_f32_16x16x32_bf16 v[32:35], v[178:181], v[194:197], v[32:35]
	v_mfma_f32_16x16x32_bf16 v[20:23], v[170:173], v[202:205], v[20:23]
	v_mfma_f32_16x16x32_bf16 v[16:19], v[178:181], v[202:205], v[16:19]
	v_mfma_f32_16x16x32_bf16 v[4:7], v[170:173], v[210:213], v[4:7]
	v_mfma_f32_16x16x32_bf16 v[0:3], v[178:181], v[210:213], v[0:3]
	s_setprio 0
	s_barrier
	s_add_i32 s65, s65, 2
	s_add_u32 s12, s12, 0x100
	s_addc_u32 s13, s13, 0
	s_add_u32 s62, s62, 0x100
	s_addc_u32 s63, s63, 0
	s_cmp_gt_u32 s65, 29
	s_cbranch_scc0 .LBB0_1309
	s_and_b64 vcc, exec, s[26:27]
	s_cbranch_vccz .LBB0_1312
	s_barrier

; #define PG8_STAGE(bufoff, gbase, voff) do { _Pragma("unroll") for (int _i = 0; _i < 2; ++_i) \
;         __builtin_amdgcn_global_load_lds((const unsigned*)((const char*)(gbase) + (voff)[_i]), (PG8_LAS unsigned*)(lds + (bufoff) + ldsw + _i * 8192), 16, 0, 0); } while (0)
; #define PG8_LDA(dst, b, h) do { _Pragma("unroll") for (int m = 0; m < 4; ++m) _Pragma("unroll") for (int k = 0; k < 2; ++k) dst[m][k] = *(const PG8_LAS bf16x8*)(lds + PG8_SA(b, h) + aoff + m * 2048 + k * 1024); } while (0)
; #define PG8_LDB(dst, b, h) do { _Pragma("unroll") for (int n = 0; n < 2; ++n) _Pragma("unroll") for (int k = 0; k < 2; ++k) dst[n][k] = *(const PG8_LAS bf16x8*)(lds + PG8_SB(b, h) + boff + n * 2048 + k * 1024); } while (0)
; #define PG8_MMA(ai, bj, At, Bt) do { __builtin_amdgcn_s_setprio(1); _Pragma("unroll") for (int m = 0; m < 4; ++m) _Pragma("unroll") for (int n = 0; n < 2; ++n) _Pragma("unroll") for (int k = 0; k < 2; ++k) \
;         acc[ai][bj][m][n] = __builtin_amdgcn_mfma_f32_16x16x32_bf16(Bt[n][k], At[m][k], acc[ai][bj][m][n], 0, 0, 0); __builtin_amdgcn_s_setprio(0); } while (0)
; #define PG8_WAIT_V(n) asm volatile("s_waitcnt vmcnt(" #n ")" ::: "memory")
; #define PG8_WAIT_L(n) asm volatile("s_waitcnt lgkmcnt(" #n ")" ::: "memory")
; #define PG8_BAR __builtin_amdgcn_s_barrier()
; #define PG8_SCHED __builtin_amdgcn_sched_barrier(0)
; template <class Epi, class Sched, bool ALIGN_EPI = false, bool SP2 = false>
; __device__ __forceinline__ void gemm_phase(PG8_LAS unsigned char* lds, const Gemm g, const Sched& S, const Epi& E) {
;     ...
;             PG8_LDB(B0, 0, 0); PG8_LDB(B1, 0, 1); PG8_SCHED; PG8_LDA(At, 0, 0); PG8_STAGE(PG8_SA(1, 1), a1 + hstepA, voffA);
;             PG8_WAIT_V(8); PG8_WAIT_L(0); PG8_BAR; PG8_MMA(0, 0, At, B0); PG8_MMA(0, 1, At, B1); PG8_BAR; PG8_SCHED;
;             PG8_LDA(At, 0, 1); PG8_STAGE(PG8_SB(0, 0), b2, voffB); PG8_STAGE(PG8_SB(0, 1), b2 + hstepB, voffB); PG8_STAGE(PG8_SA(0, 0), a2, voffA);
;             PG8_WAIT_V(8); PG8_WAIT_L(0); PG8_BAR; PG8_MMA(1, 0, At, B0); PG8_MMA(1, 1, At, B1); PG8_BAR; PG8_SCHED;
;             PG8_LDB(B0, 1, 0); PG8_LDB(B1, 1, 1); PG8_SCHED; PG8_LDA(At, 1, 0); PG8_STAGE(PG8_SA(0, 1), a2 + hstepA, voffA);
;             PG8_WAIT_V(8); PG8_WAIT_L(0); PG8_BAR; PG8_MMA(0, 0, At, B0); PG8_MMA(0, 1, At, B1); PG8_BAR; PG8_SCHED;
.LBB0_1363:
	ds_read_b128 v[128:131], v169
	ds_read_b128 v[132:135], v169 offset:1024
	ds_read_b128 v[148:151], v169 offset:2048
	ds_read_b128 v[152:155], v169 offset:3072
	ds_read_b128 v[156:159], v170
	ds_read_b128 v[160:163], v170 offset:1024
	ds_read_b128 v[174:177], v170 offset:2048
	ds_read_b128 v[178:181], v170 offset:3072
	s_add_u32 s20, s16, 0xfff80080
	s_addc_u32 s21, s17, -1
	s_cmp_eq_u32 s63, 28
	s_cselect_b32 s35, s13, s21
	s_cselect_b32 s34, s19, s20
	s_cselect_b32 s21, s29, s62
	s_cselect_b32 s20, s31, s61
	v_lshl_add_u64 v[164:165], s[16:17], 0, v[144:145]
	s_add_i32 m0, s6, 0xc000
	ds_read_b128 v[182:185], v171
	ds_read_b128 v[186:189], v171 offset:1024
	ds_read_b128 v[190:193], v171 offset:2048
	ds_read_b128 v[194:197], v171 offset:3072
	ds_read_b128 v[198:201], v171 offset:4096
	ds_read_b128 v[202:205], v171 offset:5120
	ds_read_b128 v[206:209], v171 offset:6144
	ds_read_b128 v[210:213], v171 offset:7168
	global_load_lds_dwordx4 v[164:165], off
	v_lshl_add_u64 v[164:165], s[16:17], 0, v[146:147]
	s_add_i32 m0, s6, 0xe000
	s_nop 0
	global_load_lds_dwordx4 v[164:165], off
	s_waitcnt vmcnt(8) lgkmcnt(0)
	s_barrier
	s_setprio 1
	v_mfma_f32_16x16x32_bf16 v[124:127], v[128:131], v[182:185], v[124:127]
	v_mfma_f32_16x16x32_bf16 v[120:123], v[148:151], v[182:185], v[120:123]
	v_mfma_f32_16x16x32_bf16 v[108:111], v[128:131], v[190:193], v[108:111]
	v_mfma_f32_16x16x32_bf16 v[104:107], v[148:151], v[190:193], v[104:107]
	v_mfma_f32_16x16x32_bf16 v[92:95], v[128:131], v[198:201], v[92:95]
	v_mfma_f32_16x16x32_bf16 v[88:91], v[148:151], v[198:201], v[88:91]
	v_mfma_f32_16x16x32_bf16 v[76:79], v[128:131], v[206:209], v[76:79]
	v_mfma_f32_16x16x32_bf16 v[72:75], v[148:151], v[206:209], v[72:75]
	v_mfma_f32_16x16x32_bf16 v[124:127], v[132:135], v[186:189], v[124:127]
	v_mfma_f32_16x16x32_bf16 v[120:123], v[152:155], v[186:189], v[120:123]
	v_mfma_f32_16x16x32_bf16 v[108:111], v[132:135], v[194:197], v[108:111]
	v_mfma_f32_16x16x32_bf16 v[104:107], v[152:155], v[194:197], v[104:107]
	v_mfma_f32_16x16x32_bf16 v[92:95], v[132:135], v[202:205], v[92:95]
	v_mfma_f32_16x16x32_bf16 v[88:91], v[152:155], v[202:205], v[88:91]
	v_mfma_f32_16x16x32_bf16 v[76:79], v[132:135], v[210:213], v[76:79]
	v_mfma_f32_16x16x32_bf16 v[72:75], v[152:155], v[210:213], v[72:75]
	s_setprio 0
	s_setprio 1
	v_mfma_f32_16x16x32_bf16 v[116:119], v[156:159], v[182:185], v[116:119]
	v_mfma_f32_16x16x32_bf16 v[112:115], v[174:177], v[182:185], v[112:115]
	v_mfma_f32_16x16x32_bf16 v[100:103], v[156:159], v[190:193], v[100:103]
	v_mfma_f32_16x16x32_bf16 v[96:99], v[174:177], v[190:193], v[96:99]
	v_mfma_f32_16x16x32_bf16 v[84:87], v[156:159], v[198:201], v[84:87]
	v_mfma_f32_16x16x32_bf16 v[80:83], v[174:177], v[198:201], v[80:83]
	v_mfma_f32_16x16x32_bf16 v[68:71], v[156:159], v[206:209], v[68:71]
	v_mfma_f32_16x16x32_bf16 v[64:67], v[174:177], v[206:209], v[64:67]
	v_mfma_f32_16x16x32_bf16 v[116:119], v[160:163], v[186:189], v[116:119]
	v_mfma_f32_16x16x32_bf16 v[112:115], v[178:181], v[186:189], v[112:115]
	v_mfma_f32_16x16x32_bf16 v[100:103], v[160:163], v[194:197], v[100:103]
	v_mfma_f32_16x16x32_bf16 v[96:99], v[178:181], v[194:197], v[96:99]
	v_mfma_f32_16x16x32_bf16 v[84:87], v[160:163], v[202:205], v[84:87]
	v_mfma_f32_16x16x32_bf16 v[80:83], v[178:181], v[202:205], v[80:83]
	v_mfma_f32_16x16x32_bf16 v[68:71], v[160:163], v[210:213], v[68:71]
	v_mfma_f32_16x16x32_bf16 v[64:67], v[178:181], v[210:213], v[64:67]
	s_setprio 0
	s_barrier
	s_add_i32 s64, s59, s5
	v_lshl_add_u64 v[164:165], s[20:21], 0, v[138:139]
	s_mov_b32 m0, s64
	ds_read_b128 v[182:185], v171 offset:16384
	ds_read_b128 v[186:189], v171 offset:17408
	ds_read_b128 v[190:193], v171 offset:18432
	ds_read_b128 v[194:197], v171 offset:19456
	ds_read_b128 v[198:201], v171 offset:20480
	ds_read_b128 v[202:205], v171 offset:21504
	ds_read_b128 v[206:209], v171 offset:22528
	ds_read_b128 v[210:213], v171 offset:23552
	global_load_lds_dwordx4 v[164:165], off
	s_add_i32 m0, s64, 0x2000
	s_add_u32 s64, s20, 0x80000
	v_lshl_add_u64 v[214:215], s[20:21], 0, v[142:143]
	s_addc_u32 s65, s21, 0
	s_add_i32 s66, s60, s5
	global_load_lds_dwordx4 v[214:215], off
	v_lshl_add_u64 v[216:217], s[64:65], 0, v[138:139]
	s_mov_b32 m0, s66
	v_lshl_add_u64 v[218:219], s[34:35], 0, v[140:141]
	global_load_lds_dwordx4 v[216:217], off
	v_lshl_add_u64 v[216:217], s[64:65], 0, v[142:143]
	s_add_i32 m0, s66, 0x2000
	s_nop 0
	global_load_lds_dwordx4 v[216:217], off
	v_lshl_add_u64 v[216:217], s[34:35], 0, v[136:137]
	s_mov_b32 m0, s6
	s_nop 0
	global_load_lds_dwordx4 v[216:217], off
	s_mov_b32 m0, s7
	s_nop 0
	global_load_lds_dwordx4 v[218:219], off
	s_waitcnt vmcnt(8) lgkmcnt(0)
	s_barrier
; #define PG8_STAGE(bufoff, gbase, voff) do { _Pragma("unroll") for (int _i = 0; _i < 2; ++_i) \
;         __builtin_amdgcn_global_load_lds((const unsigned*)((const char*)(gbase) + (voff)[_i]), (PG8_LAS unsigned*)(lds + (bufoff) + ldsw + _i * 8192), 16, 0, 0); } while (0)
; #define PG8_LDA(dst, b, h) do { _Pragma("unroll") for (int m = 0; m < 4; ++m) _Pragma("unroll") for (int k = 0; k < 2; ++k) dst[m][k] = *(const PG8_LAS bf16x8*)(lds + PG8_SA(b, h) + aoff + m * 2048 + k * 1024); } while (0)
; #define PG8_LDB(dst, b, h) do { _Pragma("unroll") for (int n = 0; n < 2; ++n) _Pragma("unroll") for (int k = 0; k < 2; ++k) dst[n][k] = *(const PG8_LAS bf16x8*)(lds + PG8_SB(b, h) + boff + n * 2048 + k * 1024); } while (0)
; #define PG8_MMA(ai, bj, At, Bt) do { __builtin_amdgcn_s_setprio(1); _Pragma("unroll") for (int m = 0; m < 4; ++m) _Pragma("unroll") for (int n = 0; n < 2; ++n) _Pragma("unroll") for (int k = 0; k < 2; ++k) \
;         acc[ai][bj][m][n] = __builtin_amdgcn_mfma_f32_16x16x32_bf16(Bt[n][k], At[m][k], acc[ai][bj][m][n], 0, 0, 0); __builtin_amdgcn_s_setprio(0); } while (0)
; #define PG8_WAIT_V(n) asm volatile("s_waitcnt vmcnt(" #n ")" ::: "memory")
; #define PG8_WAIT_L(n) asm volatile("s_waitcnt lgkmcnt(" #n ")" ::: "memory")
; #define PG8_BAR __builtin_amdgcn_s_barrier()
; #define PG8_SCHED __builtin_amdgcn_sched_barrier(0)
; template <class Epi, class Sched, bool ALIGN_EPI = false, bool SP2 = false>
; __device__ __forceinline__ void gemm_phase(PG8_LAS unsigned char* lds, const Gemm g, const Sched& S, const Epi& E) {
;     ...
;             PG8_LDA(At, 0, 1); PG8_STAGE(PG8_SB(0, 0), b2, voffB); PG8_STAGE(PG8_SB(0, 1), b2 + hstepB, voffB); PG8_STAGE(PG8_SA(0, 0), a2, voffA);
;             PG8_WAIT_V(8); PG8_WAIT_L(0); PG8_BAR; PG8_MMA(1, 0, At, B0); PG8_MMA(1, 1, At, B1); PG8_BAR; PG8_SCHED;
;             PG8_LDB(B0, 1, 0); PG8_LDB(B1, 1, 1); PG8_SCHED; PG8_LDA(At, 1, 0); PG8_STAGE(PG8_SA(0, 1), a2 + hstepA, voffA);
;             PG8_WAIT_V(8); PG8_WAIT_L(0); PG8_BAR; PG8_MMA(0, 0, At, B0); PG8_MMA(0, 1, At, B1); PG8_BAR; PG8_SCHED;
	s_setprio 1
	v_mfma_f32_16x16x32_bf16 v[60:63], v[128:131], v[182:185], v[60:63]
	v_mfma_f32_16x16x32_bf16 v[56:59], v[148:151], v[182:185], v[56:59]
	v_mfma_f32_16x16x32_bf16 v[44:47], v[128:131], v[190:193], v[44:47]
	v_mfma_f32_16x16x32_bf16 v[40:43], v[148:151], v[190:193], v[40:43]
	v_mfma_f32_16x16x32_bf16 v[28:31], v[128:131], v[198:201], v[28:31]
	v_mfma_f32_16x16x32_bf16 v[24:27], v[148:151], v[198:201], v[24:27]
	v_mfma_f32_16x16x32_bf16 v[12:15], v[128:131], v[206:209], v[12:15]
	v_mfma_f32_16x16x32_bf16 v[8:11], v[148:151], v[206:209], v[8:11]
	v_mfma_f32_16x16x32_bf16 v[60:63], v[132:135], v[186:189], v[60:63]
	v_mfma_f32_16x16x32_bf16 v[56:59], v[152:155], v[186:189], v[56:59]
	v_mfma_f32_16x16x32_bf16 v[44:47], v[132:135], v[194:197], v[44:47]
	v_mfma_f32_16x16x32_bf16 v[40:43], v[152:155], v[194:197], v[40:43]
	v_mfma_f32_16x16x32_bf16 v[28:31], v[132:135], v[202:205], v[28:31]
	v_mfma_f32_16x16x32_bf16 v[24:27], v[152:155], v[202:205], v[24:27]
	v_mfma_f32_16x16x32_bf16 v[12:15], v[132:135], v[210:213], v[12:15]
	v_mfma_f32_16x16x32_bf16 v[8:11], v[152:155], v[210:213], v[8:11]
	s_setprio 0
	s_setprio 1
	v_mfma_f32_16x16x32_bf16 v[52:55], v[156:159], v[182:185], v[52:55]
	v_mfma_f32_16x16x32_bf16 v[48:51], v[174:177], v[182:185], v[48:51]
	v_mfma_f32_16x16x32_bf16 v[36:39], v[156:159], v[190:193], v[36:39]
	v_mfma_f32_16x16x32_bf16 v[32:35], v[174:177], v[190:193], v[32:35]
	v_mfma_f32_16x16x32_bf16 v[20:23], v[156:159], v[198:201], v[20:23]
	v_mfma_f32_16x16x32_bf16 v[16:19], v[174:177], v[198:201], v[16:19]
	v_mfma_f32_16x16x32_bf16 v[4:7], v[156:159], v[206:209], v[4:7]
	v_mfma_f32_16x16x32_bf16 v[0:3], v[174:177], v[206:209], v[0:3]
	v_mfma_f32_16x16x32_bf16 v[52:55], v[160:163], v[186:189], v[52:55]
	v_mfma_f32_16x16x32_bf16 v[48:51], v[178:181], v[186:189], v[48:51]
	v_mfma_f32_16x16x32_bf16 v[36:39], v[160:163], v[194:197], v[36:39]
	v_mfma_f32_16x16x32_bf16 v[32:35], v[178:181], v[194:197], v[32:35]
	v_mfma_f32_16x16x32_bf16 v[20:23], v[160:163], v[202:205], v[20:23]
	v_mfma_f32_16x16x32_bf16 v[16:19], v[178:181], v[202:205], v[16:19]
	v_mfma_f32_16x16x32_bf16 v[4:7], v[160:163], v[210:213], v[4:7]
	v_mfma_f32_16x16x32_bf16 v[0:3], v[178:181], v[210:213], v[0:3]
	s_setprio 0
	s_barrier
	s_add_i32 s64, 0, 0x18000
	s_add_i32 s65, 0, 0x1c000
	v_add_u32_e32 v152, s64, v168
	v_add_u32_e32 v173, s65, v168
	ds_read_b128 v[128:131], v152
	ds_read_b128 v[132:135], v152 offset:1024
	ds_read_b128 v[148:151], v152 offset:2048
	ds_read_b128 v[152:155], v152 offset:3072
	ds_read_b128 v[156:159], v173
	ds_read_b128 v[160:163], v173 offset:1024
	ds_read_b128 v[174:177], v173 offset:2048
	ds_read_b128 v[178:181], v173 offset:3072
	s_add_u32 s34, s34, 0x80000
	s_addc_u32 s35, s35, 0
	s_mov_b32 m0, s33
	v_lshl_add_u64 v[220:221], s[34:35], 0, v[136:137]
	ds_read_b128 v[182:185], v171 offset:32768
	ds_read_b128 v[186:189], v171 offset:33792
	ds_read_b128 v[190:193], v171 offset:34816
	ds_read_b128 v[194:197], v171 offset:35840
	ds_read_b128 v[198:201], v171 offset:36864
	ds_read_b128 v[202:205], v171 offset:37888
	ds_read_b128 v[206:209], v171 offset:38912
	ds_read_b128 v[210:213], v171 offset:39936
	global_load_lds_dwordx4 v[220:221], off
	v_lshl_add_u64 v[220:221], s[34:35], 0, v[140:141]
	s_mov_b32 m0, s46
	s_nop 0
	global_load_lds_dwordx4 v[220:221], off
	s_waitcnt vmcnt(8) lgkmcnt(0)
	s_barrier
	s_setprio 1
	v_mfma_f32_16x16x32_bf16 v[124:127], v[128:131], v[182:185], v[124:127]
	v_mfma_f32_16x16x32_bf16 v[120:123], v[148:151], v[182:185], v[120:123]
	v_mfma_f32_16x16x32_bf16 v[108:111], v[128:131], v[190:193], v[108:111]
	v_mfma_f32_16x16x32_bf16 v[104:107], v[148:151], v[190:193], v[104:107]
	v_mfma_f32_16x16x32_bf16 v[92:95], v[128:131], v[198:201], v[92:95]
	v_mfma_f32_16x16x32_bf16 v[88:91], v[148:151], v[198:201], v[88:91]
	v_mfma_f32_16x16x32_bf16 v[76:79], v[128:131], v[206:209], v[76:79]
	v_mfma_f32_16x16x32_bf16 v[72:75], v[148:151], v[206:209], v[72:75]
	v_mfma_f32_16x16x32_bf16 v[124:127], v[132:135], v[186:189], v[124:127]
	v_mfma_f32_16x16x32_bf16 v[120:123], v[152:155], v[186:189], v[120:123]
	v_mfma_f32_16x16x32_bf16 v[108:111], v[132:135], v[194:197], v[108:111]
	v_mfma_f32_16x16x32_bf16 v[104:107], v[152:155], v[194:197], v[104:107]
	v_mfma_f32_16x16x32_bf16 v[92:95], v[132:135], v[202:205], v[92:95]
	v_mfma_f32_16x16x32_bf16 v[88:91], v[152:155], v[202:205], v[88:91]
	v_mfma_f32_16x16x32_bf16 v[76:79], v[132:135], v[210:213], v[76:79]
	v_mfma_f32_16x16x32_bf16 v[72:75], v[152:155], v[210:213], v[72:75]
	s_setprio 0
	s_setprio 1
	v_mfma_f32_16x16x32_bf16 v[116:119], v[156:159], v[182:185], v[116:119]
	v_mfma_f32_16x16x32_bf16 v[112:115], v[174:177], v[182:185], v[112:115]
	v_mfma_f32_16x16x32_bf16 v[100:103], v[156:159], v[190:193], v[100:103]
	v_mfma_f32_16x16x32_bf16 v[96:99], v[174:177], v[190:193], v[96:99]
	v_mfma_f32_16x16x32_bf16 v[84:87], v[156:159], v[198:201], v[84:87]
	v_mfma_f32_16x16x32_bf16 v[80:83], v[174:177], v[198:201], v[80:83]
	v_mfma_f32_16x16x32_bf16 v[68:71], v[156:159], v[206:209], v[68:71]
	v_mfma_f32_16x16x32_bf16 v[64:67], v[174:177], v[206:209], v[64:67]
	v_mfma_f32_16x16x32_bf16 v[116:119], v[160:163], v[186:189], v[116:119]
	v_mfma_f32_16x16x32_bf16 v[112:115], v[178:181], v[186:189], v[112:115]
	v_mfma_f32_16x16x32_bf16 v[100:103], v[160:163], v[194:197], v[100:103]
	v_mfma_f32_16x16x32_bf16 v[96:99], v[178:181], v[194:197], v[96:99]
	v_mfma_f32_16x16x32_bf16 v[84:87], v[160:163], v[202:205], v[84:87]
	v_mfma_f32_16x16x32_bf16 v[80:83], v[178:181], v[202:205], v[80:83]
	v_mfma_f32_16x16x32_bf16 v[68:71], v[160:163], v[210:213], v[68:71]
	v_mfma_f32_16x16x32_bf16 v[64:67], v[178:181], v[210:213], v[64:67]
	s_setprio 0
	s_barrier
; #define PG8_STAGE(bufoff, gbase, voff) do { _Pragma("unroll") for (int _i = 0; _i < 2; ++_i) \
;         __builtin_amdgcn_global_load_lds((const unsigned*)((const char*)(gbase) + (voff)[_i]), (PG8_LAS unsigned*)(lds + (bufoff) + ldsw + _i * 8192), 16, 0, 0); } while (0)
; #define PG8_LDA(dst, b, h) do { _Pragma("unroll") for (int m = 0; m < 4; ++m) _Pragma("unroll") for (int k = 0; k < 2; ++k) dst[m][k] = *(const PG8_LAS bf16x8*)(lds + PG8_SA(b, h) + aoff + m * 2048 + k * 1024); } while (0)
; #define PG8_MMA(ai, bj, At, Bt) do { __builtin_amdgcn_s_setprio(1); _Pragma("unroll") for (int m = 0; m < 4; ++m) _Pragma("unroll") for (int n = 0; n < 2; ++n) _Pragma("unroll") for (int k = 0; k < 2; ++k) \
;         acc[ai][bj][m][n] = __builtin_amdgcn_mfma_f32_16x16x32_bf16(Bt[n][k], At[m][k], acc[ai][bj][m][n], 0, 0, 0); __builtin_amdgcn_s_setprio(0); } while (0)
; #define PG8_WAIT_V(n) asm volatile("s_waitcnt vmcnt(" #n ")" ::: "memory")
; #define PG8_WAIT_L(n) asm volatile("s_waitcnt lgkmcnt(" #n ")" ::: "memory")
; #define PG8_BAR __builtin_amdgcn_s_barrier()
; #define PG8_SCHED __builtin_amdgcn_sched_barrier(0)
; template <class Epi, class Sched, bool ALIGN_EPI = false, bool SP2 = false>
; __device__ __forceinline__ void gemm_phase(PG8_LAS unsigned char* lds, const Gemm g, const Sched& S, const Epi& E) {
;     ...
;             PG8_LDA(At, 1, 1); PG8_STAGE(PG8_SB(1, 0), b3, voffB); PG8_STAGE(PG8_SB(1, 1), b3 + hstepB, voffB); PG8_STAGE(PG8_SA(1, 0), a3, voffA);
;             PG8_WAIT_V(8); PG8_WAIT_L(0); PG8_BAR; PG8_MMA(1, 0, At, B0); PG8_MMA(1, 1, At, B1); PG8_BAR; PG8_SCHED;
;     ...
;         if constexpr (ALIGN_EPI) { if (wr == 0) PG8_BAR; }
	s_add_i32 s34, s64, s5
	v_lshl_add_u64 v[164:165], v[164:165], 0, s[22:23]
	s_mov_b32 m0, s34
	ds_read_b128 v[182:185], v171 offset:49152
	ds_read_b128 v[186:189], v171 offset:50176
	ds_read_b128 v[190:193], v171 offset:51200
	ds_read_b128 v[194:197], v171 offset:52224
	ds_read_b128 v[198:201], v171 offset:53248
	ds_read_b128 v[202:205], v171 offset:54272
	ds_read_b128 v[206:209], v171 offset:55296
	ds_read_b128 v[210:213], v171 offset:56320
	global_load_lds_dwordx4 v[164:165], off
	s_add_i32 m0, s34, 0x2000
	s_add_u32 s20, s20, 0x80080
	v_lshl_add_u64 v[164:165], v[214:215], 0, s[22:23]
	s_addc_u32 s21, s21, 0
	s_add_i32 s34, s65, s5
	global_load_lds_dwordx4 v[164:165], off
	v_lshl_add_u64 v[164:165], s[20:21], 0, v[138:139]
	s_mov_b32 m0, s34
	s_nop 0
	global_load_lds_dwordx4 v[164:165], off
	v_lshl_add_u64 v[164:165], s[20:21], 0, v[142:143]
	s_add_i32 m0, s34, 0x2000
	s_nop 0
	global_load_lds_dwordx4 v[164:165], off
	v_lshl_add_u64 v[164:165], v[216:217], 0, s[22:23]
	s_mov_b32 m0, s56
	s_nop 0
	global_load_lds_dwordx4 v[164:165], off
	v_lshl_add_u64 v[164:165], v[218:219], 0, s[22:23]
	s_mov_b32 m0, s57
	s_nop 0
	global_load_lds_dwordx4 v[164:165], off
	s_waitcnt vmcnt(8) lgkmcnt(0)
	s_barrier
	s_setprio 1
	v_mfma_f32_16x16x32_bf16 v[60:63], v[128:131], v[182:185], v[60:63]
	v_mfma_f32_16x16x32_bf16 v[56:59], v[148:151], v[182:185], v[56:59]
	v_mfma_f32_16x16x32_bf16 v[44:47], v[128:131], v[190:193], v[44:47]
	v_mfma_f32_16x16x32_bf16 v[40:43], v[148:151], v[190:193], v[40:43]
	v_mfma_f32_16x16x32_bf16 v[28:31], v[128:131], v[198:201], v[28:31]
	v_mfma_f32_16x16x32_bf16 v[24:27], v[148:151], v[198:201], v[24:27]
	v_mfma_f32_16x16x32_bf16 v[12:15], v[128:131], v[206:209], v[12:15]
	v_mfma_f32_16x16x32_bf16 v[8:11], v[148:151], v[206:209], v[8:11]
	v_mfma_f32_16x16x32_bf16 v[60:63], v[132:135], v[186:189], v[60:63]
	v_mfma_f32_16x16x32_bf16 v[56:59], v[152:155], v[186:189], v[56:59]
	v_mfma_f32_16x16x32_bf16 v[44:47], v[132:135], v[194:197], v[44:47]
	v_mfma_f32_16x16x32_bf16 v[40:43], v[152:155], v[194:197], v[40:43]
	v_mfma_f32_16x16x32_bf16 v[28:31], v[132:135], v[202:205], v[28:31]
	v_mfma_f32_16x16x32_bf16 v[24:27], v[152:155], v[202:205], v[24:27]
	v_mfma_f32_16x16x32_bf16 v[12:15], v[132:135], v[210:213], v[12:15]
	v_mfma_f32_16x16x32_bf16 v[8:11], v[152:155], v[210:213], v[8:11]
	s_setprio 0
	s_setprio 1
	v_mfma_f32_16x16x32_bf16 v[52:55], v[156:159], v[182:185], v[52:55]
	v_mfma_f32_16x16x32_bf16 v[48:51], v[174:177], v[182:185], v[48:51]
	v_mfma_f32_16x16x32_bf16 v[36:39], v[156:159], v[190:193], v[36:39]
	v_mfma_f32_16x16x32_bf16 v[32:35], v[174:177], v[190:193], v[32:35]
	v_mfma_f32_16x16x32_bf16 v[20:23], v[156:159], v[198:201], v[20:23]
	v_mfma_f32_16x16x32_bf16 v[16:19], v[174:177], v[198:201], v[16:19]
	v_mfma_f32_16x16x32_bf16 v[4:7], v[156:159], v[206:209], v[4:7]
	v_mfma_f32_16x16x32_bf16 v[0:3], v[174:177], v[206:209], v[0:3]
	v_mfma_f32_16x16x32_bf16 v[52:55], v[160:163], v[186:189], v[52:55]
	v_mfma_f32_16x16x32_bf16 v[48:51], v[178:181], v[186:189], v[48:51]
	v_mfma_f32_16x16x32_bf16 v[36:39], v[160:163], v[194:197], v[36:39]
	v_mfma_f32_16x16x32_bf16 v[32:35], v[178:181], v[194:197], v[32:35]
	v_mfma_f32_16x16x32_bf16 v[20:23], v[160:163], v[202:205], v[20:23]
	v_mfma_f32_16x16x32_bf16 v[16:19], v[178:181], v[202:205], v[16:19]
	v_mfma_f32_16x16x32_bf16 v[4:7], v[160:163], v[210:213], v[4:7]
	v_mfma_f32_16x16x32_bf16 v[0:3], v[178:181], v[210:213], v[0:3]
	s_setprio 0
	s_barrier
	s_add_i32 s63, s63, 2
	s_add_u32 s16, s16, 0x100
	s_addc_u32 s17, s17, 0
	s_add_u32 s61, s61, 0x100
	s_addc_u32 s62, s62, 0
	s_cmp_gt_u32 s63, 29
	s_cbranch_scc0 .LBB0_1363
	s_and_b64 vcc, exec, s[24:25]
	s_cbranch_vccz .LBB0_1366
	s_barrier

; #define PG8_STAGE(bufoff, gbase, voff) do { _Pragma("unroll") for (int _i = 0; _i < 2; ++_i) \
;         __builtin_amdgcn_global_load_lds((const unsigned*)((const char*)(gbase) + (voff)[_i]), (PG8_LAS unsigned*)(lds + (bufoff) + ldsw + _i * 8192), 16, 0, 0); } while (0)
; #define PG8_LDA(dst, b, h) do { _Pragma("unroll") for (int m = 0; m < 4; ++m) _Pragma("unroll") for (int k = 0; k < 2; ++k) dst[m][k] = *(const PG8_LAS bf16x8*)(lds + PG8_SA(b, h) + aoff + m * 2048 + k * 1024); } while (0)
; #define PG8_LDB(dst, b, h) do { _Pragma("unroll") for (int n = 0; n < 2; ++n) _Pragma("unroll") for (int k = 0; k < 2; ++k) dst[n][k] = *(const PG8_LAS bf16x8*)(lds + PG8_SB(b, h) + boff + n * 2048 + k * 1024); } while (0)
; #define PG8_MMA(ai, bj, At, Bt) do { __builtin_amdgcn_s_setprio(1); _Pragma("unroll") for (int m = 0; m < 4; ++m) _Pragma("unroll") for (int n = 0; n < 2; ++n) _Pragma("unroll") for (int k = 0; k < 2; ++k) \
;         acc[ai][bj][m][n] = __builtin_amdgcn_mfma_f32_16x16x32_bf16(Bt[n][k], At[m][k], acc[ai][bj][m][n], 0, 0, 0); __builtin_amdgcn_s_setprio(0); } while (0)
; #define PG8_WAIT_V(n) asm volatile("s_waitcnt vmcnt(" #n ")" ::: "memory")
; #define PG8_WAIT_L(n) asm volatile("s_waitcnt lgkmcnt(" #n ")" ::: "memory")
; #define PG8_BAR __builtin_amdgcn_s_barrier()
; #define PG8_SCHED __builtin_amdgcn_sched_barrier(0)
; template <class Epi, class Sched, bool ALIGN_EPI = false, bool SP2 = false>
; __device__ __forceinline__ void gemm_phase(PG8_LAS unsigned char* lds, const Gemm g, const Sched& S, const Epi& E) {
;     ...
;             PG8_LDB(B0, 0, 0); PG8_LDB(B1, 0, 1); PG8_SCHED; PG8_LDA(At, 0, 0); PG8_STAGE(PG8_SA(1, 1), a1 + hstepA, voffA);
;             PG8_WAIT_V(8); PG8_WAIT_L(0); PG8_BAR; PG8_MMA(0, 0, At, B0); PG8_MMA(0, 1, At, B1); PG8_BAR; PG8_SCHED;
;             PG8_LDA(At, 0, 1); PG8_STAGE(PG8_SB(0, 0), b2, voffB); PG8_STAGE(PG8_SB(0, 1), b2 + hstepB, voffB); PG8_STAGE(PG8_SA(0, 0), a2, voffA);
;             PG8_WAIT_V(8); PG8_WAIT_L(0); PG8_BAR; PG8_MMA(1, 0, At, B0); PG8_MMA(1, 1, At, B1); PG8_BAR; PG8_SCHED;
;             PG8_LDB(B0, 1, 0); PG8_LDB(B1, 1, 1); PG8_SCHED; PG8_LDA(At, 1, 0); PG8_STAGE(PG8_SA(0, 1), a2 + hstepA, voffA);
;             PG8_WAIT_V(8); PG8_WAIT_L(0); PG8_BAR; PG8_MMA(0, 0, At, B0); PG8_MMA(0, 1, At, B1); PG8_BAR; PG8_SCHED;
.LBB0_1738:
	ds_read_b128 v[144:147], v151
	ds_read_b128 v[154:157], v151 offset:1024
	ds_read_b128 v[158:161], v151 offset:2048
	ds_read_b128 v[162:165], v151 offset:3072
	ds_read_b128 v[166:169], v152
	ds_read_b128 v[170:173], v152 offset:1024
	ds_read_b128 v[174:177], v152 offset:2048
	ds_read_b128 v[178:181], v152 offset:3072
	s_add_u32 s34, s20, 0xfffe0080
	s_addc_u32 s35, s21, -1
	s_cmp_eq_u32 s57, 4
	s_cselect_b32 s39, s13, s35
	s_cselect_b32 s38, s27, s34
	s_cselect_b32 s35, s25, s56
	s_cselect_b32 s34, s52, s53
	s_add_i32 m0, s5, 0xc000
	ds_read_b128 v[182:185], v153
	ds_read_b128 v[186:189], v153 offset:1024
	ds_read_b128 v[190:193], v153 offset:2048
	ds_read_b128 v[194:197], v153 offset:3072
	ds_read_b128 v[198:201], v153 offset:4096
	ds_read_b128 v[202:205], v153 offset:5120
	ds_read_b128 v[206:209], v153 offset:6144
	ds_read_b128 v[210:213], v153 offset:7168
	s_add_u32 s98, s20, 0xfffe0000
	s_addc_u32 s99, s21, -1
	s_mov_b32 m0, s42
	s_nop 0
	global_load_lds_dwordx4 v128, s[98:99]
	s_mov_b32 m0, s43
	s_nop 0
	global_load_lds_dwordx4 v132, s[98:99]
	s_add_i32 m0, s5, 0xc000
	s_nop 0
	global_load_lds_dwordx4 v136, s[20:21]
	s_add_i32 m0, s5, 0xe000
	s_nop 0
	global_load_lds_dwordx4 v138, s[20:21]
	s_waitcnt vmcnt(8) lgkmcnt(0)
	s_barrier
	s_setprio 1
	v_mfma_f32_16x16x32_bf16 v[124:127], v[144:147], v[182:185], v[124:127]
	v_mfma_f32_16x16x32_bf16 v[120:123], v[158:161], v[182:185], v[120:123]
	v_mfma_f32_16x16x32_bf16 v[108:111], v[144:147], v[190:193], v[108:111]
	v_mfma_f32_16x16x32_bf16 v[104:107], v[158:161], v[190:193], v[104:107]
	v_mfma_f32_16x16x32_bf16 v[92:95], v[144:147], v[198:201], v[92:95]
	v_mfma_f32_16x16x32_bf16 v[88:91], v[158:161], v[198:201], v[88:91]
	v_mfma_f32_16x16x32_bf16 v[76:79], v[144:147], v[206:209], v[76:79]
	v_mfma_f32_16x16x32_bf16 v[72:75], v[158:161], v[206:209], v[72:75]
	v_mfma_f32_16x16x32_bf16 v[124:127], v[154:157], v[186:189], v[124:127]
	v_mfma_f32_16x16x32_bf16 v[120:123], v[162:165], v[186:189], v[120:123]
	v_mfma_f32_16x16x32_bf16 v[108:111], v[154:157], v[194:197], v[108:111]
	v_mfma_f32_16x16x32_bf16 v[104:107], v[162:165], v[194:197], v[104:107]
	v_mfma_f32_16x16x32_bf16 v[92:95], v[154:157], v[202:205], v[92:95]
	v_mfma_f32_16x16x32_bf16 v[88:91], v[162:165], v[202:205], v[88:91]
	v_mfma_f32_16x16x32_bf16 v[76:79], v[154:157], v[210:213], v[76:79]
	v_mfma_f32_16x16x32_bf16 v[72:75], v[162:165], v[210:213], v[72:75]
	s_setprio 0
	s_setprio 1
	v_mfma_f32_16x16x32_bf16 v[116:119], v[166:169], v[182:185], v[116:119]
	v_mfma_f32_16x16x32_bf16 v[112:115], v[174:177], v[182:185], v[112:115]
	v_mfma_f32_16x16x32_bf16 v[100:103], v[166:169], v[190:193], v[100:103]
	v_mfma_f32_16x16x32_bf16 v[96:99], v[174:177], v[190:193], v[96:99]
	v_mfma_f32_16x16x32_bf16 v[84:87], v[166:169], v[198:201], v[84:87]
	v_mfma_f32_16x16x32_bf16 v[80:83], v[174:177], v[198:201], v[80:83]
	v_mfma_f32_16x16x32_bf16 v[68:71], v[166:169], v[206:209], v[68:71]
	v_mfma_f32_16x16x32_bf16 v[64:67], v[174:177], v[206:209], v[64:67]
	v_mfma_f32_16x16x32_bf16 v[116:119], v[170:173], v[186:189], v[116:119]
	v_mfma_f32_16x16x32_bf16 v[112:115], v[178:181], v[186:189], v[112:115]
	v_mfma_f32_16x16x32_bf16 v[100:103], v[170:173], v[194:197], v[100:103]
	v_mfma_f32_16x16x32_bf16 v[96:99], v[178:181], v[194:197], v[96:99]
	v_mfma_f32_16x16x32_bf16 v[84:87], v[170:173], v[202:205], v[84:87]
	v_mfma_f32_16x16x32_bf16 v[80:83], v[178:181], v[202:205], v[80:83]
	v_mfma_f32_16x16x32_bf16 v[68:71], v[170:173], v[210:213], v[68:71]
	v_mfma_f32_16x16x32_bf16 v[64:67], v[178:181], v[210:213], v[64:67]
	s_setprio 0
	s_barrier
	s_add_i32 s58, s47, s4
	s_mov_b32 m0, s58
	ds_read_b128 v[182:185], v153 offset:16384
	ds_read_b128 v[186:189], v153 offset:17408
	ds_read_b128 v[190:193], v153 offset:18432
	ds_read_b128 v[194:197], v153 offset:19456
	ds_read_b128 v[198:201], v153 offset:20480
	ds_read_b128 v[202:205], v153 offset:21504
	ds_read_b128 v[206:209], v153 offset:22528
	ds_read_b128 v[210:213], v153 offset:23552
	global_load_lds_dwordx4 v130, s[34:35]
	s_add_i32 m0, s58, 0x2000
	s_add_u32 s58, s34, 0x20000
	s_addc_u32 s59, s35, 0
	s_add_i32 s60, s50, s4
	global_load_lds_dwordx4 v134, s[34:35]
	s_mov_b32 m0, s60
	s_nop 0
	global_load_lds_dwordx4 v130, s[58:59]
	s_add_i32 m0, s60, 0x2000
	s_nop 0
	global_load_lds_dwordx4 v134, s[58:59]
	s_waitcnt vmcnt(6) lgkmcnt(0)
	s_barrier
	s_setprio 1
	v_mfma_f32_16x16x32_bf16 v[60:63], v[144:147], v[182:185], v[60:63]
	v_mfma_f32_16x16x32_bf16 v[56:59], v[158:161], v[182:185], v[56:59]
	v_mfma_f32_16x16x32_bf16 v[44:47], v[144:147], v[190:193], v[44:47]
	v_mfma_f32_16x16x32_bf16 v[40:43], v[158:161], v[190:193], v[40:43]
	v_mfma_f32_16x16x32_bf16 v[28:31], v[144:147], v[198:201], v[28:31]
	v_mfma_f32_16x16x32_bf16 v[24:27], v[158:161], v[198:201], v[24:27]
	v_mfma_f32_16x16x32_bf16 v[12:15], v[144:147], v[206:209], v[12:15]
	v_mfma_f32_16x16x32_bf16 v[8:11], v[158:161], v[206:209], v[8:11]
	v_mfma_f32_16x16x32_bf16 v[60:63], v[154:157], v[186:189], v[60:63]
	v_mfma_f32_16x16x32_bf16 v[56:59], v[162:165], v[186:189], v[56:59]
	v_mfma_f32_16x16x32_bf16 v[44:47], v[154:157], v[194:197], v[44:47]
	v_mfma_f32_16x16x32_bf16 v[40:43], v[162:165], v[194:197], v[40:43]
	v_mfma_f32_16x16x32_bf16 v[28:31], v[154:157], v[202:205], v[28:31]
	v_mfma_f32_16x16x32_bf16 v[24:27], v[162:165], v[202:205], v[24:27]
	v_mfma_f32_16x16x32_bf16 v[12:15], v[154:157], v[210:213], v[12:15]
	v_mfma_f32_16x16x32_bf16 v[8:11], v[162:165], v[210:213], v[8:11]
	s_setprio 0
	s_setprio 1
	v_mfma_f32_16x16x32_bf16 v[52:55], v[166:169], v[182:185], v[52:55]
	v_mfma_f32_16x16x32_bf16 v[48:51], v[174:177], v[182:185], v[48:51]
	v_mfma_f32_16x16x32_bf16 v[36:39], v[166:169], v[190:193], v[36:39]
	v_mfma_f32_16x16x32_bf16 v[32:35], v[174:177], v[190:193], v[32:35]
	v_mfma_f32_16x16x32_bf16 v[20:23], v[166:169], v[198:201], v[20:23]
	v_mfma_f32_16x16x32_bf16 v[16:19], v[174:177], v[198:201], v[16:19]
	v_mfma_f32_16x16x32_bf16 v[4:7], v[166:169], v[206:209], v[4:7]
	v_mfma_f32_16x16x32_bf16 v[0:3], v[174:177], v[206:209], v[0:3]
	v_mfma_f32_16x16x32_bf16 v[52:55], v[170:173], v[186:189], v[52:55]
	v_mfma_f32_16x16x32_bf16 v[48:51], v[178:181], v[186:189], v[48:51]
	v_mfma_f32_16x16x32_bf16 v[36:39], v[170:173], v[194:197], v[36:39]
	v_mfma_f32_16x16x32_bf16 v[32:35], v[178:181], v[194:197], v[32:35]
	v_mfma_f32_16x16x32_bf16 v[20:23], v[170:173], v[202:205], v[20:23]
	v_mfma_f32_16x16x32_bf16 v[16:19], v[178:181], v[202:205], v[16:19]
	v_mfma_f32_16x16x32_bf16 v[4:7], v[170:173], v[210:213], v[4:7]
	v_mfma_f32_16x16x32_bf16 v[0:3], v[178:181], v[210:213], v[0:3]
	s_setprio 0
	s_barrier
; #define PG8_STAGE(bufoff, gbase, voff) do { _Pragma("unroll") for (int _i = 0; _i < 2; ++_i) \
;         __builtin_amdgcn_global_load_lds((const unsigned*)((const char*)(gbase) + (voff)[_i]), (PG8_LAS unsigned*)(lds + (bufoff) + ldsw + _i * 8192), 16, 0, 0); } while (0)
; #define PG8_LDA(dst, b, h) do { _Pragma("unroll") for (int m = 0; m < 4; ++m) _Pragma("unroll") for (int k = 0; k < 2; ++k) dst[m][k] = *(const PG8_LAS bf16x8*)(lds + PG8_SA(b, h) + aoff + m * 2048 + k * 1024); } while (0)
; #define PG8_LDB(dst, b, h) do { _Pragma("unroll") for (int n = 0; n < 2; ++n) _Pragma("unroll") for (int k = 0; k < 2; ++k) dst[n][k] = *(const PG8_LAS bf16x8*)(lds + PG8_SB(b, h) + boff + n * 2048 + k * 1024); } while (0)
; #define PG8_MMA(ai, bj, At, Bt) do { __builtin_amdgcn_s_setprio(1); _Pragma("unroll") for (int m = 0; m < 4; ++m) _Pragma("unroll") for (int n = 0; n < 2; ++n) _Pragma("unroll") for (int k = 0; k < 2; ++k) \
;         acc[ai][bj][m][n] = __builtin_amdgcn_mfma_f32_16x16x32_bf16(Bt[n][k], At[m][k], acc[ai][bj][m][n], 0, 0, 0); __builtin_amdgcn_s_setprio(0); } while (0)
; #define PG8_WAIT_V(n) asm volatile("s_waitcnt vmcnt(" #n ")" ::: "memory")
; #define PG8_WAIT_L(n) asm volatile("s_waitcnt lgkmcnt(" #n ")" ::: "memory")
; #define PG8_BAR __builtin_amdgcn_s_barrier()
; #define PG8_SCHED __builtin_amdgcn_sched_barrier(0)
; template <class Epi, class Sched, bool ALIGN_EPI = false, bool SP2 = false>
; __device__ __forceinline__ void gemm_phase(PG8_LAS unsigned char* lds, const Gemm g, const Sched& S, const Epi& E) {
;     ...
;             PG8_LDB(B0, 1, 0); PG8_LDB(B1, 1, 1); PG8_SCHED; PG8_LDA(At, 1, 0); PG8_STAGE(PG8_SA(0, 1), a2 + hstepA, voffA);
;             PG8_WAIT_V(8); PG8_WAIT_L(0); PG8_BAR; PG8_MMA(0, 0, At, B0); PG8_MMA(0, 1, At, B1); PG8_BAR; PG8_SCHED;
;             PG8_LDA(At, 1, 1); PG8_STAGE(PG8_SB(1, 0), b3, voffB); PG8_STAGE(PG8_SB(1, 1), b3 + hstepB, voffB); PG8_STAGE(PG8_SA(1, 0), a3, voffA);
;             PG8_WAIT_V(8); PG8_WAIT_L(0); PG8_BAR; PG8_MMA(1, 0, At, B0); PG8_MMA(1, 1, At, B1); PG8_BAR; PG8_SCHED;
;     ...
;         if constexpr (ALIGN_EPI) { if (wr == 0) PG8_BAR; }
	s_add_i32 s58, 0, 0x18000
	s_add_i32 s59, 0, 0x1c000
	v_add_u32_e32 v162, s58, v150
	v_add_u32_e32 v178, s59, v150
	ds_read_b128 v[144:147], v162
	ds_read_b128 v[154:157], v162 offset:1024
	ds_read_b128 v[158:161], v162 offset:2048
	ds_read_b128 v[162:165], v162 offset:3072
	ds_read_b128 v[166:169], v178
	ds_read_b128 v[170:173], v178 offset:1024
	ds_read_b128 v[174:177], v178 offset:2048
	ds_read_b128 v[178:181], v178 offset:3072
	s_mov_b64 s[100:101], s[38:39]
	s_add_u32 s38, s38, 0x20000
	s_addc_u32 s39, s39, 0
	s_mov_b32 m0, s7
	ds_read_b128 v[182:185], v153 offset:32768
	ds_read_b128 v[186:189], v153 offset:33792
	ds_read_b128 v[190:193], v153 offset:34816
	ds_read_b128 v[194:197], v153 offset:35840
	ds_read_b128 v[198:201], v153 offset:36864
	ds_read_b128 v[202:205], v153 offset:37888
	ds_read_b128 v[206:209], v153 offset:38912
	ds_read_b128 v[210:213], v153 offset:39936
	s_mov_b32 m0, s5
	s_nop 0
	global_load_lds_dwordx4 v128, s[100:101]
	s_mov_b32 m0, s6
	s_nop 0
	global_load_lds_dwordx4 v132, s[100:101]
	s_mov_b32 m0, s7
	s_nop 0
	global_load_lds_dwordx4 v128, s[38:39]
	s_mov_b32 m0, s33
	s_nop 0
	global_load_lds_dwordx4 v132, s[38:39]
	s_waitcnt vmcnt(8) lgkmcnt(0)
	s_barrier
	s_setprio 1
	v_mfma_f32_16x16x32_bf16 v[124:127], v[144:147], v[182:185], v[124:127]
	v_mfma_f32_16x16x32_bf16 v[120:123], v[158:161], v[182:185], v[120:123]
	v_mfma_f32_16x16x32_bf16 v[108:111], v[144:147], v[190:193], v[108:111]
	v_mfma_f32_16x16x32_bf16 v[104:107], v[158:161], v[190:193], v[104:107]
	v_mfma_f32_16x16x32_bf16 v[92:95], v[144:147], v[198:201], v[92:95]
	v_mfma_f32_16x16x32_bf16 v[88:91], v[158:161], v[198:201], v[88:91]
	v_mfma_f32_16x16x32_bf16 v[76:79], v[144:147], v[206:209], v[76:79]
	v_mfma_f32_16x16x32_bf16 v[72:75], v[158:161], v[206:209], v[72:75]
	v_mfma_f32_16x16x32_bf16 v[124:127], v[154:157], v[186:189], v[124:127]
	v_mfma_f32_16x16x32_bf16 v[120:123], v[162:165], v[186:189], v[120:123]
	v_mfma_f32_16x16x32_bf16 v[108:111], v[154:157], v[194:197], v[108:111]
	v_mfma_f32_16x16x32_bf16 v[104:107], v[162:165], v[194:197], v[104:107]
	v_mfma_f32_16x16x32_bf16 v[92:95], v[154:157], v[202:205], v[92:95]
	v_mfma_f32_16x16x32_bf16 v[88:91], v[162:165], v[202:205], v[88:91]
	v_mfma_f32_16x16x32_bf16 v[76:79], v[154:157], v[210:213], v[76:79]
	v_mfma_f32_16x16x32_bf16 v[72:75], v[162:165], v[210:213], v[72:75]
	s_setprio 0
	s_setprio 1
	v_mfma_f32_16x16x32_bf16 v[116:119], v[166:169], v[182:185], v[116:119]
	v_mfma_f32_16x16x32_bf16 v[112:115], v[174:177], v[182:185], v[112:115]
	v_mfma_f32_16x16x32_bf16 v[100:103], v[166:169], v[190:193], v[100:103]
	v_mfma_f32_16x16x32_bf16 v[96:99], v[174:177], v[190:193], v[96:99]
	v_mfma_f32_16x16x32_bf16 v[84:87], v[166:169], v[198:201], v[84:87]
	v_mfma_f32_16x16x32_bf16 v[80:83], v[174:177], v[198:201], v[80:83]
	v_mfma_f32_16x16x32_bf16 v[68:71], v[166:169], v[206:209], v[68:71]
	v_mfma_f32_16x16x32_bf16 v[64:67], v[174:177], v[206:209], v[64:67]
	v_mfma_f32_16x16x32_bf16 v[116:119], v[170:173], v[186:189], v[116:119]
	v_mfma_f32_16x16x32_bf16 v[112:115], v[178:181], v[186:189], v[112:115]
	v_mfma_f32_16x16x32_bf16 v[100:103], v[170:173], v[194:197], v[100:103]
	v_mfma_f32_16x16x32_bf16 v[96:99], v[178:181], v[194:197], v[96:99]
	v_mfma_f32_16x16x32_bf16 v[84:87], v[170:173], v[202:205], v[84:87]
	v_mfma_f32_16x16x32_bf16 v[80:83], v[178:181], v[202:205], v[80:83]
	v_mfma_f32_16x16x32_bf16 v[68:71], v[170:173], v[210:213], v[68:71]
	v_mfma_f32_16x16x32_bf16 v[64:67], v[178:181], v[210:213], v[64:67]
	s_setprio 0
	s_barrier
	s_add_i32 s38, s58, s4
	s_add_u32 s98, s34, 0x80
	s_addc_u32 s99, s35, 0
	s_mov_b32 m0, s38
	ds_read_b128 v[182:185], v153 offset:49152
	ds_read_b128 v[186:189], v153 offset:50176
	ds_read_b128 v[190:193], v153 offset:51200
	ds_read_b128 v[194:197], v153 offset:52224
	ds_read_b128 v[198:201], v153 offset:53248
	ds_read_b128 v[202:205], v153 offset:54272
	ds_read_b128 v[206:209], v153 offset:55296
	ds_read_b128 v[210:213], v153 offset:56320
	global_load_lds_dwordx4 v130, s[98:99]
	s_add_i32 m0, s38, 0x2000
	s_add_u32 s34, s34, 0x20080
	s_addc_u32 s35, s35, 0
	s_add_i32 s38, s59, s4
	global_load_lds_dwordx4 v134, s[98:99]
	s_mov_b32 m0, s38
	s_nop 0
	global_load_lds_dwordx4 v130, s[34:35]
	s_add_i32 m0, s38, 0x2000
	s_nop 0
	global_load_lds_dwordx4 v134, s[34:35]
	s_waitcnt vmcnt(6) lgkmcnt(0)
	s_barrier
	s_setprio 1
	v_mfma_f32_16x16x32_bf16 v[60:63], v[144:147], v[182:185], v[60:63]
	v_mfma_f32_16x16x32_bf16 v[56:59], v[158:161], v[182:185], v[56:59]
	v_mfma_f32_16x16x32_bf16 v[44:47], v[144:147], v[190:193], v[44:47]
	v_mfma_f32_16x16x32_bf16 v[40:43], v[158:161], v[190:193], v[40:43]
	v_mfma_f32_16x16x32_bf16 v[28:31], v[144:147], v[198:201], v[28:31]
	v_mfma_f32_16x16x32_bf16 v[24:27], v[158:161], v[198:201], v[24:27]
	v_mfma_f32_16x16x32_bf16 v[12:15], v[144:147], v[206:209], v[12:15]
	v_mfma_f32_16x16x32_bf16 v[8:11], v[158:161], v[206:209], v[8:11]
	v_mfma_f32_16x16x32_bf16 v[60:63], v[154:157], v[186:189], v[60:63]
	v_mfma_f32_16x16x32_bf16 v[56:59], v[162:165], v[186:189], v[56:59]
	v_mfma_f32_16x16x32_bf16 v[44:47], v[154:157], v[194:197], v[44:47]
	v_mfma_f32_16x16x32_bf16 v[40:43], v[162:165], v[194:197], v[40:43]
	v_mfma_f32_16x16x32_bf16 v[28:31], v[154:157], v[202:205], v[28:31]
	v_mfma_f32_16x16x32_bf16 v[24:27], v[162:165], v[202:205], v[24:27]
	v_mfma_f32_16x16x32_bf16 v[12:15], v[154:157], v[210:213], v[12:15]
	v_mfma_f32_16x16x32_bf16 v[8:11], v[162:165], v[210:213], v[8:11]
	s_setprio 0
	s_setprio 1
	v_mfma_f32_16x16x32_bf16 v[52:55], v[166:169], v[182:185], v[52:55]
	v_mfma_f32_16x16x32_bf16 v[48:51], v[174:177], v[182:185], v[48:51]
	v_mfma_f32_16x16x32_bf16 v[36:39], v[166:169], v[190:193], v[36:39]
	v_mfma_f32_16x16x32_bf16 v[32:35], v[174:177], v[190:193], v[32:35]
	v_mfma_f32_16x16x32_bf16 v[20:23], v[166:169], v[198:201], v[20:23]
	v_mfma_f32_16x16x32_bf16 v[16:19], v[174:177], v[198:201], v[16:19]
	v_mfma_f32_16x16x32_bf16 v[4:7], v[166:169], v[206:209], v[4:7]
	v_mfma_f32_16x16x32_bf16 v[0:3], v[174:177], v[206:209], v[0:3]
	v_mfma_f32_16x16x32_bf16 v[52:55], v[170:173], v[186:189], v[52:55]
	v_mfma_f32_16x16x32_bf16 v[48:51], v[178:181], v[186:189], v[48:51]
	v_mfma_f32_16x16x32_bf16 v[36:39], v[170:173], v[194:197], v[36:39]
	v_mfma_f32_16x16x32_bf16 v[32:35], v[178:181], v[194:197], v[32:35]
	v_mfma_f32_16x16x32_bf16 v[20:23], v[170:173], v[202:205], v[20:23]
	v_mfma_f32_16x16x32_bf16 v[16:19], v[178:181], v[202:205], v[16:19]
	v_mfma_f32_16x16x32_bf16 v[4:7], v[170:173], v[210:213], v[4:7]
	v_mfma_f32_16x16x32_bf16 v[0:3], v[178:181], v[210:213], v[0:3]
	s_setprio 0
	s_barrier
	s_add_i32 s57, s57, 2
	s_add_u32 s20, s20, 0x100
	s_addc_u32 s21, s21, 0
	s_add_u32 s53, s53, 0x100
	s_addc_u32 s56, s56, 0
	s_cmp_gt_u32 s57, 5
	s_cbranch_scc0 .LBB0_1738
	s_and_b64 vcc, exec, s[22:23]
	s_cbranch_vccz .LBB0_1741
	s_barrier

; #define PG8_STAGE(bufoff, gbase, voff) do { _Pragma("unroll") for (int _i = 0; _i < 2; ++_i) \
;         __builtin_amdgcn_global_load_lds((const unsigned*)((const char*)(gbase) + (voff)[_i]), (PG8_LAS unsigned*)(lds + (bufoff) + ldsw + _i * 8192), 16, 0, 0); } while (0)
; #define PG8_LDA(dst, b, h) do { _Pragma("unroll") for (int m = 0; m < 4; ++m) _Pragma("unroll") for (int k = 0; k < 2; ++k) dst[m][k] = *(const PG8_LAS bf16x8*)(lds + PG8_SA(b, h) + aoff + m * 2048 + k * 1024); } while (0)
; #define PG8_LDB(dst, b, h) do { _Pragma("unroll") for (int n = 0; n < 2; ++n) _Pragma("unroll") for (int k = 0; k < 2; ++k) dst[n][k] = *(const PG8_LAS bf16x8*)(lds + PG8_SB(b, h) + boff + n * 2048 + k * 1024); } while (0)
; #define PG8_WAIT_V(n) asm volatile("s_waitcnt vmcnt(" #n ")" ::: "memory")
; #define PG8_WAIT_L(n) asm volatile("s_waitcnt lgkmcnt(" #n ")" ::: "memory")
; template <class Epi, class Sched, bool ALIGN_EPI = false, bool SP2 = false>
; __device__ __forceinline__ void gemm_phase(PG8_LAS unsigned char* lds, const Gemm g, const Sched& S, const Epi& E) {
;     ...
;         for (int t = 0; t < nt; t += 2) {
;             const bool last = (t == nt - 2);
;             if constexpr (Epi::HAS_MID) { if (t == E.mid_t) E.mid(acc, cur, wr, wc, fr, fq); }
;             const char* a1 = cA + (size_t)(t + 1) * kstep;
;             const char* a2 = last ? nA : cA + (size_t)(t + 2) * kstep; const char* b2 = last ? nB : cB + (size_t)(t + 2) * kstep;
;             const char* a3 = a2 + kstep; const char* b3 = b2 + kstep;
;             if (last && has_next) S.a_ready(nxt);
;             if constexpr (SP2) {
;             PG8_LDB(B0, 0, 0); PG8_LDB(B1, 0, 1); PG8_SCHED; PG8_LDA(At, 0, 0); PG8_STAGE(PG8_SA(1, 1), a1 + hstepA, voffA);
;             PG8_WAIT_V(8); PG8_WAIT_L(0); PG8_BAR; PG8_MMA(0, 0, At, B0); PG8_MMA(0, 1, At, B1); PG8_BAR; PG8_SCHED;
;             PG8_LDA(At, 0, 1); PG8_STAGE(PG8_SB(0, 0), b2, voffB); PG8_STAGE(PG8_SB(0, 1), b2 + hstepB, voffB); PG8_STAGE(PG8_SA(0, 0), a2, voffA);
;             PG8_WAIT_V(8); PG8_WAIT_L(0); PG8_BAR; PG8_MMA(1, 0, At, B0); PG8_MMA(1, 1, At, B1); PG8_BAR; PG8_SCHED;
;             PG8_LDB(B0, 1, 0); PG8_LDB(B1, 1, 1); PG8_SCHED; PG8_LDA(At, 1, 0); PG8_STAGE(PG8_SA(0, 1), a2 + hstepA, voffA);
;             PG8_WAIT_V(8); PG8_WAIT_L(0); PG8_BAR; PG8_MMA(0, 0, At, B0); PG8_MMA(0, 1, At, B1); PG8_BAR; PG8_SCHED;
.Lp7_full_loop:
.LBB0_1824:
	ds_read_b128 v[144:147], v151
	ds_read_b128 v[156:159], v151 offset:1024
	ds_read_b128 v[160:163], v151 offset:2048
	ds_read_b128 v[164:167], v151 offset:3072
	ds_read_b128 v[168:171], v152
	ds_read_b128 v[172:175], v152 offset:1024
	ds_read_b128 v[176:179], v152 offset:2048
	ds_read_b128 v[180:183], v152 offset:3072
	s_add_u32 s34, s30, 0xfff80080
	s_addc_u32 s35, s31, -1
	s_cmp_eq_u32 s62, 28
	s_cselect_b32 s39, s21, s35
	s_cselect_b32 s38, s25, s34
	s_cselect_b32 s35, s23, s61
	s_cselect_b32 s34, s59, s60
	ds_read_b128 v[184:187], v153
	ds_read_b128 v[188:191], v153 offset:1024
	ds_read_b128 v[192:195], v153 offset:2048
	ds_read_b128 v[196:199], v153 offset:3072
	ds_read_b128 v[200:203], v153 offset:4096
	ds_read_b128 v[204:207], v153 offset:5120
	ds_read_b128 v[208:211], v153 offset:6144
	ds_read_b128 v[212:215], v153 offset:7168
	s_add_u32 s98, s30, 0xfff80000
	s_addc_u32 s99, s31, -1
	s_mov_b32 m0, s46
	s_nop 0
	global_load_lds_dwordx4 v134, s[98:99]
	s_mov_b32 m0, s47
	s_nop 0
	global_load_lds_dwordx4 v130, s[98:99]
	s_add_i32 m0, s6, 0xc000
	s_nop 0
	global_load_lds_dwordx4 v136, s[30:31]
	s_add_i32 m0, s6, 0xe000
	s_nop 0
	global_load_lds_dwordx4 v138, s[30:31]
	s_waitcnt vmcnt(8) lgkmcnt(0)
	s_barrier
	s_setprio 1
	v_mfma_f32_16x16x32_bf16 v[124:127], v[144:147], v[184:187], v[124:127]
	v_mfma_f32_16x16x32_bf16 v[116:119], v[160:163], v[184:187], v[116:119]
	v_mfma_f32_16x16x32_bf16 v[108:111], v[144:147], v[192:195], v[108:111]
	v_mfma_f32_16x16x32_bf16 v[100:103], v[160:163], v[192:195], v[100:103]
	v_mfma_f32_16x16x32_bf16 v[92:95], v[144:147], v[200:203], v[92:95]
	v_mfma_f32_16x16x32_bf16 v[84:87], v[160:163], v[200:203], v[84:87]
	v_mfma_f32_16x16x32_bf16 v[76:79], v[144:147], v[208:211], v[76:79]
	v_mfma_f32_16x16x32_bf16 v[68:71], v[160:163], v[208:211], v[68:71]
	v_mfma_f32_16x16x32_bf16 v[124:127], v[156:159], v[188:191], v[124:127]
	v_mfma_f32_16x16x32_bf16 v[116:119], v[164:167], v[188:191], v[116:119]
	v_mfma_f32_16x16x32_bf16 v[108:111], v[156:159], v[196:199], v[108:111]
	v_mfma_f32_16x16x32_bf16 v[100:103], v[164:167], v[196:199], v[100:103]
	v_mfma_f32_16x16x32_bf16 v[92:95], v[156:159], v[204:207], v[92:95]
	v_mfma_f32_16x16x32_bf16 v[84:87], v[164:167], v[204:207], v[84:87]
	v_mfma_f32_16x16x32_bf16 v[76:79], v[156:159], v[212:215], v[76:79]
	v_mfma_f32_16x16x32_bf16 v[68:71], v[164:167], v[212:215], v[68:71]
	s_setprio 0
	s_setprio 1
	v_mfma_f32_16x16x32_bf16 v[120:123], v[168:171], v[184:187], v[120:123]
	v_mfma_f32_16x16x32_bf16 v[112:115], v[176:179], v[184:187], v[112:115]
	v_mfma_f32_16x16x32_bf16 v[104:107], v[168:171], v[192:195], v[104:107]
	v_mfma_f32_16x16x32_bf16 v[96:99], v[176:179], v[192:195], v[96:99]
	v_mfma_f32_16x16x32_bf16 v[88:91], v[168:171], v[200:203], v[88:91]
	v_mfma_f32_16x16x32_bf16 v[80:83], v[176:179], v[200:203], v[80:83]
	v_mfma_f32_16x16x32_bf16 v[72:75], v[168:171], v[208:211], v[72:75]
	v_mfma_f32_16x16x32_bf16 v[64:67], v[176:179], v[208:211], v[64:67]
	v_mfma_f32_16x16x32_bf16 v[120:123], v[172:175], v[188:191], v[120:123]
	v_mfma_f32_16x16x32_bf16 v[112:115], v[180:183], v[188:191], v[112:115]
	v_mfma_f32_16x16x32_bf16 v[104:107], v[172:175], v[196:199], v[104:107]
	v_mfma_f32_16x16x32_bf16 v[96:99], v[180:183], v[196:199], v[96:99]
	v_mfma_f32_16x16x32_bf16 v[88:91], v[172:175], v[204:207], v[88:91]
	v_mfma_f32_16x16x32_bf16 v[80:83], v[180:183], v[204:207], v[80:83]
	v_mfma_f32_16x16x32_bf16 v[72:75], v[172:175], v[212:215], v[72:75]
	v_mfma_f32_16x16x32_bf16 v[64:67], v[180:183], v[212:215], v[64:67]
	s_setprio 0
	s_barrier
	s_add_i32 s63, s53, s4
	s_mov_b32 m0, s63
	ds_read_b128 v[184:187], v153 offset:16384
	ds_read_b128 v[188:191], v153 offset:17408
	ds_read_b128 v[192:195], v153 offset:18432
	ds_read_b128 v[196:199], v153 offset:19456
	ds_read_b128 v[200:203], v153 offset:20480
	ds_read_b128 v[204:207], v153 offset:21504
	ds_read_b128 v[208:211], v153 offset:22528
	ds_read_b128 v[212:215], v153 offset:23552
	global_load_lds_dwordx4 v132, s[34:35]
	s_add_i32 m0, s63, 0x2000
	s_add_u32 s64, s34, 0x80000
	s_addc_u32 s65, s35, 0
	s_add_i32 s63, s54, s4
	global_load_lds_dwordx4 v128, s[34:35]
	s_mov_b32 m0, s63
	s_nop 0
	global_load_lds_dwordx4 v132, s[64:65]
	s_add_i32 m0, s63, 0x2000
	s_nop 0
	global_load_lds_dwordx4 v128, s[64:65]
	s_waitcnt vmcnt(6) lgkmcnt(0)
	s_barrier
	s_setprio 1
	v_mfma_f32_16x16x32_bf16 v[60:63], v[144:147], v[184:187], v[60:63]
	v_mfma_f32_16x16x32_bf16 v[52:55], v[160:163], v[184:187], v[52:55]
	v_mfma_f32_16x16x32_bf16 v[44:47], v[144:147], v[192:195], v[44:47]
	v_mfma_f32_16x16x32_bf16 v[36:39], v[160:163], v[192:195], v[36:39]
	v_mfma_f32_16x16x32_bf16 v[28:31], v[144:147], v[200:203], v[28:31]
	v_mfma_f32_16x16x32_bf16 v[20:23], v[160:163], v[200:203], v[20:23]
	v_mfma_f32_16x16x32_bf16 v[12:15], v[144:147], v[208:211], v[12:15]
	v_mfma_f32_16x16x32_bf16 v[4:7], v[160:163], v[208:211], v[4:7]
	v_mfma_f32_16x16x32_bf16 v[60:63], v[156:159], v[188:191], v[60:63]
	v_mfma_f32_16x16x32_bf16 v[52:55], v[164:167], v[188:191], v[52:55]
	v_mfma_f32_16x16x32_bf16 v[44:47], v[156:159], v[196:199], v[44:47]
	v_mfma_f32_16x16x32_bf16 v[36:39], v[164:167], v[196:199], v[36:39]
	v_mfma_f32_16x16x32_bf16 v[28:31], v[156:159], v[204:207], v[28:31]
	v_mfma_f32_16x16x32_bf16 v[20:23], v[164:167], v[204:207], v[20:23]
	v_mfma_f32_16x16x32_bf16 v[12:15], v[156:159], v[212:215], v[12:15]
	v_mfma_f32_16x16x32_bf16 v[4:7], v[164:167], v[212:215], v[4:7]
	s_setprio 0
	s_setprio 1
	v_mfma_f32_16x16x32_bf16 v[56:59], v[168:171], v[184:187], v[56:59]
	v_mfma_f32_16x16x32_bf16 v[48:51], v[176:179], v[184:187], v[48:51]
	v_mfma_f32_16x16x32_bf16 v[40:43], v[168:171], v[192:195], v[40:43]
	v_mfma_f32_16x16x32_bf16 v[32:35], v[176:179], v[192:195], v[32:35]
	v_mfma_f32_16x16x32_bf16 v[24:27], v[168:171], v[200:203], v[24:27]
	v_mfma_f32_16x16x32_bf16 v[16:19], v[176:179], v[200:203], v[16:19]
	v_mfma_f32_16x16x32_bf16 v[8:11], v[168:171], v[208:211], v[8:11]
	v_mfma_f32_16x16x32_bf16 v[0:3], v[176:179], v[208:211], v[0:3]
	v_mfma_f32_16x16x32_bf16 v[56:59], v[172:175], v[188:191], v[56:59]
	v_mfma_f32_16x16x32_bf16 v[48:51], v[180:183], v[188:191], v[48:51]
	v_mfma_f32_16x16x32_bf16 v[40:43], v[172:175], v[196:199], v[40:43]
	v_mfma_f32_16x16x32_bf16 v[32:35], v[180:183], v[196:199], v[32:35]
	v_mfma_f32_16x16x32_bf16 v[24:27], v[172:175], v[204:207], v[24:27]
	v_mfma_f32_16x16x32_bf16 v[16:19], v[180:183], v[204:207], v[16:19]
	v_mfma_f32_16x16x32_bf16 v[8:11], v[172:175], v[212:215], v[8:11]
	v_mfma_f32_16x16x32_bf16 v[0:3], v[180:183], v[212:215], v[0:3]
	s_setprio 0
	s_barrier
; #define PG8_STAGE(bufoff, gbase, voff) do { _Pragma("unroll") for (int _i = 0; _i < 2; ++_i) \
;         __builtin_amdgcn_global_load_lds((const unsigned*)((const char*)(gbase) + (voff)[_i]), (PG8_LAS unsigned*)(lds + (bufoff) + ldsw + _i * 8192), 16, 0, 0); } while (0)
; #define PG8_LDA(dst, b, h) do { _Pragma("unroll") for (int m = 0; m < 4; ++m) _Pragma("unroll") for (int k = 0; k < 2; ++k) dst[m][k] = *(const PG8_LAS bf16x8*)(lds + PG8_SA(b, h) + aoff + m * 2048 + k * 1024); } while (0)
; #define PG8_LDB(dst, b, h) do { _Pragma("unroll") for (int n = 0; n < 2; ++n) _Pragma("unroll") for (int k = 0; k < 2; ++k) dst[n][k] = *(const PG8_LAS bf16x8*)(lds + PG8_SB(b, h) + boff + n * 2048 + k * 1024); } while (0)
; #define PG8_MMA(ai, bj, At, Bt) do { __builtin_amdgcn_s_setprio(1); _Pragma("unroll") for (int m = 0; m < 4; ++m) _Pragma("unroll") for (int n = 0; n < 2; ++n) _Pragma("unroll") for (int k = 0; k < 2; ++k) \
;         acc[ai][bj][m][n] = __builtin_amdgcn_mfma_f32_16x16x32_bf16(Bt[n][k], At[m][k], acc[ai][bj][m][n], 0, 0, 0); __builtin_amdgcn_s_setprio(0); } while (0)
; #define PG8_WAIT_V(n) asm volatile("s_waitcnt vmcnt(" #n ")" ::: "memory")
; #define PG8_WAIT_L(n) asm volatile("s_waitcnt lgkmcnt(" #n ")" ::: "memory")
; #define PG8_BAR __builtin_amdgcn_s_barrier()
; #define PG8_SCHED __builtin_amdgcn_sched_barrier(0)
; template <class Epi, class Sched, bool ALIGN_EPI = false, bool SP2 = false>
; __device__ __forceinline__ void gemm_phase(PG8_LAS unsigned char* lds, const Gemm g, const Sched& S, const Epi& E) {
;     ...
;             PG8_LDB(B0, 1, 0); PG8_LDB(B1, 1, 1); PG8_SCHED; PG8_LDA(At, 1, 0); PG8_STAGE(PG8_SA(0, 1), a2 + hstepA, voffA);
;             PG8_WAIT_V(8); PG8_WAIT_L(0); PG8_BAR; PG8_MMA(0, 0, At, B0); PG8_MMA(0, 1, At, B1); PG8_BAR; PG8_SCHED;
;             PG8_LDA(At, 1, 1); PG8_STAGE(PG8_SB(1, 0), b3, voffB); PG8_STAGE(PG8_SB(1, 1), b3 + hstepB, voffB); PG8_STAGE(PG8_SA(1, 0), a3, voffA);
;             PG8_WAIT_V(8); PG8_WAIT_L(0); PG8_BAR; PG8_MMA(1, 0, At, B0); PG8_MMA(1, 1, At, B1); PG8_BAR; PG8_SCHED;
	s_add_i32 s63, 0, 0x18000
	v_add_u32_e32 v155, s63, v150
	s_add_i32 s64, 0, 0x1c000
	ds_read_b128 v[144:147], v155
	ds_read_b128 v[156:159], v155 offset:1024
	ds_read_b128 v[160:163], v155 offset:2048
	ds_read_b128 v[164:167], v155 offset:3072
	v_add_u32_e32 v155, s64, v150
	ds_read_b128 v[168:171], v155
	ds_read_b128 v[172:175], v155 offset:1024
	ds_read_b128 v[176:179], v155 offset:2048
	ds_read_b128 v[180:183], v155 offset:3072
	s_mov_b64 s[100:101], s[38:39]
	s_add_u32 s38, s38, 0x80000
	s_addc_u32 s39, s39, 0
	ds_read_b128 v[184:187], v153 offset:32768
	ds_read_b128 v[188:191], v153 offset:33792
	ds_read_b128 v[192:195], v153 offset:34816
	ds_read_b128 v[196:199], v153 offset:35840
	ds_read_b128 v[200:203], v153 offset:36864
	ds_read_b128 v[204:207], v153 offset:37888
	ds_read_b128 v[208:211], v153 offset:38912
	ds_read_b128 v[212:215], v153 offset:39936
	s_mov_b32 m0, s6
	s_nop 0
	global_load_lds_dwordx4 v134, s[100:101]
	s_mov_b32 m0, s7
	s_nop 0
	global_load_lds_dwordx4 v130, s[100:101]
	s_mov_b32 m0, s41
	s_nop 0
	global_load_lds_dwordx4 v134, s[38:39]
	s_mov_b32 m0, s42
	s_nop 0
	global_load_lds_dwordx4 v130, s[38:39]
	s_waitcnt vmcnt(8) lgkmcnt(0)
	s_barrier
	s_setprio 1
	v_mfma_f32_16x16x32_bf16 v[124:127], v[144:147], v[184:187], v[124:127]
	v_mfma_f32_16x16x32_bf16 v[116:119], v[160:163], v[184:187], v[116:119]
	v_mfma_f32_16x16x32_bf16 v[108:111], v[144:147], v[192:195], v[108:111]
	v_mfma_f32_16x16x32_bf16 v[100:103], v[160:163], v[192:195], v[100:103]
	v_mfma_f32_16x16x32_bf16 v[92:95], v[144:147], v[200:203], v[92:95]
	v_mfma_f32_16x16x32_bf16 v[84:87], v[160:163], v[200:203], v[84:87]
	v_mfma_f32_16x16x32_bf16 v[76:79], v[144:147], v[208:211], v[76:79]
	v_mfma_f32_16x16x32_bf16 v[68:71], v[160:163], v[208:211], v[68:71]
	v_mfma_f32_16x16x32_bf16 v[124:127], v[156:159], v[188:191], v[124:127]
	v_mfma_f32_16x16x32_bf16 v[116:119], v[164:167], v[188:191], v[116:119]
	v_mfma_f32_16x16x32_bf16 v[108:111], v[156:159], v[196:199], v[108:111]
	v_mfma_f32_16x16x32_bf16 v[100:103], v[164:167], v[196:199], v[100:103]
	v_mfma_f32_16x16x32_bf16 v[92:95], v[156:159], v[204:207], v[92:95]
	v_mfma_f32_16x16x32_bf16 v[84:87], v[164:167], v[204:207], v[84:87]
	v_mfma_f32_16x16x32_bf16 v[76:79], v[156:159], v[212:215], v[76:79]
	v_mfma_f32_16x16x32_bf16 v[68:71], v[164:167], v[212:215], v[68:71]
	s_setprio 0
	s_setprio 1
	v_mfma_f32_16x16x32_bf16 v[120:123], v[168:171], v[184:187], v[120:123]
	v_mfma_f32_16x16x32_bf16 v[112:115], v[176:179], v[184:187], v[112:115]
	v_mfma_f32_16x16x32_bf16 v[104:107], v[168:171], v[192:195], v[104:107]
	v_mfma_f32_16x16x32_bf16 v[96:99], v[176:179], v[192:195], v[96:99]
	v_mfma_f32_16x16x32_bf16 v[88:91], v[168:171], v[200:203], v[88:91]
	v_mfma_f32_16x16x32_bf16 v[80:83], v[176:179], v[200:203], v[80:83]
	v_mfma_f32_16x16x32_bf16 v[72:75], v[168:171], v[208:211], v[72:75]
	v_mfma_f32_16x16x32_bf16 v[64:67], v[176:179], v[208:211], v[64:67]
	v_mfma_f32_16x16x32_bf16 v[120:123], v[172:175], v[188:191], v[120:123]
	v_mfma_f32_16x16x32_bf16 v[112:115], v[180:183], v[188:191], v[112:115]
	v_mfma_f32_16x16x32_bf16 v[104:107], v[172:175], v[196:199], v[104:107]
	v_mfma_f32_16x16x32_bf16 v[96:99], v[180:183], v[196:199], v[96:99]
	v_mfma_f32_16x16x32_bf16 v[88:91], v[172:175], v[204:207], v[88:91]
	v_mfma_f32_16x16x32_bf16 v[80:83], v[180:183], v[204:207], v[80:83]
	v_mfma_f32_16x16x32_bf16 v[72:75], v[172:175], v[212:215], v[72:75]
	v_mfma_f32_16x16x32_bf16 v[64:67], v[180:183], v[212:215], v[64:67]
	s_setprio 0
	s_barrier
	s_add_i32 s38, s63, s4
	s_add_u32 s98, s34, 0x80
	s_addc_u32 s99, s35, 0
	s_mov_b32 m0, s38
	ds_read_b128 v[184:187], v153 offset:49152
	ds_read_b128 v[188:191], v153 offset:50176
	ds_read_b128 v[192:195], v153 offset:51200
	ds_read_b128 v[196:199], v153 offset:52224
	ds_read_b128 v[200:203], v153 offset:53248
	ds_read_b128 v[204:207], v153 offset:54272
	ds_read_b128 v[208:211], v153 offset:55296
	ds_read_b128 v[212:215], v153 offset:56320
	global_load_lds_dwordx4 v132, s[98:99]
	s_add_i32 m0, s38, 0x2000
	s_add_u32 s34, s34, 0x80080
	s_addc_u32 s35, s35, 0
	s_add_i32 s38, s64, s4
	global_load_lds_dwordx4 v128, s[98:99]
	s_mov_b32 m0, s38
	s_nop 0
	global_load_lds_dwordx4 v132, s[34:35]
	s_add_i32 m0, s38, 0x2000
	s_nop 0
	global_load_lds_dwordx4 v128, s[34:35]
	s_waitcnt vmcnt(6) lgkmcnt(0)
	s_barrier
	s_setprio 1
	v_mfma_f32_16x16x32_bf16 v[60:63], v[144:147], v[184:187], v[60:63]
	v_mfma_f32_16x16x32_bf16 v[52:55], v[160:163], v[184:187], v[52:55]
	v_mfma_f32_16x16x32_bf16 v[44:47], v[144:147], v[192:195], v[44:47]
	v_mfma_f32_16x16x32_bf16 v[36:39], v[160:163], v[192:195], v[36:39]
	v_mfma_f32_16x16x32_bf16 v[28:31], v[144:147], v[200:203], v[28:31]
	v_mfma_f32_16x16x32_bf16 v[20:23], v[160:163], v[200:203], v[20:23]
	v_mfma_f32_16x16x32_bf16 v[12:15], v[144:147], v[208:211], v[12:15]
	v_mfma_f32_16x16x32_bf16 v[4:7], v[160:163], v[208:211], v[4:7]
	v_mfma_f32_16x16x32_bf16 v[60:63], v[156:159], v[188:191], v[60:63]
	v_mfma_f32_16x16x32_bf16 v[52:55], v[164:167], v[188:191], v[52:55]
	v_mfma_f32_16x16x32_bf16 v[44:47], v[156:159], v[196:199], v[44:47]
	v_mfma_f32_16x16x32_bf16 v[36:39], v[164:167], v[196:199], v[36:39]
	v_mfma_f32_16x16x32_bf16 v[28:31], v[156:159], v[204:207], v[28:31]
	v_mfma_f32_16x16x32_bf16 v[20:23], v[164:167], v[204:207], v[20:23]
	v_mfma_f32_16x16x32_bf16 v[12:15], v[156:159], v[212:215], v[12:15]
	v_mfma_f32_16x16x32_bf16 v[4:7], v[164:167], v[212:215], v[4:7]
	s_setprio 0
	s_setprio 1
	v_mfma_f32_16x16x32_bf16 v[56:59], v[168:171], v[184:187], v[56:59]
	v_mfma_f32_16x16x32_bf16 v[48:51], v[176:179], v[184:187], v[48:51]
	v_mfma_f32_16x16x32_bf16 v[40:43], v[168:171], v[192:195], v[40:43]
	v_mfma_f32_16x16x32_bf16 v[32:35], v[176:179], v[192:195], v[32:35]
	v_mfma_f32_16x16x32_bf16 v[24:27], v[168:171], v[200:203], v[24:27]
	v_mfma_f32_16x16x32_bf16 v[16:19], v[176:179], v[200:203], v[16:19]
	v_mfma_f32_16x16x32_bf16 v[8:11], v[168:171], v[208:211], v[8:11]
	v_mfma_f32_16x16x32_bf16 v[0:3], v[176:179], v[208:211], v[0:3]
	v_mfma_f32_16x16x32_bf16 v[56:59], v[172:175], v[188:191], v[56:59]
	v_mfma_f32_16x16x32_bf16 v[48:51], v[180:183], v[188:191], v[48:51]
	v_mfma_f32_16x16x32_bf16 v[40:43], v[172:175], v[196:199], v[40:43]
	v_mfma_f32_16x16x32_bf16 v[32:35], v[180:183], v[196:199], v[32:35]
	v_mfma_f32_16x16x32_bf16 v[24:27], v[172:175], v[204:207], v[24:27]
	v_mfma_f32_16x16x32_bf16 v[16:19], v[180:183], v[204:207], v[16:19]
	v_mfma_f32_16x16x32_bf16 v[8:11], v[172:175], v[212:215], v[8:11]
	v_mfma_f32_16x16x32_bf16 v[0:3], v[180:183], v[212:215], v[0:3]
	s_setprio 0
	s_barrier
	s_add_i32 s62, s62, 2
	s_add_u32 s30, s30, 0x100
	s_addc_u32 s31, s31, 0
	s_add_u32 s60, s60, 0x100
	s_addc_u32 s61, s61, 0
	s_cmp_gt_u32 s62, 29
	s_cbranch_scc0 .LBB0_1824

; #define PG8_STAGE(bufoff, gbase, voff) do { _Pragma("unroll") for (int _i = 0; _i < 2; ++_i) \
;         __builtin_amdgcn_global_load_lds((const unsigned*)((const char*)(gbase) + (voff)[_i]), (PG8_LAS unsigned*)(lds + (bufoff) + ldsw + _i * 8192), 16, 0, 0); } while (0)
; #define PG8_LDA(dst, b, h) do { _Pragma("unroll") for (int m = 0; m < 4; ++m) _Pragma("unroll") for (int k = 0; k < 2; ++k) dst[m][k] = *(const PG8_LAS bf16x8*)(lds + PG8_SA(b, h) + aoff + m * 2048 + k * 1024); } while (0)
; #define PG8_LDB(dst, b, h) do { _Pragma("unroll") for (int n = 0; n < 2; ++n) _Pragma("unroll") for (int k = 0; k < 2; ++k) dst[n][k] = *(const PG8_LAS bf16x8*)(lds + PG8_SB(b, h) + boff + n * 2048 + k * 1024); } while (0)
; #define PG8_MMA(ai, bj, At, Bt) do { __builtin_amdgcn_s_setprio(1); _Pragma("unroll") for (int m = 0; m < 4; ++m) _Pragma("unroll") for (int n = 0; n < 2; ++n) _Pragma("unroll") for (int k = 0; k < 2; ++k) \
;         acc[ai][bj][m][n] = __builtin_amdgcn_mfma_f32_16x16x32_bf16(Bt[n][k], At[m][k], acc[ai][bj][m][n], 0, 0, 0); __builtin_amdgcn_s_setprio(0); } while (0)
; #define PG8_WAIT_V(n) asm volatile("s_waitcnt vmcnt(" #n ")" ::: "memory")
; #define PG8_WAIT_L(n) asm volatile("s_waitcnt lgkmcnt(" #n ")" ::: "memory")
; #define PG8_BAR __builtin_amdgcn_s_barrier()
; #define PG8_SCHED __builtin_amdgcn_sched_barrier(0)
; template <class Epi, class Sched, bool ALIGN_EPI = false, bool SP2 = false>
; __device__ __forceinline__ void gemm_phase(PG8_LAS unsigned char* lds, const Gemm g, const Sched& S, const Epi& E) {
;     ...
;             PG8_LDB(B0, 0, 0); PG8_LDB(B1, 0, 1); PG8_SCHED; PG8_LDA(At, 0, 0); PG8_STAGE(PG8_SA(1, 1), a1 + hstepA, voffA);
;             PG8_WAIT_V(8); PG8_WAIT_L(0); PG8_BAR; PG8_MMA(0, 0, At, B0); PG8_MMA(0, 1, At, B1); PG8_BAR; PG8_SCHED;
;             PG8_LDA(At, 0, 1); PG8_STAGE(PG8_SB(0, 0), b2, voffB); PG8_STAGE(PG8_SB(0, 1), b2 + hstepB, voffB); PG8_STAGE(PG8_SA(0, 0), a2, voffA);
;             PG8_WAIT_V(8); PG8_WAIT_L(0); PG8_BAR; PG8_MMA(1, 0, At, B0); PG8_MMA(1, 1, At, B1); PG8_BAR; PG8_SCHED;
;             PG8_LDB(B0, 1, 0); PG8_LDB(B1, 1, 1); PG8_SCHED; PG8_LDA(At, 1, 0); PG8_STAGE(PG8_SA(0, 1), a2 + hstepA, voffA);
;             PG8_WAIT_V(8); PG8_WAIT_L(0); PG8_BAR; PG8_MMA(0, 0, At, B0); PG8_MMA(0, 1, At, B1); PG8_BAR; PG8_SCHED;
.Lp7h_loop:
	ds_read_b128 v[144:147], v151
	ds_read_b128 v[156:159], v151 offset:1024
	ds_read_b128 v[160:163], v151 offset:2048
	ds_read_b128 v[164:167], v151 offset:3072
	ds_read_b128 v[168:171], v152
	ds_read_b128 v[172:175], v152 offset:1024
	ds_read_b128 v[176:179], v152 offset:2048
	ds_read_b128 v[180:183], v152 offset:3072
	s_add_u32 s34, s30, 0xfff80080
	s_addc_u32 s35, s31, -1
	s_cmp_eq_u32 s62, 28
	s_cselect_b32 s39, s21, s35
	s_cselect_b32 s38, s25, s34
	s_cselect_b32 s35, s23, s61
	s_cselect_b32 s34, s59, s60
	s_add_i32 m0, s6, 0xc000
	s_nop 0
	global_load_lds_dwordx4 v136, s[30:31]
	s_add_i32 m0, s6, 0xe000
	s_nop 0
	global_load_lds_dwordx4 v138, s[30:31]
	s_waitcnt vmcnt(6) lgkmcnt(0)
	s_barrier
	s_setprio 1
	s_waitcnt lgkmcnt(0)
	v_mfma_f32_16x16x32_bf16 v[56:59], v[80:83], v[184:187], v[56:59]
	v_mfma_f32_16x16x32_bf16 v[48:51], v[88:91], v[184:187], v[48:51]
	v_mfma_f32_16x16x32_bf16 v[40:43], v[80:83], v[192:195], v[40:43]
	v_mfma_f32_16x16x32_bf16 v[32:35], v[88:91], v[192:195], v[32:35]
	v_mfma_f32_16x16x32_bf16 v[24:27], v[80:83], v[200:203], v[24:27]
	v_mfma_f32_16x16x32_bf16 v[16:19], v[88:91], v[200:203], v[16:19]
	v_mfma_f32_16x16x32_bf16 v[8:11], v[80:83], v[208:211], v[8:11]
	v_mfma_f32_16x16x32_bf16 v[0:3], v[88:91], v[208:211], v[0:3]
	v_mfma_f32_16x16x32_bf16 v[56:59], v[84:87], v[188:191], v[56:59]
	v_mfma_f32_16x16x32_bf16 v[48:51], v[92:95], v[188:191], v[48:51]
	v_mfma_f32_16x16x32_bf16 v[40:43], v[84:87], v[196:199], v[40:43]
	v_mfma_f32_16x16x32_bf16 v[32:35], v[92:95], v[196:199], v[32:35]
	v_mfma_f32_16x16x32_bf16 v[24:27], v[84:87], v[204:207], v[24:27]
	v_mfma_f32_16x16x32_bf16 v[16:19], v[92:95], v[204:207], v[16:19]
	v_mfma_f32_16x16x32_bf16 v[8:11], v[84:87], v[212:215], v[8:11]
	v_mfma_f32_16x16x32_bf16 v[0:3], v[92:95], v[212:215], v[0:3]
	s_setprio 0
	s_setprio 1
	s_setprio 0
	s_barrier
	s_add_i32 s63, s53, s4
	s_mov_b32 m0, s63
	ds_read_b128 v[184:187], v153 offset:16384
	ds_read_b128 v[188:191], v153 offset:17408
	ds_read_b128 v[192:195], v153 offset:18432
	ds_read_b128 v[196:199], v153 offset:19456
	ds_read_b128 v[200:203], v153 offset:20480
	ds_read_b128 v[204:207], v153 offset:21504
	ds_read_b128 v[208:211], v153 offset:22528
	ds_read_b128 v[212:215], v153 offset:23552
	global_load_lds_dwordx4 v132, s[34:35]
	s_add_i32 m0, s63, 0x2000
	s_add_u32 s64, s34, 0x80000
	s_addc_u32 s65, s35, 0
	s_add_i32 s63, s54, s4
	global_load_lds_dwordx4 v128, s[34:35]
	s_mov_b32 m0, s63
	s_nop 0
	global_load_lds_dwordx4 v132, s[64:65]
	s_add_i32 m0, s63, 0x2000
	s_nop 0
	global_load_lds_dwordx4 v128, s[64:65]
	s_waitcnt vmcnt(6) lgkmcnt(0)
	s_barrier
	s_setprio 1
	s_waitcnt lgkmcnt(0)
	v_mfma_f32_16x16x32_bf16 v[60:63], v[144:147], v[184:187], v[60:63]
	v_mfma_f32_16x16x32_bf16 v[52:55], v[160:163], v[184:187], v[52:55]
	v_mfma_f32_16x16x32_bf16 v[44:47], v[144:147], v[192:195], v[44:47]
	v_mfma_f32_16x16x32_bf16 v[36:39], v[160:163], v[192:195], v[36:39]
	v_mfma_f32_16x16x32_bf16 v[28:31], v[144:147], v[200:203], v[28:31]
	v_mfma_f32_16x16x32_bf16 v[20:23], v[160:163], v[200:203], v[20:23]
	v_mfma_f32_16x16x32_bf16 v[12:15], v[144:147], v[208:211], v[12:15]
	v_mfma_f32_16x16x32_bf16 v[4:7], v[160:163], v[208:211], v[4:7]
	v_mfma_f32_16x16x32_bf16 v[60:63], v[156:159], v[188:191], v[60:63]
	v_mfma_f32_16x16x32_bf16 v[52:55], v[164:167], v[188:191], v[52:55]
	v_mfma_f32_16x16x32_bf16 v[44:47], v[156:159], v[196:199], v[44:47]
	v_mfma_f32_16x16x32_bf16 v[36:39], v[164:167], v[196:199], v[36:39]
	v_mfma_f32_16x16x32_bf16 v[28:31], v[156:159], v[204:207], v[28:31]
	v_mfma_f32_16x16x32_bf16 v[20:23], v[164:167], v[204:207], v[20:23]
	v_mfma_f32_16x16x32_bf16 v[12:15], v[156:159], v[212:215], v[12:15]
	v_mfma_f32_16x16x32_bf16 v[4:7], v[164:167], v[212:215], v[4:7]
	s_setprio 0
	s_setprio 1
	s_setprio 0
	s_barrier
	s_add_i32 s63, 0, 0x18000
	v_add_u32_e32 v155, s63, v150
	s_add_i32 s64, 0, 0x1c000
	ds_read_b128 v[64:67], v155
	ds_read_b128 v[68:71], v155 offset:1024
	ds_read_b128 v[72:75], v155 offset:2048
	ds_read_b128 v[76:79], v155 offset:3072
	v_add_u32_e32 v155, s64, v150
	ds_read_b128 v[80:83], v155
	ds_read_b128 v[84:87], v155 offset:1024
	ds_read_b128 v[88:91], v155 offset:2048
	ds_read_b128 v[92:95], v155 offset:3072
	s_add_u32 s38, s38, 0x80000
	s_addc_u32 s39, s39, 0
	s_mov_b32 m0, s41
	s_nop 0
	global_load_lds_dwordx4 v134, s[38:39]
	s_mov_b32 m0, s42
	s_nop 0
	global_load_lds_dwordx4 v130, s[38:39]
	s_waitcnt vmcnt(6) lgkmcnt(0)
	s_barrier
; #define PG8_STAGE(bufoff, gbase, voff) do { _Pragma("unroll") for (int _i = 0; _i < 2; ++_i) \
;         __builtin_amdgcn_global_load_lds((const unsigned*)((const char*)(gbase) + (voff)[_i]), (PG8_LAS unsigned*)(lds + (bufoff) + ldsw + _i * 8192), 16, 0, 0); } while (0)
; #define PG8_LDA(dst, b, h) do { _Pragma("unroll") for (int m = 0; m < 4; ++m) _Pragma("unroll") for (int k = 0; k < 2; ++k) dst[m][k] = *(const PG8_LAS bf16x8*)(lds + PG8_SA(b, h) + aoff + m * 2048 + k * 1024); } while (0)
; #define PG8_LDB(dst, b, h) do { _Pragma("unroll") for (int n = 0; n < 2; ++n) _Pragma("unroll") for (int k = 0; k < 2; ++k) dst[n][k] = *(const PG8_LAS bf16x8*)(lds + PG8_SB(b, h) + boff + n * 2048 + k * 1024); } while (0)
; #define PG8_MMA(ai, bj, At, Bt) do { __builtin_amdgcn_s_setprio(1); _Pragma("unroll") for (int m = 0; m < 4; ++m) _Pragma("unroll") for (int n = 0; n < 2; ++n) _Pragma("unroll") for (int k = 0; k < 2; ++k) \
;         acc[ai][bj][m][n] = __builtin_amdgcn_mfma_f32_16x16x32_bf16(Bt[n][k], At[m][k], acc[ai][bj][m][n], 0, 0, 0); __builtin_amdgcn_s_setprio(0); } while (0)
; #define PG8_WAIT_V(n) asm volatile("s_waitcnt vmcnt(" #n ")" ::: "memory")
; #define PG8_WAIT_L(n) asm volatile("s_waitcnt lgkmcnt(" #n ")" ::: "memory")
; #define PG8_BAR __builtin_amdgcn_s_barrier()
; #define PG8_SCHED __builtin_amdgcn_sched_barrier(0)
; template <class Epi, class Sched, bool ALIGN_EPI = false, bool SP2 = false>
; __device__ __forceinline__ void gemm_phase(PG8_LAS unsigned char* lds, const Gemm g, const Sched& S, const Epi& E) {
;     ...
;             PG8_LDB(B0, 1, 0); PG8_LDB(B1, 1, 1); PG8_SCHED; PG8_LDA(At, 1, 0); PG8_STAGE(PG8_SA(0, 1), a2 + hstepA, voffA);
;             PG8_WAIT_V(8); PG8_WAIT_L(0); PG8_BAR; PG8_MMA(0, 0, At, B0); PG8_MMA(0, 1, At, B1); PG8_BAR; PG8_SCHED;
;             PG8_LDA(At, 1, 1); PG8_STAGE(PG8_SB(1, 0), b3, voffB); PG8_STAGE(PG8_SB(1, 1), b3 + hstepB, voffB); PG8_STAGE(PG8_SA(1, 0), a3, voffA);
;             PG8_WAIT_V(8); PG8_WAIT_L(0); PG8_BAR; PG8_MMA(1, 0, At, B0); PG8_MMA(1, 1, At, B1); PG8_BAR; PG8_SCHED;
	s_setprio 1
	s_waitcnt lgkmcnt(0)
	v_mfma_f32_16x16x32_bf16 v[56:59], v[168:171], v[184:187], v[56:59]
	v_mfma_f32_16x16x32_bf16 v[48:51], v[176:179], v[184:187], v[48:51]
	v_mfma_f32_16x16x32_bf16 v[40:43], v[168:171], v[192:195], v[40:43]
	v_mfma_f32_16x16x32_bf16 v[32:35], v[176:179], v[192:195], v[32:35]
	v_mfma_f32_16x16x32_bf16 v[24:27], v[168:171], v[200:203], v[24:27]
	v_mfma_f32_16x16x32_bf16 v[16:19], v[176:179], v[200:203], v[16:19]
	v_mfma_f32_16x16x32_bf16 v[8:11], v[168:171], v[208:211], v[8:11]
	v_mfma_f32_16x16x32_bf16 v[0:3], v[176:179], v[208:211], v[0:3]
	v_mfma_f32_16x16x32_bf16 v[56:59], v[172:175], v[188:191], v[56:59]
	v_mfma_f32_16x16x32_bf16 v[48:51], v[180:183], v[188:191], v[48:51]
	v_mfma_f32_16x16x32_bf16 v[40:43], v[172:175], v[196:199], v[40:43]
	v_mfma_f32_16x16x32_bf16 v[32:35], v[180:183], v[196:199], v[32:35]
	v_mfma_f32_16x16x32_bf16 v[24:27], v[172:175], v[204:207], v[24:27]
	v_mfma_f32_16x16x32_bf16 v[16:19], v[180:183], v[204:207], v[16:19]
	v_mfma_f32_16x16x32_bf16 v[8:11], v[172:175], v[212:215], v[8:11]
	v_mfma_f32_16x16x32_bf16 v[0:3], v[180:183], v[212:215], v[0:3]
	s_setprio 0
	s_setprio 1
	s_setprio 0
	s_barrier
	s_add_i32 s38, s63, s4
	s_add_u32 s98, s34, 0x80
	s_addc_u32 s99, s35, 0
	s_mov_b32 m0, s38
	ds_read_b128 v[184:187], v153 offset:49152
	ds_read_b128 v[188:191], v153 offset:50176
	ds_read_b128 v[192:195], v153 offset:51200
	ds_read_b128 v[196:199], v153 offset:52224
	ds_read_b128 v[200:203], v153 offset:53248
	ds_read_b128 v[204:207], v153 offset:54272
	ds_read_b128 v[208:211], v153 offset:55296
	ds_read_b128 v[212:215], v153 offset:56320
	global_load_lds_dwordx4 v132, s[98:99]
	s_add_i32 m0, s38, 0x2000
	s_add_u32 s34, s34, 0x80080
	s_addc_u32 s35, s35, 0
	s_add_i32 s38, s64, s4
	global_load_lds_dwordx4 v128, s[98:99]
	s_mov_b32 m0, s38
	s_nop 0
	global_load_lds_dwordx4 v132, s[34:35]
	s_add_i32 m0, s38, 0x2000
	s_nop 0
	global_load_lds_dwordx4 v128, s[34:35]
	s_waitcnt vmcnt(6) lgkmcnt(0)
	s_barrier
	s_setprio 1
	s_waitcnt lgkmcnt(0)
	v_mfma_f32_16x16x32_bf16 v[60:63], v[64:67], v[184:187], v[60:63]
	v_mfma_f32_16x16x32_bf16 v[52:55], v[72:75], v[184:187], v[52:55]
	v_mfma_f32_16x16x32_bf16 v[44:47], v[64:67], v[192:195], v[44:47]
	v_mfma_f32_16x16x32_bf16 v[36:39], v[72:75], v[192:195], v[36:39]
	v_mfma_f32_16x16x32_bf16 v[28:31], v[64:67], v[200:203], v[28:31]
	v_mfma_f32_16x16x32_bf16 v[20:23], v[72:75], v[200:203], v[20:23]
	v_mfma_f32_16x16x32_bf16 v[12:15], v[64:67], v[208:211], v[12:15]
	v_mfma_f32_16x16x32_bf16 v[4:7], v[72:75], v[208:211], v[4:7]
	v_mfma_f32_16x16x32_bf16 v[60:63], v[68:71], v[188:191], v[60:63]
	v_mfma_f32_16x16x32_bf16 v[52:55], v[76:79], v[188:191], v[52:55]
	v_mfma_f32_16x16x32_bf16 v[44:47], v[68:71], v[196:199], v[44:47]
	v_mfma_f32_16x16x32_bf16 v[36:39], v[76:79], v[196:199], v[36:39]
	v_mfma_f32_16x16x32_bf16 v[28:31], v[68:71], v[204:207], v[28:31]
	v_mfma_f32_16x16x32_bf16 v[20:23], v[76:79], v[204:207], v[20:23]
	v_mfma_f32_16x16x32_bf16 v[12:15], v[68:71], v[212:215], v[12:15]
	v_mfma_f32_16x16x32_bf16 v[4:7], v[76:79], v[212:215], v[4:7]
	s_setprio 0
	s_setprio 1
	s_setprio 0
	s_barrier
	s_add_i32 s62, s62, 2
	s_add_u32 s30, s30, 0x100
	s_addc_u32 s31, s31, 0
	s_add_u32 s60, s60, 0x100
	s_addc_u32 s61, s61, 0
	s_cmp_gt_u32 s62, 29
	s_cbranch_scc0 .Lp7h_loop
	v_mfma_f32_16x16x32_bf16 v[56:59], v[80:83], v[184:187], v[56:59]
	v_mfma_f32_16x16x32_bf16 v[48:51], v[88:91], v[184:187], v[48:51]
	v_mfma_f32_16x16x32_bf16 v[40:43], v[80:83], v[192:195], v[40:43]
	v_mfma_f32_16x16x32_bf16 v[32:35], v[88:91], v[192:195], v[32:35]
	v_mfma_f32_16x16x32_bf16 v[24:27], v[80:83], v[200:203], v[24:27]
	v_mfma_f32_16x16x32_bf16 v[16:19], v[88:91], v[200:203], v[16:19]
	v_mfma_f32_16x16x32_bf16 v[8:11], v[80:83], v[208:211], v[8:11]
	v_mfma_f32_16x16x32_bf16 v[0:3], v[88:91], v[208:211], v[0:3]
	v_mfma_f32_16x16x32_bf16 v[56:59], v[84:87], v[188:191], v[56:59]
	v_mfma_f32_16x16x32_bf16 v[48:51], v[92:95], v[188:191], v[48:51]
	v_mfma_f32_16x16x32_bf16 v[40:43], v[84:87], v[196:199], v[40:43]
	v_mfma_f32_16x16x32_bf16 v[32:35], v[92:95], v[196:199], v[32:35]
	v_mfma_f32_16x16x32_bf16 v[24:27], v[84:87], v[204:207], v[24:27]
	v_mfma_f32_16x16x32_bf16 v[16:19], v[92:95], v[204:207], v[16:19]
	v_mfma_f32_16x16x32_bf16 v[8:11], v[84:87], v[212:215], v[8:11]
	v_mfma_f32_16x16x32_bf16 v[0:3], v[92:95], v[212:215], v[0:3]
	s_nop 15
	s_nop 15
	s_branch .Lp7_after_loop

; #define PG8_STAGE(bufoff, gbase, voff) do { _Pragma("unroll") for (int _i = 0; _i < 2; ++_i) \
;         __builtin_amdgcn_global_load_lds((const unsigned*)((const char*)(gbase) + (voff)[_i]), (PG8_LAS unsigned*)(lds + (bufoff) + ldsw + _i * 8192), 16, 0, 0); } while (0)
; #define PG8_LDA(dst, b, h) do { _Pragma("unroll") for (int m = 0; m < 4; ++m) _Pragma("unroll") for (int k = 0; k < 2; ++k) dst[m][k] = *(const PG8_LAS bf16x8*)(lds + PG8_SA(b, h) + aoff + m * 2048 + k * 1024); } while (0)
; #define PG8_LDB(dst, b, h) do { _Pragma("unroll") for (int n = 0; n < 2; ++n) _Pragma("unroll") for (int k = 0; k < 2; ++k) dst[n][k] = *(const PG8_LAS bf16x8*)(lds + PG8_SB(b, h) + boff + n * 2048 + k * 1024); } while (0)
; #define PG8_WAIT_V(n) asm volatile("s_waitcnt vmcnt(" #n ")" ::: "memory")
; #define PG8_WAIT_L(n) asm volatile("s_waitcnt lgkmcnt(" #n ")" ::: "memory")
; template <class Epi, class Sched, bool ALIGN_EPI = false, bool SP2 = false>
; __device__ __forceinline__ void gemm_phase(PG8_LAS unsigned char* lds, const Gemm g, const Sched& S, const Epi& E) {
;     ...
;         for (int t = 0; t < nt; t += 2) {
;             const bool last = (t == nt - 2);
;             if constexpr (Epi::HAS_MID) { if (t == E.mid_t) E.mid(acc, cur, wr, wc, fr, fq); }
;             const char* a1 = cA + (size_t)(t + 1) * kstep;
;             const char* a2 = last ? nA : cA + (size_t)(t + 2) * kstep; const char* b2 = last ? nB : cB + (size_t)(t + 2) * kstep;
;             const char* a3 = a2 + kstep; const char* b3 = b2 + kstep;
;             if (last && has_next) S.a_ready(nxt);
;             if constexpr (SP2) {
;             PG8_LDB(B0, 0, 0); PG8_LDB(B1, 0, 1); PG8_SCHED; PG8_LDA(At, 0, 0); PG8_STAGE(PG8_SA(1, 1), a1 + hstepA, voffA);
;             PG8_WAIT_V(8); PG8_WAIT_L(0); PG8_BAR; PG8_MMA(0, 0, At, B0); PG8_MMA(0, 1, At, B1); PG8_BAR; PG8_SCHED;
;             PG8_LDA(At, 0, 1); PG8_STAGE(PG8_SB(0, 0), b2, voffB); PG8_STAGE(PG8_SB(0, 1), b2 + hstepB, voffB); PG8_STAGE(PG8_SA(0, 0), a2, voffA);
;             PG8_WAIT_V(8); PG8_WAIT_L(0); PG8_BAR; PG8_MMA(1, 0, At, B0); PG8_MMA(1, 1, At, B1); PG8_BAR; PG8_SCHED;
;             PG8_LDB(B0, 1, 0); PG8_LDB(B1, 1, 1); PG8_SCHED; PG8_LDA(At, 1, 0); PG8_STAGE(PG8_SA(0, 1), a2 + hstepA, voffA);
;             PG8_WAIT_V(8); PG8_WAIT_L(0); PG8_BAR; PG8_MMA(0, 0, At, B0); PG8_MMA(0, 1, At, B1); PG8_BAR; PG8_SCHED;
.LBB0_1912:
	ds_read_b128 v[144:147], v151
	ds_read_b128 v[154:157], v151 offset:1024
	ds_read_b128 v[158:161], v151 offset:2048
	ds_read_b128 v[162:165], v151 offset:3072
	ds_read_b128 v[166:169], v152
	ds_read_b128 v[170:173], v152 offset:1024
	ds_read_b128 v[174:177], v152 offset:2048
	ds_read_b128 v[178:181], v152 offset:3072
	s_add_u32 s4, s40, 0x100
	s_addc_u32 s5, s41, 0
	s_cmpk_eq_i32 s65, 0x54
	s_cselect_b32 s47, s35, s5
	s_cselect_b32 s46, s34, s4
	s_cselect_b32 s43, s37, s64
	s_cselect_b32 s42, s36, s39
	ds_read_b128 v[182:185], v153
	ds_read_b128 v[186:189], v153 offset:1024
	ds_read_b128 v[190:193], v153 offset:2048
	ds_read_b128 v[194:197], v153 offset:3072
	ds_read_b128 v[198:201], v153 offset:4096
	ds_read_b128 v[202:205], v153 offset:5120
	ds_read_b128 v[206:209], v153 offset:6144
	ds_read_b128 v[210:213], v153 offset:7168
	s_add_u32 s98, s40, 0x80
	s_addc_u32 s99, s41, 0
	s_mov_b32 m0, s55
	s_nop 0
	global_load_lds_dwordx4 v128, s[98:99]
	s_mov_b32 m0, s56
	s_nop 0
	global_load_lds_dwordx4 v132, s[98:99]
	s_add_i32 m0, s50, 0xc000
	s_nop 0
	global_load_lds_dwordx4 v136, s[40:41]
	s_add_i32 m0, s50, 0xe000
	s_nop 0
	global_load_lds_dwordx4 v138, s[40:41]
	s_waitcnt vmcnt(8) lgkmcnt(0)
	s_barrier
	s_setprio 1
	v_mfma_f32_16x16x32_bf16 v[120:123], v[144:147], v[182:185], v[120:123]
	v_mfma_f32_16x16x32_bf16 v[124:127], v[158:161], v[182:185], v[124:127]
	v_mfma_f32_16x16x32_bf16 v[104:107], v[144:147], v[190:193], v[104:107]
	v_mfma_f32_16x16x32_bf16 v[108:111], v[158:161], v[190:193], v[108:111]
	v_mfma_f32_16x16x32_bf16 v[88:91], v[144:147], v[198:201], v[88:91]
	v_mfma_f32_16x16x32_bf16 v[92:95], v[158:161], v[198:201], v[92:95]
	v_mfma_f32_16x16x32_bf16 v[72:75], v[144:147], v[206:209], v[72:75]
	v_mfma_f32_16x16x32_bf16 v[76:79], v[158:161], v[206:209], v[76:79]
	v_mfma_f32_16x16x32_bf16 v[120:123], v[154:157], v[186:189], v[120:123]
	v_mfma_f32_16x16x32_bf16 v[124:127], v[162:165], v[186:189], v[124:127]
	v_mfma_f32_16x16x32_bf16 v[104:107], v[154:157], v[194:197], v[104:107]
	v_mfma_f32_16x16x32_bf16 v[108:111], v[162:165], v[194:197], v[108:111]
	v_mfma_f32_16x16x32_bf16 v[88:91], v[154:157], v[202:205], v[88:91]
	v_mfma_f32_16x16x32_bf16 v[92:95], v[162:165], v[202:205], v[92:95]
	v_mfma_f32_16x16x32_bf16 v[72:75], v[154:157], v[210:213], v[72:75]
	v_mfma_f32_16x16x32_bf16 v[76:79], v[162:165], v[210:213], v[76:79]
	s_setprio 0
	s_setprio 1
	v_mfma_f32_16x16x32_bf16 v[112:115], v[166:169], v[182:185], v[112:115]
	v_mfma_f32_16x16x32_bf16 v[116:119], v[174:177], v[182:185], v[116:119]
	v_mfma_f32_16x16x32_bf16 v[96:99], v[166:169], v[190:193], v[96:99]
	v_mfma_f32_16x16x32_bf16 v[100:103], v[174:177], v[190:193], v[100:103]
	v_mfma_f32_16x16x32_bf16 v[80:83], v[166:169], v[198:201], v[80:83]
	v_mfma_f32_16x16x32_bf16 v[84:87], v[174:177], v[198:201], v[84:87]
	v_mfma_f32_16x16x32_bf16 v[64:67], v[166:169], v[206:209], v[64:67]
	v_mfma_f32_16x16x32_bf16 v[68:71], v[174:177], v[206:209], v[68:71]
	v_mfma_f32_16x16x32_bf16 v[112:115], v[170:173], v[186:189], v[112:115]
	v_mfma_f32_16x16x32_bf16 v[116:119], v[178:181], v[186:189], v[116:119]
	v_mfma_f32_16x16x32_bf16 v[96:99], v[170:173], v[194:197], v[96:99]
	v_mfma_f32_16x16x32_bf16 v[100:103], v[178:181], v[194:197], v[100:103]
	v_mfma_f32_16x16x32_bf16 v[80:83], v[170:173], v[202:205], v[80:83]
	v_mfma_f32_16x16x32_bf16 v[84:87], v[178:181], v[202:205], v[84:87]
	v_mfma_f32_16x16x32_bf16 v[64:67], v[170:173], v[210:213], v[64:67]
	v_mfma_f32_16x16x32_bf16 v[68:71], v[178:181], v[210:213], v[68:71]
	s_setprio 0
	s_barrier
	s_add_i32 s40, s58, s33
	s_mov_b32 m0, s40
	ds_read_b128 v[182:185], v153 offset:16384
	ds_read_b128 v[186:189], v153 offset:17408
	ds_read_b128 v[190:193], v153 offset:18432
	ds_read_b128 v[194:197], v153 offset:19456
	ds_read_b128 v[198:201], v153 offset:20480
	ds_read_b128 v[202:205], v153 offset:21504
	ds_read_b128 v[206:209], v153 offset:22528
	ds_read_b128 v[210:213], v153 offset:23552
	global_load_lds_dwordx4 v130, s[42:43]
	s_add_i32 m0, s40, 0x2000
	s_add_u32 s40, s42, 0x160000
	s_addc_u32 s41, s43, 0
	s_add_i32 s66, s59, s33
	global_load_lds_dwordx4 v134, s[42:43]
	s_mov_b32 m0, s66
	s_nop 0
	global_load_lds_dwordx4 v130, s[40:41]
	s_add_i32 m0, s66, 0x2000
	s_nop 0
	global_load_lds_dwordx4 v134, s[40:41]
	s_waitcnt vmcnt(6) lgkmcnt(0)
	s_barrier
	s_setprio 1
	v_mfma_f32_16x16x32_bf16 v[56:59], v[144:147], v[182:185], v[56:59]
	v_mfma_f32_16x16x32_bf16 v[60:63], v[158:161], v[182:185], v[60:63]
	v_mfma_f32_16x16x32_bf16 v[40:43], v[144:147], v[190:193], v[40:43]
	v_mfma_f32_16x16x32_bf16 v[44:47], v[158:161], v[190:193], v[44:47]
	v_mfma_f32_16x16x32_bf16 v[24:27], v[144:147], v[198:201], v[24:27]
	v_mfma_f32_16x16x32_bf16 v[28:31], v[158:161], v[198:201], v[28:31]
	v_mfma_f32_16x16x32_bf16 v[8:11], v[144:147], v[206:209], v[8:11]
	v_mfma_f32_16x16x32_bf16 v[12:15], v[158:161], v[206:209], v[12:15]
	v_mfma_f32_16x16x32_bf16 v[56:59], v[154:157], v[186:189], v[56:59]
	v_mfma_f32_16x16x32_bf16 v[60:63], v[162:165], v[186:189], v[60:63]
	v_mfma_f32_16x16x32_bf16 v[40:43], v[154:157], v[194:197], v[40:43]
	v_mfma_f32_16x16x32_bf16 v[44:47], v[162:165], v[194:197], v[44:47]
	v_mfma_f32_16x16x32_bf16 v[24:27], v[154:157], v[202:205], v[24:27]
	v_mfma_f32_16x16x32_bf16 v[28:31], v[162:165], v[202:205], v[28:31]
	v_mfma_f32_16x16x32_bf16 v[8:11], v[154:157], v[210:213], v[8:11]
	v_mfma_f32_16x16x32_bf16 v[12:15], v[162:165], v[210:213], v[12:15]
	s_setprio 0
	s_setprio 1
	v_mfma_f32_16x16x32_bf16 v[48:51], v[166:169], v[182:185], v[48:51]
	v_mfma_f32_16x16x32_bf16 v[52:55], v[174:177], v[182:185], v[52:55]
	v_mfma_f32_16x16x32_bf16 v[32:35], v[166:169], v[190:193], v[32:35]
	v_mfma_f32_16x16x32_bf16 v[36:39], v[174:177], v[190:193], v[36:39]
	v_mfma_f32_16x16x32_bf16 v[16:19], v[166:169], v[198:201], v[16:19]
	v_mfma_f32_16x16x32_bf16 v[20:23], v[174:177], v[198:201], v[20:23]
	v_mfma_f32_16x16x32_bf16 v[4:7], v[166:169], v[206:209], v[4:7]
	v_mfma_f32_16x16x32_bf16 v[0:3], v[174:177], v[206:209], v[0:3]
	v_mfma_f32_16x16x32_bf16 v[48:51], v[170:173], v[186:189], v[48:51]
	v_mfma_f32_16x16x32_bf16 v[52:55], v[178:181], v[186:189], v[52:55]
	v_mfma_f32_16x16x32_bf16 v[32:35], v[170:173], v[194:197], v[32:35]
	v_mfma_f32_16x16x32_bf16 v[36:39], v[178:181], v[194:197], v[36:39]
	v_mfma_f32_16x16x32_bf16 v[16:19], v[170:173], v[202:205], v[16:19]
	v_mfma_f32_16x16x32_bf16 v[20:23], v[178:181], v[202:205], v[20:23]
	v_mfma_f32_16x16x32_bf16 v[4:7], v[170:173], v[210:213], v[4:7]
	v_mfma_f32_16x16x32_bf16 v[0:3], v[178:181], v[210:213], v[0:3]
	s_setprio 0
	s_barrier
; #define PG8_STAGE(bufoff, gbase, voff) do { _Pragma("unroll") for (int _i = 0; _i < 2; ++_i) \
;         __builtin_amdgcn_global_load_lds((const unsigned*)((const char*)(gbase) + (voff)[_i]), (PG8_LAS unsigned*)(lds + (bufoff) + ldsw + _i * 8192), 16, 0, 0); } while (0)
; #define PG8_LDA(dst, b, h) do { _Pragma("unroll") for (int m = 0; m < 4; ++m) _Pragma("unroll") for (int k = 0; k < 2; ++k) dst[m][k] = *(const PG8_LAS bf16x8*)(lds + PG8_SA(b, h) + aoff + m * 2048 + k * 1024); } while (0)
; #define PG8_LDB(dst, b, h) do { _Pragma("unroll") for (int n = 0; n < 2; ++n) _Pragma("unroll") for (int k = 0; k < 2; ++k) dst[n][k] = *(const PG8_LAS bf16x8*)(lds + PG8_SB(b, h) + boff + n * 2048 + k * 1024); } while (0)
; #define PG8_MMA(ai, bj, At, Bt) do { __builtin_amdgcn_s_setprio(1); _Pragma("unroll") for (int m = 0; m < 4; ++m) _Pragma("unroll") for (int n = 0; n < 2; ++n) _Pragma("unroll") for (int k = 0; k < 2; ++k) \
;         acc[ai][bj][m][n] = __builtin_amdgcn_mfma_f32_16x16x32_bf16(Bt[n][k], At[m][k], acc[ai][bj][m][n], 0, 0, 0); __builtin_amdgcn_s_setprio(0); } while (0)
; #define PG8_WAIT_V(n) asm volatile("s_waitcnt vmcnt(" #n ")" ::: "memory")
; #define PG8_WAIT_L(n) asm volatile("s_waitcnt lgkmcnt(" #n ")" ::: "memory")
; #define PG8_BAR __builtin_amdgcn_s_barrier()
; #define PG8_SCHED __builtin_amdgcn_sched_barrier(0)
; template <class Epi, class Sched, bool ALIGN_EPI = false, bool SP2 = false>
; __device__ __forceinline__ void gemm_phase(PG8_LAS unsigned char* lds, const Gemm g, const Sched& S, const Epi& E) {
;     ...
;             PG8_LDB(B0, 1, 0); PG8_LDB(B1, 1, 1); PG8_SCHED; PG8_LDA(At, 1, 0); PG8_STAGE(PG8_SA(0, 1), a2 + hstepA, voffA);
;             PG8_WAIT_V(8); PG8_WAIT_L(0); PG8_BAR; PG8_MMA(0, 0, At, B0); PG8_MMA(0, 1, At, B1); PG8_BAR; PG8_SCHED;
;             PG8_LDA(At, 1, 1); PG8_STAGE(PG8_SB(1, 0), b3, voffB); PG8_STAGE(PG8_SB(1, 1), b3 + hstepB, voffB); PG8_STAGE(PG8_SA(1, 0), a3, voffA);
;             PG8_WAIT_V(8); PG8_WAIT_L(0); PG8_BAR; PG8_MMA(1, 0, At, B0); PG8_MMA(1, 1, At, B1); PG8_BAR; PG8_SCHED;
;     ...
;         if constexpr (ALIGN_EPI) { if (wr == 0) PG8_BAR; }
	s_add_i32 s66, 0, 0x18000
	s_add_i32 s67, 0, 0x1c000
	v_add_u32_e32 v162, s66, v150
	v_add_u32_e32 v178, s67, v150
	ds_read_b128 v[144:147], v162
	ds_read_b128 v[154:157], v162 offset:1024
	ds_read_b128 v[158:161], v162 offset:2048
	ds_read_b128 v[162:165], v162 offset:3072
	ds_read_b128 v[166:169], v178
	ds_read_b128 v[170:173], v178 offset:1024
	ds_read_b128 v[174:177], v178 offset:2048
	ds_read_b128 v[178:181], v178 offset:3072
	s_add_u32 s40, s46, 0x160000
	s_addc_u32 s41, s47, 0
	ds_read_b128 v[182:185], v153 offset:32768
	ds_read_b128 v[186:189], v153 offset:33792
	ds_read_b128 v[190:193], v153 offset:34816
	ds_read_b128 v[194:197], v153 offset:35840
	ds_read_b128 v[198:201], v153 offset:36864
	ds_read_b128 v[202:205], v153 offset:37888
	ds_read_b128 v[206:209], v153 offset:38912
	ds_read_b128 v[210:213], v153 offset:39936
	s_mov_b32 m0, s50
	s_nop 0
	global_load_lds_dwordx4 v128, s[46:47]
	s_mov_b32 m0, s51
	s_nop 0
	global_load_lds_dwordx4 v132, s[46:47]
	s_mov_b32 m0, s52
	s_nop 0
	global_load_lds_dwordx4 v128, s[40:41]
	s_mov_b32 m0, s53
	s_nop 0
	global_load_lds_dwordx4 v132, s[40:41]
	s_waitcnt vmcnt(8) lgkmcnt(0)
	s_barrier
	s_setprio 1
	v_mfma_f32_16x16x32_bf16 v[120:123], v[144:147], v[182:185], v[120:123]
	v_mfma_f32_16x16x32_bf16 v[124:127], v[158:161], v[182:185], v[124:127]
	v_mfma_f32_16x16x32_bf16 v[104:107], v[144:147], v[190:193], v[104:107]
	v_mfma_f32_16x16x32_bf16 v[108:111], v[158:161], v[190:193], v[108:111]
	v_mfma_f32_16x16x32_bf16 v[88:91], v[144:147], v[198:201], v[88:91]
	v_mfma_f32_16x16x32_bf16 v[92:95], v[158:161], v[198:201], v[92:95]
	v_mfma_f32_16x16x32_bf16 v[72:75], v[144:147], v[206:209], v[72:75]
	v_mfma_f32_16x16x32_bf16 v[76:79], v[158:161], v[206:209], v[76:79]
	v_mfma_f32_16x16x32_bf16 v[120:123], v[154:157], v[186:189], v[120:123]
	v_mfma_f32_16x16x32_bf16 v[124:127], v[162:165], v[186:189], v[124:127]
	v_mfma_f32_16x16x32_bf16 v[104:107], v[154:157], v[194:197], v[104:107]
	v_mfma_f32_16x16x32_bf16 v[108:111], v[162:165], v[194:197], v[108:111]
	v_mfma_f32_16x16x32_bf16 v[88:91], v[154:157], v[202:205], v[88:91]
	v_mfma_f32_16x16x32_bf16 v[92:95], v[162:165], v[202:205], v[92:95]
	v_mfma_f32_16x16x32_bf16 v[72:75], v[154:157], v[210:213], v[72:75]
	v_mfma_f32_16x16x32_bf16 v[76:79], v[162:165], v[210:213], v[76:79]
	s_setprio 0
	s_setprio 1
	v_mfma_f32_16x16x32_bf16 v[112:115], v[166:169], v[182:185], v[112:115]
	v_mfma_f32_16x16x32_bf16 v[116:119], v[174:177], v[182:185], v[116:119]
	v_mfma_f32_16x16x32_bf16 v[96:99], v[166:169], v[190:193], v[96:99]
	v_mfma_f32_16x16x32_bf16 v[100:103], v[174:177], v[190:193], v[100:103]
	v_mfma_f32_16x16x32_bf16 v[80:83], v[166:169], v[198:201], v[80:83]
	v_mfma_f32_16x16x32_bf16 v[84:87], v[174:177], v[198:201], v[84:87]
	v_mfma_f32_16x16x32_bf16 v[64:67], v[166:169], v[206:209], v[64:67]
	v_mfma_f32_16x16x32_bf16 v[68:71], v[174:177], v[206:209], v[68:71]
	v_mfma_f32_16x16x32_bf16 v[112:115], v[170:173], v[186:189], v[112:115]
	v_mfma_f32_16x16x32_bf16 v[116:119], v[178:181], v[186:189], v[116:119]
	v_mfma_f32_16x16x32_bf16 v[96:99], v[170:173], v[194:197], v[96:99]
	v_mfma_f32_16x16x32_bf16 v[100:103], v[178:181], v[194:197], v[100:103]
	v_mfma_f32_16x16x32_bf16 v[80:83], v[170:173], v[202:205], v[80:83]
	v_mfma_f32_16x16x32_bf16 v[84:87], v[178:181], v[202:205], v[84:87]
	v_mfma_f32_16x16x32_bf16 v[64:67], v[170:173], v[210:213], v[64:67]
	v_mfma_f32_16x16x32_bf16 v[68:71], v[178:181], v[210:213], v[68:71]
	s_setprio 0
	s_barrier
	s_add_i32 s40, s66, s33
	s_add_u32 s98, s42, 0x80
	s_addc_u32 s99, s43, 0
	s_mov_b32 m0, s40
	ds_read_b128 v[182:185], v153 offset:49152
	ds_read_b128 v[186:189], v153 offset:50176
	ds_read_b128 v[190:193], v153 offset:51200
	ds_read_b128 v[194:197], v153 offset:52224
	ds_read_b128 v[198:201], v153 offset:53248
	ds_read_b128 v[202:205], v153 offset:54272
	ds_read_b128 v[206:209], v153 offset:55296
	ds_read_b128 v[210:213], v153 offset:56320
	global_load_lds_dwordx4 v130, s[98:99]
	s_add_i32 m0, s40, 0x2000
	s_add_u32 s40, s42, 0x160080
	s_addc_u32 s41, s43, 0
	s_add_i32 s42, s67, s33
	global_load_lds_dwordx4 v134, s[98:99]
	s_mov_b32 m0, s42
	s_nop 0
	global_load_lds_dwordx4 v130, s[40:41]
	s_add_i32 m0, s42, 0x2000
	s_nop 0
	global_load_lds_dwordx4 v134, s[40:41]
	s_waitcnt vmcnt(6) lgkmcnt(0)
	s_barrier
	s_setprio 1
	v_mfma_f32_16x16x32_bf16 v[56:59], v[144:147], v[182:185], v[56:59]
	v_mfma_f32_16x16x32_bf16 v[60:63], v[158:161], v[182:185], v[60:63]
	v_mfma_f32_16x16x32_bf16 v[40:43], v[144:147], v[190:193], v[40:43]
	v_mfma_f32_16x16x32_bf16 v[44:47], v[158:161], v[190:193], v[44:47]
	v_mfma_f32_16x16x32_bf16 v[24:27], v[144:147], v[198:201], v[24:27]
	v_mfma_f32_16x16x32_bf16 v[28:31], v[158:161], v[198:201], v[28:31]
	v_mfma_f32_16x16x32_bf16 v[8:11], v[144:147], v[206:209], v[8:11]
	v_mfma_f32_16x16x32_bf16 v[12:15], v[158:161], v[206:209], v[12:15]
	v_mfma_f32_16x16x32_bf16 v[56:59], v[154:157], v[186:189], v[56:59]
	v_mfma_f32_16x16x32_bf16 v[60:63], v[162:165], v[186:189], v[60:63]
	v_mfma_f32_16x16x32_bf16 v[40:43], v[154:157], v[194:197], v[40:43]
	v_mfma_f32_16x16x32_bf16 v[44:47], v[162:165], v[194:197], v[44:47]
	v_mfma_f32_16x16x32_bf16 v[24:27], v[154:157], v[202:205], v[24:27]
	v_mfma_f32_16x16x32_bf16 v[28:31], v[162:165], v[202:205], v[28:31]
	v_mfma_f32_16x16x32_bf16 v[8:11], v[154:157], v[210:213], v[8:11]
	v_mfma_f32_16x16x32_bf16 v[12:15], v[162:165], v[210:213], v[12:15]
	s_setprio 0
	s_setprio 1
	v_mfma_f32_16x16x32_bf16 v[48:51], v[166:169], v[182:185], v[48:51]
	v_mfma_f32_16x16x32_bf16 v[52:55], v[174:177], v[182:185], v[52:55]
	v_mfma_f32_16x16x32_bf16 v[32:35], v[166:169], v[190:193], v[32:35]
	v_mfma_f32_16x16x32_bf16 v[36:39], v[174:177], v[190:193], v[36:39]
	v_mfma_f32_16x16x32_bf16 v[16:19], v[166:169], v[198:201], v[16:19]
	v_mfma_f32_16x16x32_bf16 v[20:23], v[174:177], v[198:201], v[20:23]
	v_mfma_f32_16x16x32_bf16 v[4:7], v[166:169], v[206:209], v[4:7]
	v_mfma_f32_16x16x32_bf16 v[0:3], v[174:177], v[206:209], v[0:3]
	v_mfma_f32_16x16x32_bf16 v[48:51], v[170:173], v[186:189], v[48:51]
	v_mfma_f32_16x16x32_bf16 v[52:55], v[178:181], v[186:189], v[52:55]
	v_mfma_f32_16x16x32_bf16 v[32:35], v[170:173], v[194:197], v[32:35]
	v_mfma_f32_16x16x32_bf16 v[36:39], v[178:181], v[194:197], v[36:39]
	v_mfma_f32_16x16x32_bf16 v[16:19], v[170:173], v[202:205], v[16:19]
	v_mfma_f32_16x16x32_bf16 v[20:23], v[178:181], v[202:205], v[20:23]
	v_mfma_f32_16x16x32_bf16 v[4:7], v[170:173], v[210:213], v[4:7]
	v_mfma_f32_16x16x32_bf16 v[0:3], v[178:181], v[210:213], v[0:3]
	s_setprio 0
	s_barrier
	s_add_i32 s65, s65, 2
	s_add_u32 s39, s39, 0x100
	s_addc_u32 s64, s64, 0
	s_cmpk_gt_u32 s65, 0x55
	s_mov_b64 s[40:41], s[4:5]
	s_cbranch_scc0 .LBB0_1912
	s_and_b64 vcc, exec, s[14:15]
	s_cbranch_vccz .LBB0_1915
	s_barrier
